# in-GEMM (SwiGLU) units with a successor: second half of the epilogue (acc v0-63) interleaved with the next unit's first peel MFMA block (writes only v64-127); live-ins/temps renamed to v216-225
# baseline (speedup 1.0000x reference)
.Lov_0:
	v_mul_f32_e32 v151, 0xbfb8aa3b, v124
	v_exp_f32_e32 v151, v151
	v_mul_f32_e32 v154, 0xbfb8aa3b, v125
	v_exp_f32_e32 v154, v154
	v_lshl_or_b32 v142, s65, 7, v146
	v_add_f32_e32 v151, 1.0, v151
	v_rcp_f32_e32 v151, v151
	v_lshl_add_u32 v150, s36, 8, v144
	v_ashrrev_i32_e32 v143, 31, v142
	v_mov_b64_e32 v[140:141], s[22:23]
	v_mul_f32_e32 v124, v124, v151
	v_mul_f32_e32 v120, v120, v124
	v_add_f32_e32 v124, 1.0, v154
	v_mul_f32_e32 v151, 0xbfb8aa3b, v126
	v_rcp_f32_e32 v124, v124
	v_exp_f32_e32 v151, v151
	v_mul_f32_e32 v154, 0xbfb8aa3b, v127
	v_exp_f32_e32 v154, v154
	v_mul_f32_e32 v124, v125, v124
	v_add_f32_e32 v125, 1.0, v151
	v_rcp_f32_e32 v125, v125
	v_add_f32_e32 v151, 1.0, v154
	v_rcp_f32_e32 v151, v151
	v_mul_f32_e32 v121, v121, v124
	v_mul_f32_e32 v124, v126, v125
	v_mul_f32_e32 v125, 0xbfb8aa3b, v116
	v_exp_f32_e32 v125, v125
	v_mul_f32_e32 v122, v122, v124
	v_mul_f32_e32 v124, v127, v151
	v_mul_f32_e32 v123, v123, v124
	v_cvt_pk_bf16_f32 v120, v120, v121
	v_cvt_pk_bf16_f32 v121, v122, v123
	v_add_f32_e32 v122, 1.0, v125
	v_rcp_f32_e32 v122, v122
	v_mul_f32_e32 v123, 0xbfb8aa3b, v117
	v_exp_f32_e32 v123, v123
	v_mad_i64_i32 v[152:153], s[44:45], v150, s64, v[140:141]
	v_lshlrev_b64 v[142:143], 1, v[142:143]
	v_lshl_add_u64 v[152:153], v[152:153], 0, v[142:143]
	v_mul_f32_e32 v116, v116, v122
	global_store_dwordx2 v[152:153], v[120:121], off
	v_mul_f32_e32 v112, v112, v116
	v_add_f32_e32 v116, 1.0, v123
	v_mul_f32_e32 v120, 0xbfb8aa3b, v118
	v_rcp_f32_e32 v116, v116
	v_exp_f32_e32 v120, v120
	v_mul_f32_e32 v121, 0xbfb8aa3b, v119
	v_exp_f32_e32 v121, v121
	v_mul_f32_e32 v116, v117, v116
	v_add_f32_e32 v117, 1.0, v120
	v_rcp_f32_e32 v117, v117
	v_add_f32_e32 v120, 1.0, v121
	v_rcp_f32_e32 v120, v120
	v_mul_f32_e32 v113, v113, v116
	v_mul_f32_e32 v116, v118, v117
	v_mul_f32_e32 v114, v114, v116
	v_mul_f32_e32 v116, v119, v120
	v_cvt_pk_bf16_f32 v112, v112, v113
	v_mul_f32_e32 v115, v115, v116
	v_cvt_pk_bf16_f32 v113, v114, v115
	global_store_dwordx2 v[152:153], v[112:113], off offset:128
	v_mul_f32_e32 v112, 0xbfb8aa3b, v108
	v_exp_f32_e32 v114, v112
	v_mul_f32_e32 v115, 0xbfb8aa3b, v109
	v_exp_f32_e32 v115, v115
	v_or_b32_e32 v112, 16, v150
	v_add_f32_e32 v114, 1.0, v114
	v_rcp_f32_e32 v114, v114
	v_mad_i64_i32 v[112:113], s[44:45], v112, s64, v[140:141]
	v_lshl_add_u64 v[112:113], v[112:113], 0, v[142:143]
	v_mul_f32_e32 v108, v108, v114
	v_mul_f32_e32 v104, v104, v108
	v_add_f32_e32 v108, 1.0, v115
	v_mul_f32_e32 v114, 0xbfb8aa3b, v110
	v_rcp_f32_e32 v108, v108
	v_exp_f32_e32 v114, v114
	v_mul_f32_e32 v115, 0xbfb8aa3b, v111
	v_exp_f32_e32 v115, v115
	v_mul_f32_e32 v108, v109, v108
	v_add_f32_e32 v109, 1.0, v114
	v_rcp_f32_e32 v109, v109
	v_add_f32_e32 v114, 1.0, v115
	v_rcp_f32_e32 v114, v114
	v_mul_f32_e32 v105, v105, v108
	v_mul_f32_e32 v108, v110, v109
	v_mul_f32_e32 v109, 0xbfb8aa3b, v100
	v_exp_f32_e32 v109, v109
	v_mul_f32_e32 v106, v106, v108
	v_mul_f32_e32 v108, v111, v114
	v_mul_f32_e32 v107, v107, v108
	v_cvt_pk_bf16_f32 v104, v104, v105
	v_cvt_pk_bf16_f32 v105, v106, v107
	v_add_f32_e32 v106, 1.0, v109
	v_rcp_f32_e32 v106, v106
	v_mul_f32_e32 v107, 0xbfb8aa3b, v101
	v_exp_f32_e32 v107, v107
	global_store_dwordx2 v[112:113], v[104:105], off
	v_mul_f32_e32 v100, v100, v106
	v_mul_f32_e32 v96, v96, v100
	v_add_f32_e32 v100, 1.0, v107
	v_mul_f32_e32 v104, 0xbfb8aa3b, v102
	v_rcp_f32_e32 v100, v100
	v_exp_f32_e32 v104, v104
	v_mul_f32_e32 v105, 0xbfb8aa3b, v103
	v_exp_f32_e32 v105, v105
	v_mul_f32_e32 v100, v101, v100
	v_add_f32_e32 v101, 1.0, v104
	v_rcp_f32_e32 v101, v101
	v_add_f32_e32 v104, 1.0, v105
	v_rcp_f32_e32 v104, v104
	v_mul_f32_e32 v97, v97, v100
	v_mul_f32_e32 v100, v102, v101
	v_mul_f32_e32 v98, v98, v100
	v_mul_f32_e32 v100, v103, v104
	v_cvt_pk_bf16_f32 v96, v96, v97
	v_mul_f32_e32 v99, v99, v100
	v_cvt_pk_bf16_f32 v97, v98, v99
	global_store_dwordx2 v[112:113], v[96:97], off offset:128
	v_mul_f32_e32 v96, 0xbfb8aa3b, v92
	v_exp_f32_e32 v98, v96
	v_mul_f32_e32 v99, 0xbfb8aa3b, v93
	v_exp_f32_e32 v99, v99
	v_or_b32_e32 v96, 32, v150
	v_add_f32_e32 v98, 1.0, v98
	v_rcp_f32_e32 v98, v98
	v_mad_i64_i32 v[96:97], s[44:45], v96, s64, v[140:141]
	v_lshl_add_u64 v[96:97], v[96:97], 0, v[142:143]
	v_mul_f32_e32 v92, v92, v98
	v_mul_f32_e32 v88, v88, v92
	v_add_f32_e32 v92, 1.0, v99
	v_mul_f32_e32 v98, 0xbfb8aa3b, v94
	v_rcp_f32_e32 v92, v92
	v_exp_f32_e32 v98, v98
	v_mul_f32_e32 v99, 0xbfb8aa3b, v95
	v_exp_f32_e32 v99, v99
	v_mul_f32_e32 v92, v93, v92
	v_add_f32_e32 v93, 1.0, v98
	v_rcp_f32_e32 v93, v93
	v_add_f32_e32 v98, 1.0, v99
	v_rcp_f32_e32 v98, v98
	v_mul_f32_e32 v89, v89, v92
	v_mul_f32_e32 v92, v94, v93
	v_mul_f32_e32 v93, 0xbfb8aa3b, v84
	v_exp_f32_e32 v93, v93
	v_mul_f32_e32 v90, v90, v92
	v_mul_f32_e32 v92, v95, v98
	v_mul_f32_e32 v91, v91, v92
	v_cvt_pk_bf16_f32 v88, v88, v89
	v_cvt_pk_bf16_f32 v89, v90, v91
	v_add_f32_e32 v90, 1.0, v93
	v_rcp_f32_e32 v90, v90
	v_mul_f32_e32 v91, 0xbfb8aa3b, v85
	v_exp_f32_e32 v91, v91
	global_store_dwordx2 v[96:97], v[88:89], off
	v_mul_f32_e32 v84, v84, v90
	v_mul_f32_e32 v80, v80, v84
	v_add_f32_e32 v84, 1.0, v91
	v_mul_f32_e32 v88, 0xbfb8aa3b, v86
	v_rcp_f32_e32 v84, v84
	v_exp_f32_e32 v88, v88
	v_mul_f32_e32 v89, 0xbfb8aa3b, v87
	v_exp_f32_e32 v89, v89
	v_mul_f32_e32 v84, v85, v84
	v_add_f32_e32 v85, 1.0, v88
	v_rcp_f32_e32 v85, v85
	v_add_f32_e32 v88, 1.0, v89
	v_rcp_f32_e32 v88, v88
	v_mul_f32_e32 v81, v81, v84
	v_mul_f32_e32 v84, v86, v85
	v_mul_f32_e32 v82, v82, v84
	v_mul_f32_e32 v84, v87, v88
	v_cvt_pk_bf16_f32 v80, v80, v81
	v_mul_f32_e32 v83, v83, v84
	v_cvt_pk_bf16_f32 v81, v82, v83
	global_store_dwordx2 v[96:97], v[80:81], off offset:128
	v_mul_f32_e32 v80, 0xbfb8aa3b, v76
	v_exp_f32_e32 v82, v80
	v_mul_f32_e32 v83, 0xbfb8aa3b, v77
	v_exp_f32_e32 v83, v83
	v_or_b32_e32 v80, 48, v150
	v_add_f32_e32 v82, 1.0, v82
	v_rcp_f32_e32 v82, v82
	v_mad_i64_i32 v[80:81], s[44:45], v80, s64, v[140:141]
	v_lshl_add_u64 v[80:81], v[80:81], 0, v[142:143]
	v_mul_f32_e32 v76, v76, v82
	v_mul_f32_e32 v72, v72, v76
	v_add_f32_e32 v76, 1.0, v83
	v_mul_f32_e32 v82, 0xbfb8aa3b, v78
	v_rcp_f32_e32 v76, v76
	v_exp_f32_e32 v82, v82
	v_mul_f32_e32 v83, 0xbfb8aa3b, v79
	v_exp_f32_e32 v83, v83
	v_mul_f32_e32 v76, v77, v76
	v_add_f32_e32 v77, 1.0, v82
	v_rcp_f32_e32 v77, v77
	v_add_f32_e32 v82, 1.0, v83
	v_rcp_f32_e32 v82, v82
	v_mul_f32_e32 v73, v73, v76
	v_mul_f32_e32 v76, v78, v77
	v_mul_f32_e32 v77, 0xbfb8aa3b, v68
	v_exp_f32_e32 v77, v77
	v_mul_f32_e32 v74, v74, v76
	v_mul_f32_e32 v76, v79, v82
	v_mul_f32_e32 v75, v75, v76
	v_cvt_pk_bf16_f32 v72, v72, v73
	v_cvt_pk_bf16_f32 v73, v74, v75
	v_add_f32_e32 v74, 1.0, v77
	v_rcp_f32_e32 v74, v74
	v_mul_f32_e32 v75, 0xbfb8aa3b, v69
	v_exp_f32_e32 v75, v75
	global_store_dwordx2 v[80:81], v[72:73], off
	v_mul_f32_e32 v68, v68, v74
	v_mul_f32_e32 v64, v64, v68
	v_add_f32_e32 v68, 1.0, v75
	v_mul_f32_e32 v72, 0xbfb8aa3b, v70
	v_rcp_f32_e32 v68, v68
	v_exp_f32_e32 v72, v72
	v_mul_f32_e32 v73, 0xbfb8aa3b, v71
	v_exp_f32_e32 v73, v73
	v_mul_f32_e32 v68, v69, v68
	v_add_f32_e32 v69, 1.0, v72
	v_rcp_f32_e32 v69, v69
	v_add_f32_e32 v72, 1.0, v73
	v_rcp_f32_e32 v72, v72
	v_mul_f32_e32 v65, v65, v68
	v_mul_f32_e32 v68, v70, v69
	v_mul_f32_e32 v66, v66, v68
	v_mul_f32_e32 v68, v71, v72
	v_cvt_pk_bf16_f32 v64, v64, v65
	v_mul_f32_e32 v67, v67, v68
	v_cvt_pk_bf16_f32 v65, v66, v67
	global_store_dwordx2 v[80:81], v[64:65], off offset:128
	v_mov_b32_e32 v216, v140
	v_mov_b32_e32 v217, v141
	v_mov_b32_e32 v218, v142
	v_mov_b32_e32 v219, v143
	v_mov_b32_e32 v220, v150
	s_andn2_b64 vcc, exec, s[0:1]
	s_cbranch_vccnz .Lov_nb_0
	s_barrier
.Lov_nb_0:
	s_mov_b32 s65, s10
	s_mov_b32 s36, s12
	s_mov_b64 s[46:47], s[30:31]
	s_mov_b64 s[44:45], s[24:25]
	s_add_i32 s59, s59, 1
	s_mul_i32 s4, s59, s21
	s_mul_hi_u32 s5, s59, s20
	s_add_i32 s5, s5, s4
	s_mul_i32 s4, s59, s20
	s_add_u32 s24, s4, s2
	s_addc_u32 s25, s5, s3
	v_cmp_gt_i64_e32 vcc, s[24:25], v[138:139]
	v_cmp_lt_i64_e64 s[4:5], s[24:25], v[136:137]
	s_cbranch_vccnz .LBB0_183_ov0
	s_lshr_b32 s10, s24, 3
	s_and_b32 s12, s24, 7
	s_lshl_b32 s12, s12, 1
	s_cmp_ge_u32 s10, 0xb0
	s_cbranch_scc0 .Ldec_0_ov0
	s_sub_u32 s10, s10, 0xb0
	s_add_u32 s12, s12, 1

.LBB0_183_ov0:
	s_ashr_i32 s13, s12, 31
	s_lshl_b64 s[24:25], s[12:13], 19
	s_add_u32 s24, s80, s24
	s_addc_u32 s25, s81, s25
	s_and_b64 s[30:31], s[4:5], exec
	s_cselect_b32 s13, s25, s45
	s_cselect_b32 s66, s24, s44
	s_ashr_i32 s11, s10, 31
	s_lshl_b64 s[30:31], s[10:11], 19
	s_add_u32 s30, s52, s30
	s_addc_u32 s31, s53, s31
	s_and_b64 s[48:49], s[4:5], exec
	s_cselect_b32 s11, s31, s47
	s_cselect_b32 s67, s30, s46
	s_add_u32 s44, s44, 0x40080
	s_addc_u32 s45, s45, 0
	s_add_u32 s68, s46, 0x100
	s_addc_u32 s69, s47, 0
	s_mov_b32 s70, -2
	ds_read_b128 v[140:143], v147
	ds_read_b128 v[150:153], v147 offset:1024
	ds_read_b128 v[154:157], v147 offset:2048
	ds_read_b128 v[158:161], v147 offset:3072
	ds_read_b128 v[162:165], v148
	ds_read_b128 v[166:169], v148 offset:1024
	ds_read_b128 v[170:173], v148 offset:2048
	ds_read_b128 v[174:177], v148 offset:3072
	s_add_u32 s18, s44, 0xfffc0080
	s_addc_u32 s19, s45, -1
	s_cmp_eq_u32 s70, 12
	s_cselect_b32 s49, s13, s19
	s_cselect_b32 s48, s66, s18
	s_cselect_b32 s47, s11, s69
	s_cselect_b32 s46, s67, s68
	v_lshl_add_u64 v[178:179], s[44:45], 0, v[132:133]
	s_add_i32 m0, s37, 0xc000
	ds_read_b128 v[184:187], v149
	ds_read_b128 v[188:191], v149 offset:1024
	ds_read_b128 v[192:195], v149 offset:2048
	ds_read_b128 v[196:199], v149 offset:3072
	ds_read_b128 v[200:203], v149 offset:4096
	ds_read_b128 v[204:207], v149 offset:5120
	ds_read_b128 v[208:211], v149 offset:6144
	ds_read_b128 v[212:215], v149 offset:7168
	global_load_lds_dwordx4 v[178:179], off
	v_lshl_add_u64 v[178:179], s[44:45], 0, v[134:135]
	s_add_i32 m0, s37, 0xe000
	s_nop 0
	global_load_lds_dwordx4 v[178:179], off
	s_waitcnt vmcnt(8)
	s_waitcnt lgkmcnt(0)
	s_barrier
	s_setprio 1
	s_waitcnt lgkmcnt(0)
	v_mfma_f32_16x16x32_bf16 v[124:127], v[140:143], v[184:187], 0
	v_mul_f32_e32 v222, 0xbfb8aa3b, v60
	v_exp_f32_e32 v224, v222
	v_mul_f32_e32 v225, 0xbfb8aa3b, v61
	v_exp_f32_e32 v225, v225
	v_add_u32_e32 v222, 0x80, v220
	v_add_f32_e32 v224, 1.0, v224
	v_rcp_f32_e32 v224, v224
	v_mad_i64_i32 v[222:223], vcc, v222, s64, v[216:217]
	v_mfma_f32_16x16x32_bf16 v[124:127], v[150:153], v[188:191], v[124:127]
	v_lshl_add_u64 v[222:223], v[222:223], 0, v[218:219]
	v_mul_f32_e32 v60, v60, v224
	v_mul_f32_e32 v56, v56, v60
	v_add_f32_e32 v60, 1.0, v225
	v_mul_f32_e32 v224, 0xbfb8aa3b, v62
	v_rcp_f32_e32 v60, v60
	v_exp_f32_e32 v224, v224
	v_mul_f32_e32 v225, 0xbfb8aa3b, v63
	v_mfma_f32_16x16x32_bf16 v[120:123], v[154:157], v[184:187], 0
	v_exp_f32_e32 v225, v225
	v_mul_f32_e32 v60, v61, v60
	v_add_f32_e32 v61, 1.0, v224
	v_rcp_f32_e32 v61, v61
	v_add_f32_e32 v224, 1.0, v225
	v_rcp_f32_e32 v224, v224
	v_mul_f32_e32 v57, v57, v60
	v_mul_f32_e32 v60, v62, v61
	v_mfma_f32_16x16x32_bf16 v[120:123], v[158:161], v[188:191], v[120:123]
	v_mul_f32_e32 v61, 0xbfb8aa3b, v52
	v_exp_f32_e32 v61, v61
	v_mul_f32_e32 v58, v58, v60
	v_mul_f32_e32 v60, v63, v224
	v_mul_f32_e32 v59, v59, v60
	v_cvt_pk_bf16_f32 v56, v56, v57
	v_cvt_pk_bf16_f32 v57, v58, v59
	v_add_f32_e32 v58, 1.0, v61
	v_mfma_f32_16x16x32_bf16 v[108:111], v[140:143], v[192:195], 0
	v_rcp_f32_e32 v58, v58
	v_mul_f32_e32 v59, 0xbfb8aa3b, v53
	v_exp_f32_e32 v59, v59
	global_store_dwordx2 v[222:223], v[56:57], off
	v_mul_f32_e32 v52, v52, v58
	v_mul_f32_e32 v48, v48, v52
	v_add_f32_e32 v52, 1.0, v59
	v_mul_f32_e32 v56, 0xbfb8aa3b, v54
	v_mfma_f32_16x16x32_bf16 v[108:111], v[150:153], v[196:199], v[108:111]
	v_rcp_f32_e32 v52, v52
	v_exp_f32_e32 v56, v56
	v_mul_f32_e32 v57, 0xbfb8aa3b, v55
	v_exp_f32_e32 v57, v57
	v_mul_f32_e32 v52, v53, v52
	v_add_f32_e32 v53, 1.0, v56
	v_rcp_f32_e32 v53, v53
	v_add_f32_e32 v56, 1.0, v57
	v_mfma_f32_16x16x32_bf16 v[104:107], v[154:157], v[192:195], 0
	v_rcp_f32_e32 v56, v56
	v_mul_f32_e32 v49, v49, v52
	v_mul_f32_e32 v52, v54, v53
	v_mul_f32_e32 v50, v50, v52
	v_mul_f32_e32 v52, v55, v56
	v_cvt_pk_bf16_f32 v48, v48, v49
	v_mul_f32_e32 v51, v51, v52
	v_cvt_pk_bf16_f32 v49, v50, v51
	v_mfma_f32_16x16x32_bf16 v[104:107], v[158:161], v[196:199], v[104:107]
	global_store_dwordx2 v[222:223], v[48:49], off offset:128
	v_mul_f32_e32 v48, 0xbfb8aa3b, v44
	v_exp_f32_e32 v50, v48
	v_mul_f32_e32 v51, 0xbfb8aa3b, v45
	v_exp_f32_e32 v51, v51
	v_add_u32_e32 v48, 0x90, v220
	v_add_f32_e32 v50, 1.0, v50
	v_rcp_f32_e32 v50, v50
	v_mfma_f32_16x16x32_bf16 v[92:95], v[140:143], v[200:203], 0
	v_mad_i64_i32 v[48:49], vcc, v48, s64, v[216:217]
	v_lshl_add_u64 v[48:49], v[48:49], 0, v[218:219]
	v_mul_f32_e32 v44, v44, v50
	v_mul_f32_e32 v40, v40, v44
	v_add_f32_e32 v44, 1.0, v51
	v_mul_f32_e32 v50, 0xbfb8aa3b, v46
	v_rcp_f32_e32 v44, v44
	v_exp_f32_e32 v50, v50
	v_mfma_f32_16x16x32_bf16 v[92:95], v[150:153], v[204:207], v[92:95]
	v_mul_f32_e32 v51, 0xbfb8aa3b, v47
	v_exp_f32_e32 v51, v51
	v_mul_f32_e32 v44, v45, v44
	v_add_f32_e32 v45, 1.0, v50
	v_rcp_f32_e32 v45, v45
	v_add_f32_e32 v50, 1.0, v51
	v_rcp_f32_e32 v50, v50
	v_mul_f32_e32 v41, v41, v44
	v_mfma_f32_16x16x32_bf16 v[88:91], v[154:157], v[200:203], 0
	v_mul_f32_e32 v44, v46, v45
	v_mul_f32_e32 v45, 0xbfb8aa3b, v36
	v_exp_f32_e32 v45, v45
	v_mul_f32_e32 v42, v42, v44
	v_mul_f32_e32 v44, v47, v50
	v_mul_f32_e32 v43, v43, v44
	v_cvt_pk_bf16_f32 v40, v40, v41
	v_cvt_pk_bf16_f32 v41, v42, v43
	v_mfma_f32_16x16x32_bf16 v[88:91], v[158:161], v[204:207], v[88:91]
	v_add_f32_e32 v42, 1.0, v45
	v_rcp_f32_e32 v42, v42
	v_mul_f32_e32 v43, 0xbfb8aa3b, v37
	v_exp_f32_e32 v43, v43
	global_store_dwordx2 v[48:49], v[40:41], off
	v_mul_f32_e32 v36, v36, v42
	v_mul_f32_e32 v32, v32, v36
	v_add_f32_e32 v36, 1.0, v43
	v_mfma_f32_16x16x32_bf16 v[76:79], v[140:143], v[208:211], 0
	v_mul_f32_e32 v40, 0xbfb8aa3b, v38
	v_rcp_f32_e32 v36, v36
	v_exp_f32_e32 v40, v40
	v_mul_f32_e32 v41, 0xbfb8aa3b, v39
	v_exp_f32_e32 v41, v41
	v_mul_f32_e32 v36, v37, v36
	v_add_f32_e32 v37, 1.0, v40
	v_rcp_f32_e32 v37, v37
	v_mfma_f32_16x16x32_bf16 v[76:79], v[150:153], v[212:215], v[76:79]
	v_add_f32_e32 v40, 1.0, v41
	v_rcp_f32_e32 v40, v40
	v_mul_f32_e32 v33, v33, v36
	v_mul_f32_e32 v36, v38, v37
	v_mul_f32_e32 v34, v34, v36
	v_mul_f32_e32 v36, v39, v40
	v_cvt_pk_bf16_f32 v32, v32, v33
	v_mul_f32_e32 v35, v35, v36
	v_mfma_f32_16x16x32_bf16 v[72:75], v[154:157], v[208:211], 0
	v_cvt_pk_bf16_f32 v33, v34, v35
	global_store_dwordx2 v[48:49], v[32:33], off offset:128
	v_mul_f32_e32 v32, 0xbfb8aa3b, v28
	v_exp_f32_e32 v34, v32
	v_mul_f32_e32 v35, 0xbfb8aa3b, v29
	v_exp_f32_e32 v35, v35
	v_add_u32_e32 v32, 0xa0, v220
	v_add_f32_e32 v34, 1.0, v34
	v_mfma_f32_16x16x32_bf16 v[72:75], v[158:161], v[212:215], v[72:75]
	v_rcp_f32_e32 v34, v34
	v_mad_i64_i32 v[32:33], vcc, v32, s64, v[216:217]
	v_lshl_add_u64 v[32:33], v[32:33], 0, v[218:219]
	v_mul_f32_e32 v28, v28, v34
	v_mul_f32_e32 v24, v24, v28
	v_add_f32_e32 v28, 1.0, v35
	v_mul_f32_e32 v34, 0xbfb8aa3b, v30
	v_rcp_f32_e32 v28, v28
	v_mfma_f32_16x16x32_bf16 v[116:119], v[162:165], v[184:187], 0
	v_exp_f32_e32 v34, v34
	v_mul_f32_e32 v35, 0xbfb8aa3b, v31
	v_exp_f32_e32 v35, v35
	v_mul_f32_e32 v28, v29, v28
	v_add_f32_e32 v29, 1.0, v34
	v_rcp_f32_e32 v29, v29
	v_add_f32_e32 v34, 1.0, v35
	v_rcp_f32_e32 v34, v34
	v_mfma_f32_16x16x32_bf16 v[116:119], v[166:169], v[188:191], v[116:119]
	v_mul_f32_e32 v25, v25, v28
	v_mul_f32_e32 v28, v30, v29
	v_mul_f32_e32 v29, 0xbfb8aa3b, v20
	v_exp_f32_e32 v29, v29
	v_mul_f32_e32 v26, v26, v28
	v_mul_f32_e32 v28, v31, v34
	v_mul_f32_e32 v27, v27, v28
	v_cvt_pk_bf16_f32 v24, v24, v25
	v_mfma_f32_16x16x32_bf16 v[112:115], v[170:173], v[184:187], 0
	v_cvt_pk_bf16_f32 v25, v26, v27
	v_add_f32_e32 v26, 1.0, v29
	v_rcp_f32_e32 v26, v26
	v_mul_f32_e32 v27, 0xbfb8aa3b, v21
	v_exp_f32_e32 v27, v27
	global_store_dwordx2 v[32:33], v[24:25], off
	v_mul_f32_e32 v20, v20, v26
	v_mul_f32_e32 v16, v16, v20
	v_mfma_f32_16x16x32_bf16 v[112:115], v[174:177], v[188:191], v[112:115]
	v_add_f32_e32 v20, 1.0, v27
	v_mul_f32_e32 v24, 0xbfb8aa3b, v22
	v_rcp_f32_e32 v20, v20
	v_exp_f32_e32 v24, v24
	v_mul_f32_e32 v25, 0xbfb8aa3b, v23
	v_exp_f32_e32 v25, v25
	v_mul_f32_e32 v20, v21, v20
	v_add_f32_e32 v21, 1.0, v24
	v_mfma_f32_16x16x32_bf16 v[100:103], v[162:165], v[192:195], 0
	v_rcp_f32_e32 v21, v21
	v_add_f32_e32 v24, 1.0, v25
	v_rcp_f32_e32 v24, v24
	v_mul_f32_e32 v17, v17, v20
	v_mul_f32_e32 v20, v22, v21
	v_mul_f32_e32 v18, v18, v20
	v_mul_f32_e32 v20, v23, v24
	v_cvt_pk_bf16_f32 v16, v16, v17
	v_mfma_f32_16x16x32_bf16 v[100:103], v[166:169], v[196:199], v[100:103]
	v_mul_f32_e32 v19, v19, v20
	v_cvt_pk_bf16_f32 v17, v18, v19
	global_store_dwordx2 v[32:33], v[16:17], off offset:128
	v_mul_f32_e32 v16, 0xbfb8aa3b, v12
	v_exp_f32_e32 v18, v16
	v_mul_f32_e32 v19, 0xbfb8aa3b, v13
	v_exp_f32_e32 v19, v19
	v_add_u32_e32 v16, 0xb0, v220
	v_mfma_f32_16x16x32_bf16 v[96:99], v[170:173], v[192:195], 0
	v_add_f32_e32 v18, 1.0, v18
	v_rcp_f32_e32 v18, v18
	v_mad_i64_i32 v[16:17], vcc, v16, s64, v[216:217]
	v_lshl_add_u64 v[16:17], v[16:17], 0, v[218:219]
	v_mul_f32_e32 v12, v12, v18
	v_mul_f32_e32 v8, v8, v12
	v_add_f32_e32 v12, 1.0, v19
	v_mul_f32_e32 v18, 0xbfb8aa3b, v14
	v_mfma_f32_16x16x32_bf16 v[96:99], v[174:177], v[196:199], v[96:99]
	v_rcp_f32_e32 v12, v12
	v_exp_f32_e32 v18, v18
	v_mul_f32_e32 v19, 0xbfb8aa3b, v15
	v_exp_f32_e32 v19, v19
	v_mul_f32_e32 v12, v13, v12
	v_add_f32_e32 v13, 1.0, v18
	v_rcp_f32_e32 v13, v13
	v_add_f32_e32 v18, 1.0, v19
	v_mfma_f32_16x16x32_bf16 v[84:87], v[162:165], v[200:203], 0
	v_rcp_f32_e32 v18, v18
	v_mul_f32_e32 v9, v9, v12
	v_mul_f32_e32 v12, v14, v13
	v_mul_f32_e32 v13, 0xbfb8aa3b, v4
	v_exp_f32_e32 v13, v13
	v_mul_f32_e32 v10, v10, v12
	v_mul_f32_e32 v12, v15, v18
	v_mul_f32_e32 v11, v11, v12
	v_mfma_f32_16x16x32_bf16 v[84:87], v[166:169], v[204:207], v[84:87]
	v_cvt_pk_bf16_f32 v8, v8, v9
	v_cvt_pk_bf16_f32 v9, v10, v11
	v_add_f32_e32 v10, 1.0, v13
	v_rcp_f32_e32 v10, v10
	v_mul_f32_e32 v11, 0xbfb8aa3b, v5
	v_exp_f32_e32 v11, v11
	global_store_dwordx2 v[16:17], v[8:9], off
	v_mul_f32_e32 v4, v4, v10
	v_mfma_f32_16x16x32_bf16 v[80:83], v[170:173], v[200:203], 0
	v_mul_f32_e32 v0, v0, v4
	v_add_f32_e32 v4, 1.0, v11
	v_mul_f32_e32 v8, 0xbfb8aa3b, v6
	v_rcp_f32_e32 v4, v4
	v_exp_f32_e32 v8, v8
	v_mul_f32_e32 v9, 0xbfb8aa3b, v7
	v_exp_f32_e32 v9, v9
	v_mul_f32_e32 v4, v5, v4
	v_mfma_f32_16x16x32_bf16 v[80:83], v[174:177], v[204:207], v[80:83]
	v_add_f32_e32 v5, 1.0, v8
	v_rcp_f32_e32 v5, v5
	v_add_f32_e32 v8, 1.0, v9
	v_rcp_f32_e32 v8, v8
	v_mul_f32_e32 v1, v1, v4
	v_mul_f32_e32 v4, v6, v5
	v_mul_f32_e32 v2, v2, v4
	v_mul_f32_e32 v4, v7, v8
	v_mfma_f32_16x16x32_bf16 v[68:71], v[162:165], v[208:211], 0
	v_mul_f32_e32 v3, v3, v4
	v_cvt_pk_bf16_f32 v0, v0, v1
	v_cvt_pk_bf16_f32 v1, v2, v3
	global_store_dwordx2 v[16:17], v[0:1], off offset:128
	v_mfma_f32_16x16x32_bf16 v[68:71], v[166:169], v[212:215], v[68:71]
	v_mfma_f32_16x16x32_bf16 v[64:67], v[170:173], v[208:211], 0
	v_mfma_f32_16x16x32_bf16 v[64:67], v[174:177], v[212:215], v[64:67]
	s_setprio 0
	s_barrier
	s_add_i32 s18, s62, s54
	v_lshl_add_u64 v[178:179], s[46:47], 0, v[130:131]
	s_mov_b32 m0, s18
	ds_read_b128 v[184:187], v149 offset:16384
	ds_read_b128 v[188:191], v149 offset:17408
	ds_read_b128 v[192:195], v149 offset:18432
	ds_read_b128 v[196:199], v149 offset:19456
	ds_read_b128 v[200:203], v149 offset:20480
	ds_read_b128 v[204:207], v149 offset:21504
	ds_read_b128 v[208:211], v149 offset:22528
	ds_read_b128 v[212:215], v149 offset:23552
	global_load_lds_dwordx4 v[178:179], off
	s_add_i32 m0, s18, 0x2000
	s_add_u32 s72, s46, 0x40000
	v_lshl_add_u64 v[216:217], s[46:47], 0, v[128:129]
	s_addc_u32 s73, s47, 0
	s_add_i32 s18, s63, s54
	global_load_lds_dwordx4 v[216:217], off
	v_lshl_add_u64 v[218:219], s[72:73], 0, v[130:131]
	s_mov_b32 m0, s18
	v_lshl_add_u64 v[220:221], s[48:49], 0, v[128:129]
	global_load_lds_dwordx4 v[218:219], off
	v_lshl_add_u64 v[218:219], s[72:73], 0, v[128:129]
	s_add_i32 m0, s18, 0x2000
	s_nop 0
	global_load_lds_dwordx4 v[218:219], off
	v_lshl_add_u64 v[218:219], s[48:49], 0, v[130:131]
	s_mov_b32 m0, s37
	s_nop 0
	global_load_lds_dwordx4 v[218:219], off
	s_mov_b32 m0, s56
	s_nop 0
	global_load_lds_dwordx4 v[220:221], off
	s_waitcnt vmcnt(8)
	s_waitcnt lgkmcnt(0)
	s_barrier
	s_setprio 1
	s_waitcnt lgkmcnt(0)
	v_mfma_f32_16x16x32_bf16 v[60:63], v[140:143], v[184:187], 0
	v_mfma_f32_16x16x32_bf16 v[60:63], v[150:153], v[188:191], v[60:63]
	v_mfma_f32_16x16x32_bf16 v[56:59], v[154:157], v[184:187], 0
	v_mfma_f32_16x16x32_bf16 v[56:59], v[158:161], v[188:191], v[56:59]
	v_mfma_f32_16x16x32_bf16 v[44:47], v[140:143], v[192:195], 0
	v_mfma_f32_16x16x32_bf16 v[44:47], v[150:153], v[196:199], v[44:47]
	v_mfma_f32_16x16x32_bf16 v[40:43], v[154:157], v[192:195], 0
	v_mfma_f32_16x16x32_bf16 v[40:43], v[158:161], v[196:199], v[40:43]
	v_mfma_f32_16x16x32_bf16 v[28:31], v[140:143], v[200:203], 0
	v_mfma_f32_16x16x32_bf16 v[28:31], v[150:153], v[204:207], v[28:31]
	v_mfma_f32_16x16x32_bf16 v[24:27], v[154:157], v[200:203], 0
	v_mfma_f32_16x16x32_bf16 v[24:27], v[158:161], v[204:207], v[24:27]
	v_mfma_f32_16x16x32_bf16 v[12:15], v[140:143], v[208:211], 0
	v_mfma_f32_16x16x32_bf16 v[12:15], v[150:153], v[212:215], v[12:15]
	v_mfma_f32_16x16x32_bf16 v[8:11], v[154:157], v[208:211], 0
	v_mfma_f32_16x16x32_bf16 v[8:11], v[158:161], v[212:215], v[8:11]
	v_mfma_f32_16x16x32_bf16 v[52:55], v[162:165], v[184:187], 0
	v_mfma_f32_16x16x32_bf16 v[52:55], v[166:169], v[188:191], v[52:55]
	v_mfma_f32_16x16x32_bf16 v[48:51], v[170:173], v[184:187], 0
	v_mfma_f32_16x16x32_bf16 v[48:51], v[174:177], v[188:191], v[48:51]
	v_mfma_f32_16x16x32_bf16 v[36:39], v[162:165], v[192:195], 0
	v_mfma_f32_16x16x32_bf16 v[36:39], v[166:169], v[196:199], v[36:39]
	v_mfma_f32_16x16x32_bf16 v[32:35], v[170:173], v[192:195], 0
	v_mfma_f32_16x16x32_bf16 v[32:35], v[174:177], v[196:199], v[32:35]
	v_mfma_f32_16x16x32_bf16 v[20:23], v[162:165], v[200:203], 0
	v_mfma_f32_16x16x32_bf16 v[20:23], v[166:169], v[204:207], v[20:23]
	v_mfma_f32_16x16x32_bf16 v[16:19], v[170:173], v[200:203], 0
	v_mfma_f32_16x16x32_bf16 v[16:19], v[174:177], v[204:207], v[16:19]
	v_mfma_f32_16x16x32_bf16 v[4:7], v[162:165], v[208:211], 0
	v_mfma_f32_16x16x32_bf16 v[4:7], v[166:169], v[212:215], v[4:7]
	v_mfma_f32_16x16x32_bf16 v[0:3], v[170:173], v[208:211], 0
	v_mfma_f32_16x16x32_bf16 v[0:3], v[174:177], v[212:215], v[0:3]
	s_setprio 0
	s_barrier
	s_branch .Lmid_gemm0

.LBB0_187:
	s_and_b64 vcc, exec, s[4:5]
	s_cbranch_vccnz .Lov_0
	v_mul_f32_e32 v151, 0xbfb8aa3b, v124
	v_exp_f32_e32 v151, v151
	v_mul_f32_e32 v154, 0xbfb8aa3b, v125
	v_exp_f32_e32 v154, v154
	v_lshl_or_b32 v142, s65, 7, v146
	v_add_f32_e32 v151, 1.0, v151
	v_rcp_f32_e32 v151, v151
	v_lshl_add_u32 v150, s36, 8, v144
	v_ashrrev_i32_e32 v143, 31, v142
	v_mov_b64_e32 v[140:141], s[22:23]
	v_mul_f32_e32 v124, v124, v151
	v_mul_f32_e32 v120, v120, v124
	v_add_f32_e32 v124, 1.0, v154
	v_mul_f32_e32 v151, 0xbfb8aa3b, v126
	v_rcp_f32_e32 v124, v124
	v_exp_f32_e32 v151, v151
	v_mul_f32_e32 v154, 0xbfb8aa3b, v127
	v_exp_f32_e32 v154, v154
	v_mul_f32_e32 v124, v125, v124
	v_add_f32_e32 v125, 1.0, v151
	v_rcp_f32_e32 v125, v125
	v_add_f32_e32 v151, 1.0, v154
	v_rcp_f32_e32 v151, v151
	v_mul_f32_e32 v121, v121, v124
	v_mul_f32_e32 v124, v126, v125
	v_mul_f32_e32 v125, 0xbfb8aa3b, v116
	v_exp_f32_e32 v125, v125
	v_mul_f32_e32 v122, v122, v124
	v_mul_f32_e32 v124, v127, v151
	v_mul_f32_e32 v123, v123, v124
	v_cvt_pk_bf16_f32 v120, v120, v121
	v_cvt_pk_bf16_f32 v121, v122, v123
	v_add_f32_e32 v122, 1.0, v125
	v_rcp_f32_e32 v122, v122
	v_mul_f32_e32 v123, 0xbfb8aa3b, v117
	v_exp_f32_e32 v123, v123
	v_mad_i64_i32 v[152:153], s[44:45], v150, s64, v[140:141]
	v_lshlrev_b64 v[142:143], 1, v[142:143]
	v_lshl_add_u64 v[152:153], v[152:153], 0, v[142:143]
	v_mul_f32_e32 v116, v116, v122
	global_store_dwordx2 v[152:153], v[120:121], off
	v_mul_f32_e32 v112, v112, v116
	v_add_f32_e32 v116, 1.0, v123
	v_mul_f32_e32 v120, 0xbfb8aa3b, v118
	v_rcp_f32_e32 v116, v116
	v_exp_f32_e32 v120, v120
	v_mul_f32_e32 v121, 0xbfb8aa3b, v119
	v_exp_f32_e32 v121, v121
	v_mul_f32_e32 v116, v117, v116
	v_add_f32_e32 v117, 1.0, v120
	v_rcp_f32_e32 v117, v117
	v_add_f32_e32 v120, 1.0, v121
	v_rcp_f32_e32 v120, v120
	v_mul_f32_e32 v113, v113, v116
	v_mul_f32_e32 v116, v118, v117
	v_mul_f32_e32 v114, v114, v116
	v_mul_f32_e32 v116, v119, v120
	v_cvt_pk_bf16_f32 v112, v112, v113
	v_mul_f32_e32 v115, v115, v116
	v_cvt_pk_bf16_f32 v113, v114, v115
	global_store_dwordx2 v[152:153], v[112:113], off offset:128
	v_mul_f32_e32 v112, 0xbfb8aa3b, v108
	v_exp_f32_e32 v114, v112
	v_mul_f32_e32 v115, 0xbfb8aa3b, v109
	v_exp_f32_e32 v115, v115
	v_or_b32_e32 v112, 16, v150
	v_add_f32_e32 v114, 1.0, v114
	v_rcp_f32_e32 v114, v114
	v_mad_i64_i32 v[112:113], s[44:45], v112, s64, v[140:141]
	v_lshl_add_u64 v[112:113], v[112:113], 0, v[142:143]
	v_mul_f32_e32 v108, v108, v114
	v_mul_f32_e32 v104, v104, v108
	v_add_f32_e32 v108, 1.0, v115
	v_mul_f32_e32 v114, 0xbfb8aa3b, v110
	v_rcp_f32_e32 v108, v108
	v_exp_f32_e32 v114, v114
	v_mul_f32_e32 v115, 0xbfb8aa3b, v111
	v_exp_f32_e32 v115, v115
	v_mul_f32_e32 v108, v109, v108
	v_add_f32_e32 v109, 1.0, v114
	v_rcp_f32_e32 v109, v109
	v_add_f32_e32 v114, 1.0, v115
	v_rcp_f32_e32 v114, v114
	v_mul_f32_e32 v105, v105, v108
	v_mul_f32_e32 v108, v110, v109
	v_mul_f32_e32 v109, 0xbfb8aa3b, v100
	v_exp_f32_e32 v109, v109
	v_mul_f32_e32 v106, v106, v108
	v_mul_f32_e32 v108, v111, v114
	v_mul_f32_e32 v107, v107, v108
	v_cvt_pk_bf16_f32 v104, v104, v105
	v_cvt_pk_bf16_f32 v105, v106, v107
	v_add_f32_e32 v106, 1.0, v109
	v_rcp_f32_e32 v106, v106
	v_mul_f32_e32 v107, 0xbfb8aa3b, v101
	v_exp_f32_e32 v107, v107
	global_store_dwordx2 v[112:113], v[104:105], off
	v_mul_f32_e32 v100, v100, v106
	v_mul_f32_e32 v96, v96, v100
	v_add_f32_e32 v100, 1.0, v107
	v_mul_f32_e32 v104, 0xbfb8aa3b, v102
	v_rcp_f32_e32 v100, v100
	v_exp_f32_e32 v104, v104
	v_mul_f32_e32 v105, 0xbfb8aa3b, v103
	v_exp_f32_e32 v105, v105
	v_mul_f32_e32 v100, v101, v100
	v_add_f32_e32 v101, 1.0, v104
	v_rcp_f32_e32 v101, v101
	v_add_f32_e32 v104, 1.0, v105
	v_rcp_f32_e32 v104, v104
	v_mul_f32_e32 v97, v97, v100
	v_mul_f32_e32 v100, v102, v101
	v_mul_f32_e32 v98, v98, v100
	v_mul_f32_e32 v100, v103, v104
	v_cvt_pk_bf16_f32 v96, v96, v97
	v_mul_f32_e32 v99, v99, v100
	v_cvt_pk_bf16_f32 v97, v98, v99
	global_store_dwordx2 v[112:113], v[96:97], off offset:128
	v_mul_f32_e32 v96, 0xbfb8aa3b, v92
	v_exp_f32_e32 v98, v96
	v_mul_f32_e32 v99, 0xbfb8aa3b, v93
	v_exp_f32_e32 v99, v99
	v_or_b32_e32 v96, 32, v150
	v_add_f32_e32 v98, 1.0, v98
	v_rcp_f32_e32 v98, v98
	v_mad_i64_i32 v[96:97], s[44:45], v96, s64, v[140:141]
	v_lshl_add_u64 v[96:97], v[96:97], 0, v[142:143]
	v_mul_f32_e32 v92, v92, v98
	v_mul_f32_e32 v88, v88, v92
	v_add_f32_e32 v92, 1.0, v99
	v_mul_f32_e32 v98, 0xbfb8aa3b, v94
	v_rcp_f32_e32 v92, v92
	v_exp_f32_e32 v98, v98
	v_mul_f32_e32 v99, 0xbfb8aa3b, v95
	v_exp_f32_e32 v99, v99
	v_mul_f32_e32 v92, v93, v92
	v_add_f32_e32 v93, 1.0, v98
	v_rcp_f32_e32 v93, v93
	v_add_f32_e32 v98, 1.0, v99
	v_rcp_f32_e32 v98, v98
	v_mul_f32_e32 v89, v89, v92
	v_mul_f32_e32 v92, v94, v93
	v_mul_f32_e32 v93, 0xbfb8aa3b, v84
	v_exp_f32_e32 v93, v93
	v_mul_f32_e32 v90, v90, v92
	v_mul_f32_e32 v92, v95, v98
	v_mul_f32_e32 v91, v91, v92
	v_cvt_pk_bf16_f32 v88, v88, v89
	v_cvt_pk_bf16_f32 v89, v90, v91
	v_add_f32_e32 v90, 1.0, v93
	v_rcp_f32_e32 v90, v90
	v_mul_f32_e32 v91, 0xbfb8aa3b, v85
	v_exp_f32_e32 v91, v91
	global_store_dwordx2 v[96:97], v[88:89], off
	v_mul_f32_e32 v84, v84, v90
	v_mul_f32_e32 v80, v80, v84
	v_add_f32_e32 v84, 1.0, v91
	v_mul_f32_e32 v88, 0xbfb8aa3b, v86
	v_rcp_f32_e32 v84, v84
	v_exp_f32_e32 v88, v88
	v_mul_f32_e32 v89, 0xbfb8aa3b, v87
	v_exp_f32_e32 v89, v89
	v_mul_f32_e32 v84, v85, v84
	v_add_f32_e32 v85, 1.0, v88
	v_rcp_f32_e32 v85, v85
	v_add_f32_e32 v88, 1.0, v89
	v_rcp_f32_e32 v88, v88
	v_mul_f32_e32 v81, v81, v84
	v_mul_f32_e32 v84, v86, v85
	v_mul_f32_e32 v82, v82, v84
	v_mul_f32_e32 v84, v87, v88
	v_cvt_pk_bf16_f32 v80, v80, v81
	v_mul_f32_e32 v83, v83, v84
	v_cvt_pk_bf16_f32 v81, v82, v83
	global_store_dwordx2 v[96:97], v[80:81], off offset:128
	v_mul_f32_e32 v80, 0xbfb8aa3b, v76
	v_exp_f32_e32 v82, v80
	v_mul_f32_e32 v83, 0xbfb8aa3b, v77
	v_exp_f32_e32 v83, v83
	v_or_b32_e32 v80, 48, v150
	v_add_f32_e32 v82, 1.0, v82
	v_rcp_f32_e32 v82, v82
	v_mad_i64_i32 v[80:81], s[44:45], v80, s64, v[140:141]
	v_lshl_add_u64 v[80:81], v[80:81], 0, v[142:143]
	v_mul_f32_e32 v76, v76, v82
	v_mul_f32_e32 v72, v72, v76
	v_add_f32_e32 v76, 1.0, v83
	v_mul_f32_e32 v82, 0xbfb8aa3b, v78
	v_rcp_f32_e32 v76, v76
	v_exp_f32_e32 v82, v82
	v_mul_f32_e32 v83, 0xbfb8aa3b, v79
	v_exp_f32_e32 v83, v83
	v_mul_f32_e32 v76, v77, v76
	v_add_f32_e32 v77, 1.0, v82
	v_rcp_f32_e32 v77, v77
	v_add_f32_e32 v82, 1.0, v83
	v_rcp_f32_e32 v82, v82
	v_mul_f32_e32 v73, v73, v76
	v_mul_f32_e32 v76, v78, v77
	v_mul_f32_e32 v77, 0xbfb8aa3b, v68
	v_exp_f32_e32 v77, v77
	v_mul_f32_e32 v74, v74, v76
	v_mul_f32_e32 v76, v79, v82
	v_mul_f32_e32 v75, v75, v76
	v_cvt_pk_bf16_f32 v72, v72, v73
	v_cvt_pk_bf16_f32 v73, v74, v75
	v_add_f32_e32 v74, 1.0, v77
	v_rcp_f32_e32 v74, v74
	v_mul_f32_e32 v75, 0xbfb8aa3b, v69
	v_exp_f32_e32 v75, v75
	global_store_dwordx2 v[80:81], v[72:73], off
	v_mul_f32_e32 v68, v68, v74
	v_mul_f32_e32 v64, v64, v68
	v_add_f32_e32 v68, 1.0, v75
	v_mul_f32_e32 v72, 0xbfb8aa3b, v70
	v_rcp_f32_e32 v68, v68
	v_exp_f32_e32 v72, v72
	v_mul_f32_e32 v73, 0xbfb8aa3b, v71
	v_exp_f32_e32 v73, v73
	v_mul_f32_e32 v68, v69, v68
	v_add_f32_e32 v69, 1.0, v72
	v_rcp_f32_e32 v69, v69
	v_add_f32_e32 v72, 1.0, v73
	v_rcp_f32_e32 v72, v72
	v_mul_f32_e32 v65, v65, v68
	v_mul_f32_e32 v68, v70, v69
	v_mul_f32_e32 v66, v66, v68
	v_mul_f32_e32 v68, v71, v72
	v_cvt_pk_bf16_f32 v64, v64, v65
	v_mul_f32_e32 v67, v67, v68
	v_cvt_pk_bf16_f32 v65, v66, v67
	global_store_dwordx2 v[80:81], v[64:65], off offset:128
	v_mul_f32_e32 v64, 0xbfb8aa3b, v60
	v_exp_f32_e32 v66, v64
	v_mul_f32_e32 v67, 0xbfb8aa3b, v61
	v_exp_f32_e32 v67, v67
	v_add_u32_e32 v64, 0x80, v150
	v_add_f32_e32 v66, 1.0, v66
	v_rcp_f32_e32 v66, v66
	v_mad_i64_i32 v[64:65], s[44:45], v64, s64, v[140:141]
	v_lshl_add_u64 v[64:65], v[64:65], 0, v[142:143]
	v_mul_f32_e32 v60, v60, v66
	v_mul_f32_e32 v56, v56, v60
	v_add_f32_e32 v60, 1.0, v67
	v_mul_f32_e32 v66, 0xbfb8aa3b, v62
	v_rcp_f32_e32 v60, v60
	v_exp_f32_e32 v66, v66
	v_mul_f32_e32 v67, 0xbfb8aa3b, v63
	v_exp_f32_e32 v67, v67
	v_mul_f32_e32 v60, v61, v60
	v_add_f32_e32 v61, 1.0, v66
	v_rcp_f32_e32 v61, v61
	v_add_f32_e32 v66, 1.0, v67
	v_rcp_f32_e32 v66, v66
	v_mul_f32_e32 v57, v57, v60
	v_mul_f32_e32 v60, v62, v61
	v_mul_f32_e32 v61, 0xbfb8aa3b, v52
	v_exp_f32_e32 v61, v61
	v_mul_f32_e32 v58, v58, v60
	v_mul_f32_e32 v60, v63, v66
	v_mul_f32_e32 v59, v59, v60
	v_cvt_pk_bf16_f32 v56, v56, v57
	v_cvt_pk_bf16_f32 v57, v58, v59
	v_add_f32_e32 v58, 1.0, v61
	v_rcp_f32_e32 v58, v58
	v_mul_f32_e32 v59, 0xbfb8aa3b, v53
	v_exp_f32_e32 v59, v59
	global_store_dwordx2 v[64:65], v[56:57], off
	v_mul_f32_e32 v52, v52, v58
	v_mul_f32_e32 v48, v48, v52
	v_add_f32_e32 v52, 1.0, v59
	v_mul_f32_e32 v56, 0xbfb8aa3b, v54
	v_rcp_f32_e32 v52, v52
	v_exp_f32_e32 v56, v56
	v_mul_f32_e32 v57, 0xbfb8aa3b, v55
	v_exp_f32_e32 v57, v57
	v_mul_f32_e32 v52, v53, v52
	v_add_f32_e32 v53, 1.0, v56
	v_rcp_f32_e32 v53, v53
	v_add_f32_e32 v56, 1.0, v57
	v_rcp_f32_e32 v56, v56
	v_mul_f32_e32 v49, v49, v52
	v_mul_f32_e32 v52, v54, v53
	v_mul_f32_e32 v50, v50, v52
	v_mul_f32_e32 v52, v55, v56
	v_cvt_pk_bf16_f32 v48, v48, v49
	v_mul_f32_e32 v51, v51, v52
	v_cvt_pk_bf16_f32 v49, v50, v51
	global_store_dwordx2 v[64:65], v[48:49], off offset:128
	v_mul_f32_e32 v48, 0xbfb8aa3b, v44
	v_exp_f32_e32 v50, v48
	v_mul_f32_e32 v51, 0xbfb8aa3b, v45
	v_exp_f32_e32 v51, v51
	v_add_u32_e32 v48, 0x90, v150
	v_add_f32_e32 v50, 1.0, v50
	v_rcp_f32_e32 v50, v50
	v_mad_i64_i32 v[48:49], s[44:45], v48, s64, v[140:141]
	v_lshl_add_u64 v[48:49], v[48:49], 0, v[142:143]
	v_mul_f32_e32 v44, v44, v50
	v_mul_f32_e32 v40, v40, v44
	v_add_f32_e32 v44, 1.0, v51
	v_mul_f32_e32 v50, 0xbfb8aa3b, v46
	v_rcp_f32_e32 v44, v44
	v_exp_f32_e32 v50, v50
	v_mul_f32_e32 v51, 0xbfb8aa3b, v47
	v_exp_f32_e32 v51, v51
	v_mul_f32_e32 v44, v45, v44
	v_add_f32_e32 v45, 1.0, v50
	v_rcp_f32_e32 v45, v45
	v_add_f32_e32 v50, 1.0, v51
	v_rcp_f32_e32 v50, v50
	v_mul_f32_e32 v41, v41, v44
	v_mul_f32_e32 v44, v46, v45
	v_mul_f32_e32 v45, 0xbfb8aa3b, v36
	v_exp_f32_e32 v45, v45
	v_mul_f32_e32 v42, v42, v44
	v_mul_f32_e32 v44, v47, v50
	v_mul_f32_e32 v43, v43, v44
	v_cvt_pk_bf16_f32 v40, v40, v41
	v_cvt_pk_bf16_f32 v41, v42, v43
	v_add_f32_e32 v42, 1.0, v45
	v_rcp_f32_e32 v42, v42
	v_mul_f32_e32 v43, 0xbfb8aa3b, v37
	v_exp_f32_e32 v43, v43
	global_store_dwordx2 v[48:49], v[40:41], off
	v_mul_f32_e32 v36, v36, v42
	v_mul_f32_e32 v32, v32, v36
	v_add_f32_e32 v36, 1.0, v43
	v_mul_f32_e32 v40, 0xbfb8aa3b, v38
	v_rcp_f32_e32 v36, v36
	v_exp_f32_e32 v40, v40
	v_mul_f32_e32 v41, 0xbfb8aa3b, v39
	v_exp_f32_e32 v41, v41
	v_mul_f32_e32 v36, v37, v36
	v_add_f32_e32 v37, 1.0, v40
	v_rcp_f32_e32 v37, v37
	v_add_f32_e32 v40, 1.0, v41
	v_rcp_f32_e32 v40, v40
	v_mul_f32_e32 v33, v33, v36
	v_mul_f32_e32 v36, v38, v37
	v_mul_f32_e32 v34, v34, v36
	v_mul_f32_e32 v36, v39, v40
	v_cvt_pk_bf16_f32 v32, v32, v33
	v_mul_f32_e32 v35, v35, v36
	v_cvt_pk_bf16_f32 v33, v34, v35
	global_store_dwordx2 v[48:49], v[32:33], off offset:128
	v_mul_f32_e32 v32, 0xbfb8aa3b, v28
	v_exp_f32_e32 v34, v32
	v_mul_f32_e32 v35, 0xbfb8aa3b, v29
	v_exp_f32_e32 v35, v35
	v_add_u32_e32 v32, 0xa0, v150
	v_add_f32_e32 v34, 1.0, v34
	v_rcp_f32_e32 v34, v34
	v_mad_i64_i32 v[32:33], s[44:45], v32, s64, v[140:141]
	v_lshl_add_u64 v[32:33], v[32:33], 0, v[142:143]
	v_mul_f32_e32 v28, v28, v34
	v_mul_f32_e32 v24, v24, v28
	v_add_f32_e32 v28, 1.0, v35
	v_mul_f32_e32 v34, 0xbfb8aa3b, v30
	v_rcp_f32_e32 v28, v28
	v_exp_f32_e32 v34, v34
	v_mul_f32_e32 v35, 0xbfb8aa3b, v31
	v_exp_f32_e32 v35, v35
	v_mul_f32_e32 v28, v29, v28
	v_add_f32_e32 v29, 1.0, v34
	v_rcp_f32_e32 v29, v29
	v_add_f32_e32 v34, 1.0, v35
	v_rcp_f32_e32 v34, v34
	v_mul_f32_e32 v25, v25, v28
	v_mul_f32_e32 v28, v30, v29
	v_mul_f32_e32 v29, 0xbfb8aa3b, v20
	v_exp_f32_e32 v29, v29
	v_mul_f32_e32 v26, v26, v28
	v_mul_f32_e32 v28, v31, v34
	v_mul_f32_e32 v27, v27, v28
	v_cvt_pk_bf16_f32 v24, v24, v25
	v_cvt_pk_bf16_f32 v25, v26, v27
	v_add_f32_e32 v26, 1.0, v29
	v_rcp_f32_e32 v26, v26
	v_mul_f32_e32 v27, 0xbfb8aa3b, v21
	v_exp_f32_e32 v27, v27
	global_store_dwordx2 v[32:33], v[24:25], off
	v_mul_f32_e32 v20, v20, v26
	v_mul_f32_e32 v16, v16, v20
	v_add_f32_e32 v20, 1.0, v27
	v_mul_f32_e32 v24, 0xbfb8aa3b, v22
	v_rcp_f32_e32 v20, v20
	v_exp_f32_e32 v24, v24
	v_mul_f32_e32 v25, 0xbfb8aa3b, v23
	v_exp_f32_e32 v25, v25
	v_mul_f32_e32 v20, v21, v20
	v_add_f32_e32 v21, 1.0, v24
	v_rcp_f32_e32 v21, v21
	v_add_f32_e32 v24, 1.0, v25
	v_rcp_f32_e32 v24, v24
	v_mul_f32_e32 v17, v17, v20
	v_mul_f32_e32 v20, v22, v21
	v_mul_f32_e32 v18, v18, v20
	v_mul_f32_e32 v20, v23, v24
	v_cvt_pk_bf16_f32 v16, v16, v17
	v_mul_f32_e32 v19, v19, v20
	v_cvt_pk_bf16_f32 v17, v18, v19
	global_store_dwordx2 v[32:33], v[16:17], off offset:128
	v_mul_f32_e32 v16, 0xbfb8aa3b, v12
	v_exp_f32_e32 v18, v16
	v_mul_f32_e32 v19, 0xbfb8aa3b, v13
	v_exp_f32_e32 v19, v19
	v_add_u32_e32 v16, 0xb0, v150
	v_add_f32_e32 v18, 1.0, v18
	v_rcp_f32_e32 v18, v18
	v_mad_i64_i32 v[16:17], s[44:45], v16, s64, v[140:141]
	v_lshl_add_u64 v[16:17], v[16:17], 0, v[142:143]
	v_mul_f32_e32 v12, v12, v18
	v_mul_f32_e32 v8, v8, v12
	v_add_f32_e32 v12, 1.0, v19
	v_mul_f32_e32 v18, 0xbfb8aa3b, v14
	v_rcp_f32_e32 v12, v12
	v_exp_f32_e32 v18, v18
	v_mul_f32_e32 v19, 0xbfb8aa3b, v15
	v_exp_f32_e32 v19, v19
	v_mul_f32_e32 v12, v13, v12
	v_add_f32_e32 v13, 1.0, v18
	v_rcp_f32_e32 v13, v13
	v_add_f32_e32 v18, 1.0, v19
	v_rcp_f32_e32 v18, v18
	v_mul_f32_e32 v9, v9, v12
	v_mul_f32_e32 v12, v14, v13
	v_mul_f32_e32 v13, 0xbfb8aa3b, v4
	v_exp_f32_e32 v13, v13
	v_mul_f32_e32 v10, v10, v12
	v_mul_f32_e32 v12, v15, v18
	v_mul_f32_e32 v11, v11, v12
	v_cvt_pk_bf16_f32 v8, v8, v9
	v_cvt_pk_bf16_f32 v9, v10, v11
	v_add_f32_e32 v10, 1.0, v13
	v_rcp_f32_e32 v10, v10
	v_mul_f32_e32 v11, 0xbfb8aa3b, v5
	v_exp_f32_e32 v11, v11
	global_store_dwordx2 v[16:17], v[8:9], off
	v_mul_f32_e32 v4, v4, v10
	v_mul_f32_e32 v0, v0, v4
	v_add_f32_e32 v4, 1.0, v11
	v_mul_f32_e32 v8, 0xbfb8aa3b, v6
	v_rcp_f32_e32 v4, v4
	v_exp_f32_e32 v8, v8
	v_mul_f32_e32 v9, 0xbfb8aa3b, v7
	v_exp_f32_e32 v9, v9
	v_mul_f32_e32 v4, v5, v4
	v_add_f32_e32 v5, 1.0, v8
	v_rcp_f32_e32 v5, v5
	v_add_f32_e32 v8, 1.0, v9
	v_rcp_f32_e32 v8, v8
	v_mul_f32_e32 v1, v1, v4
	v_mul_f32_e32 v4, v6, v5
	v_mul_f32_e32 v2, v2, v4
	v_mul_f32_e32 v4, v7, v8
	s_andn2_b64 vcc, exec, s[4:5]
	s_mov_b64 s[4:5], -1
	v_mul_f32_e32 v3, v3, v4
	v_cvt_pk_bf16_f32 v0, v0, v1
	v_cvt_pk_bf16_f32 v1, v2, v3
	global_store_dwordx2 v[16:17], v[0:1], off offset:128
	s_cbranch_vccnz .LBB0_180
	s_andn2_b64 vcc, exec, s[0:1]
	s_cbranch_vccnz .LBB0_179
	s_barrier
	s_branch .LBB0_179

.Lov_4:
	v_mul_f32_e32 v151, 0xbfb8aa3b, v124
	v_exp_f32_e32 v151, v151
	v_mul_f32_e32 v154, 0xbfb8aa3b, v125
	v_exp_f32_e32 v154, v154
	v_lshl_or_b32 v142, s69, 7, v146
	v_add_f32_e32 v151, 1.0, v151
	v_rcp_f32_e32 v151, v151
	v_lshl_add_u32 v150, s46, 8, v144
	v_ashrrev_i32_e32 v143, 31, v142
	v_mov_b64_e32 v[140:141], s[22:23]
	v_mul_f32_e32 v124, v124, v151
	v_mul_f32_e32 v120, v120, v124
	v_add_f32_e32 v124, 1.0, v154
	v_mul_f32_e32 v151, 0xbfb8aa3b, v126
	v_rcp_f32_e32 v124, v124
	v_exp_f32_e32 v151, v151
	v_mul_f32_e32 v154, 0xbfb8aa3b, v127
	v_exp_f32_e32 v154, v154
	v_mul_f32_e32 v124, v125, v124
	v_add_f32_e32 v125, 1.0, v151
	v_rcp_f32_e32 v125, v125
	v_add_f32_e32 v151, 1.0, v154
	v_rcp_f32_e32 v151, v151
	v_mul_f32_e32 v121, v121, v124
	v_mul_f32_e32 v124, v126, v125
	v_mul_f32_e32 v125, 0xbfb8aa3b, v116
	v_exp_f32_e32 v125, v125
	v_mul_f32_e32 v122, v122, v124
	v_mul_f32_e32 v124, v127, v151
	v_mul_f32_e32 v123, v123, v124
	v_cvt_pk_bf16_f32 v120, v120, v121
	v_cvt_pk_bf16_f32 v121, v122, v123
	v_add_f32_e32 v122, 1.0, v125
	v_rcp_f32_e32 v122, v122
	v_mul_f32_e32 v123, 0xbfb8aa3b, v117
	v_exp_f32_e32 v123, v123
	v_mad_i64_i32 v[152:153], s[48:49], v150, s68, v[140:141]
	v_lshlrev_b64 v[142:143], 1, v[142:143]
	v_lshl_add_u64 v[152:153], v[152:153], 0, v[142:143]
	v_mul_f32_e32 v116, v116, v122
	global_store_dwordx2 v[152:153], v[120:121], off
	v_mul_f32_e32 v112, v112, v116
	v_add_f32_e32 v116, 1.0, v123
	v_mul_f32_e32 v120, 0xbfb8aa3b, v118
	v_rcp_f32_e32 v116, v116
	v_exp_f32_e32 v120, v120
	v_mul_f32_e32 v121, 0xbfb8aa3b, v119
	v_exp_f32_e32 v121, v121
	v_mul_f32_e32 v116, v117, v116
	v_add_f32_e32 v117, 1.0, v120
	v_rcp_f32_e32 v117, v117
	v_add_f32_e32 v120, 1.0, v121
	v_rcp_f32_e32 v120, v120
	v_mul_f32_e32 v113, v113, v116
	v_mul_f32_e32 v116, v118, v117
	v_mul_f32_e32 v114, v114, v116
	v_mul_f32_e32 v116, v119, v120
	v_cvt_pk_bf16_f32 v112, v112, v113
	v_mul_f32_e32 v115, v115, v116
	v_cvt_pk_bf16_f32 v113, v114, v115
	global_store_dwordx2 v[152:153], v[112:113], off offset:128
	v_mul_f32_e32 v112, 0xbfb8aa3b, v108
	v_exp_f32_e32 v114, v112
	v_mul_f32_e32 v115, 0xbfb8aa3b, v109
	v_exp_f32_e32 v115, v115
	v_or_b32_e32 v112, 16, v150
	v_add_f32_e32 v114, 1.0, v114
	v_rcp_f32_e32 v114, v114
	v_mad_i64_i32 v[112:113], s[48:49], v112, s68, v[140:141]
	v_lshl_add_u64 v[112:113], v[112:113], 0, v[142:143]
	v_mul_f32_e32 v108, v108, v114
	v_mul_f32_e32 v104, v104, v108
	v_add_f32_e32 v108, 1.0, v115
	v_mul_f32_e32 v114, 0xbfb8aa3b, v110
	v_rcp_f32_e32 v108, v108
	v_exp_f32_e32 v114, v114
	v_mul_f32_e32 v115, 0xbfb8aa3b, v111
	v_exp_f32_e32 v115, v115
	v_mul_f32_e32 v108, v109, v108
	v_add_f32_e32 v109, 1.0, v114
	v_rcp_f32_e32 v109, v109
	v_add_f32_e32 v114, 1.0, v115
	v_rcp_f32_e32 v114, v114
	v_mul_f32_e32 v105, v105, v108
	v_mul_f32_e32 v108, v110, v109
	v_mul_f32_e32 v109, 0xbfb8aa3b, v100
	v_exp_f32_e32 v109, v109
	v_mul_f32_e32 v106, v106, v108
	v_mul_f32_e32 v108, v111, v114
	v_mul_f32_e32 v107, v107, v108
	v_cvt_pk_bf16_f32 v104, v104, v105
	v_cvt_pk_bf16_f32 v105, v106, v107
	v_add_f32_e32 v106, 1.0, v109
	v_rcp_f32_e32 v106, v106
	v_mul_f32_e32 v107, 0xbfb8aa3b, v101
	v_exp_f32_e32 v107, v107
	global_store_dwordx2 v[112:113], v[104:105], off
	v_mul_f32_e32 v100, v100, v106
	v_mul_f32_e32 v96, v96, v100
	v_add_f32_e32 v100, 1.0, v107
	v_mul_f32_e32 v104, 0xbfb8aa3b, v102
	v_rcp_f32_e32 v100, v100
	v_exp_f32_e32 v104, v104
	v_mul_f32_e32 v105, 0xbfb8aa3b, v103
	v_exp_f32_e32 v105, v105
	v_mul_f32_e32 v100, v101, v100
	v_add_f32_e32 v101, 1.0, v104
	v_rcp_f32_e32 v101, v101
	v_add_f32_e32 v104, 1.0, v105
	v_rcp_f32_e32 v104, v104
	v_mul_f32_e32 v97, v97, v100
	v_mul_f32_e32 v100, v102, v101
	v_mul_f32_e32 v98, v98, v100
	v_mul_f32_e32 v100, v103, v104
	v_cvt_pk_bf16_f32 v96, v96, v97
	v_mul_f32_e32 v99, v99, v100
	v_cvt_pk_bf16_f32 v97, v98, v99
	global_store_dwordx2 v[112:113], v[96:97], off offset:128
	v_mul_f32_e32 v96, 0xbfb8aa3b, v92
	v_exp_f32_e32 v98, v96
	v_mul_f32_e32 v99, 0xbfb8aa3b, v93
	v_exp_f32_e32 v99, v99
	v_or_b32_e32 v96, 32, v150
	v_add_f32_e32 v98, 1.0, v98
	v_rcp_f32_e32 v98, v98
	v_mad_i64_i32 v[96:97], s[48:49], v96, s68, v[140:141]
	v_lshl_add_u64 v[96:97], v[96:97], 0, v[142:143]
	v_mul_f32_e32 v92, v92, v98
	v_mul_f32_e32 v88, v88, v92
	v_add_f32_e32 v92, 1.0, v99
	v_mul_f32_e32 v98, 0xbfb8aa3b, v94
	v_rcp_f32_e32 v92, v92
	v_exp_f32_e32 v98, v98
	v_mul_f32_e32 v99, 0xbfb8aa3b, v95
	v_exp_f32_e32 v99, v99
	v_mul_f32_e32 v92, v93, v92
	v_add_f32_e32 v93, 1.0, v98
	v_rcp_f32_e32 v93, v93
	v_add_f32_e32 v98, 1.0, v99
	v_rcp_f32_e32 v98, v98
	v_mul_f32_e32 v89, v89, v92
	v_mul_f32_e32 v92, v94, v93
	v_mul_f32_e32 v93, 0xbfb8aa3b, v84
	v_exp_f32_e32 v93, v93
	v_mul_f32_e32 v90, v90, v92
	v_mul_f32_e32 v92, v95, v98
	v_mul_f32_e32 v91, v91, v92
	v_cvt_pk_bf16_f32 v88, v88, v89
	v_cvt_pk_bf16_f32 v89, v90, v91
	v_add_f32_e32 v90, 1.0, v93
	v_rcp_f32_e32 v90, v90
	v_mul_f32_e32 v91, 0xbfb8aa3b, v85
	v_exp_f32_e32 v91, v91
	global_store_dwordx2 v[96:97], v[88:89], off
	v_mul_f32_e32 v84, v84, v90
	v_mul_f32_e32 v80, v80, v84
	v_add_f32_e32 v84, 1.0, v91
	v_mul_f32_e32 v88, 0xbfb8aa3b, v86
	v_rcp_f32_e32 v84, v84
	v_exp_f32_e32 v88, v88
	v_mul_f32_e32 v89, 0xbfb8aa3b, v87
	v_exp_f32_e32 v89, v89
	v_mul_f32_e32 v84, v85, v84
	v_add_f32_e32 v85, 1.0, v88
	v_rcp_f32_e32 v85, v85
	v_add_f32_e32 v88, 1.0, v89
	v_rcp_f32_e32 v88, v88
	v_mul_f32_e32 v81, v81, v84
	v_mul_f32_e32 v84, v86, v85
	v_mul_f32_e32 v82, v82, v84
	v_mul_f32_e32 v84, v87, v88
	v_cvt_pk_bf16_f32 v80, v80, v81
	v_mul_f32_e32 v83, v83, v84
	v_cvt_pk_bf16_f32 v81, v82, v83
	global_store_dwordx2 v[96:97], v[80:81], off offset:128
	v_mul_f32_e32 v80, 0xbfb8aa3b, v76
	v_exp_f32_e32 v82, v80
	v_mul_f32_e32 v83, 0xbfb8aa3b, v77
	v_exp_f32_e32 v83, v83
	v_or_b32_e32 v80, 48, v150
	v_add_f32_e32 v82, 1.0, v82
	v_rcp_f32_e32 v82, v82
	v_mad_i64_i32 v[80:81], s[48:49], v80, s68, v[140:141]
	v_lshl_add_u64 v[80:81], v[80:81], 0, v[142:143]
	v_mul_f32_e32 v76, v76, v82
	v_mul_f32_e32 v72, v72, v76
	v_add_f32_e32 v76, 1.0, v83
	v_mul_f32_e32 v82, 0xbfb8aa3b, v78
	v_rcp_f32_e32 v76, v76
	v_exp_f32_e32 v82, v82
	v_mul_f32_e32 v83, 0xbfb8aa3b, v79
	v_exp_f32_e32 v83, v83
	v_mul_f32_e32 v76, v77, v76
	v_add_f32_e32 v77, 1.0, v82
	v_rcp_f32_e32 v77, v77
	v_add_f32_e32 v82, 1.0, v83
	v_rcp_f32_e32 v82, v82
	v_mul_f32_e32 v73, v73, v76
	v_mul_f32_e32 v76, v78, v77
	v_mul_f32_e32 v77, 0xbfb8aa3b, v68
	v_exp_f32_e32 v77, v77
	v_mul_f32_e32 v74, v74, v76
	v_mul_f32_e32 v76, v79, v82
	v_mul_f32_e32 v75, v75, v76
	v_cvt_pk_bf16_f32 v72, v72, v73
	v_cvt_pk_bf16_f32 v73, v74, v75
	v_add_f32_e32 v74, 1.0, v77
	v_rcp_f32_e32 v74, v74
	v_mul_f32_e32 v75, 0xbfb8aa3b, v69
	v_exp_f32_e32 v75, v75
	global_store_dwordx2 v[80:81], v[72:73], off
	v_mul_f32_e32 v68, v68, v74
	v_mul_f32_e32 v64, v64, v68
	v_add_f32_e32 v68, 1.0, v75
	v_mul_f32_e32 v72, 0xbfb8aa3b, v70
	v_rcp_f32_e32 v68, v68
	v_exp_f32_e32 v72, v72
	v_mul_f32_e32 v73, 0xbfb8aa3b, v71
	v_exp_f32_e32 v73, v73
	v_mul_f32_e32 v68, v69, v68
	v_add_f32_e32 v69, 1.0, v72
	v_rcp_f32_e32 v69, v69
	v_add_f32_e32 v72, 1.0, v73
	v_rcp_f32_e32 v72, v72
	v_mul_f32_e32 v65, v65, v68
	v_mul_f32_e32 v68, v70, v69
	v_mul_f32_e32 v66, v66, v68
	v_mul_f32_e32 v68, v71, v72
	v_cvt_pk_bf16_f32 v64, v64, v65
	v_mul_f32_e32 v67, v67, v68
	v_cvt_pk_bf16_f32 v65, v66, v67
	global_store_dwordx2 v[80:81], v[64:65], off offset:128
	v_mov_b32_e32 v216, v140
	v_mov_b32_e32 v217, v141
	v_mov_b32_e32 v218, v142
	v_mov_b32_e32 v219, v143
	v_mov_b32_e32 v220, v150
	s_andn2_b64 vcc, exec, s[0:1]
	s_cbranch_vccnz .Lov_nb_4
	s_barrier
.Lov_nb_4:
	s_mov_b32 s69, s18
	s_mov_b32 s46, s30
	s_mov_b64 s[52:53], s[44:45]
	s_mov_b64 s[48:49], s[36:37]
	s_add_i32 s63, s63, 1
	s_mul_i32 s10, s63, s21
	s_mul_hi_u32 s11, s63, s20
	s_add_i32 s11, s11, s10
	s_mul_i32 s10, s63, s20
	s_add_u32 s36, s10, s2
	s_addc_u32 s37, s11, s3
	v_cmp_gt_i64_e32 vcc, s[36:37], v[138:139]
	v_cmp_lt_i64_e64 s[10:11], s[36:37], v[136:137]
	s_cbranch_vccnz .LBB0_723_ov4
	s_lshr_b32 s18, s36, 3
	s_and_b32 s30, s36, 7
	s_lshl_b32 s30, s30, 1
	s_cmp_ge_u32 s18, 0xb0
	s_cbranch_scc0 .Ldec_4_ov4
	s_sub_u32 s18, s18, 0xb0
	s_add_u32 s30, s30, 1

.LBB0_723_ov4:
	s_ashr_i32 s31, s30, 31
	s_lshl_b64 s[36:37], s[30:31], 19
	s_add_u32 s36, s80, s36
	s_addc_u32 s37, s81, s37
	s_and_b64 s[44:45], s[10:11], exec
	s_cselect_b32 s31, s37, s49
	s_cselect_b32 s70, s36, s48
	s_ashr_i32 s19, s18, 31
	s_lshl_b64 s[44:45], s[18:19], 19
	s_add_u32 s44, s56, s44
	s_addc_u32 s45, s57, s45
	s_and_b64 s[54:55], s[10:11], exec
	s_cselect_b32 s19, s45, s53
	s_cselect_b32 s71, s44, s52
	s_add_u32 s48, s48, 0x40080
	s_addc_u32 s49, s49, 0
	s_add_u32 s72, s52, 0x100
	s_addc_u32 s73, s53, 0
	s_mov_b32 s74, -2
	ds_read_b128 v[140:143], v147
	ds_read_b128 v[150:153], v147 offset:1024
	ds_read_b128 v[154:157], v147 offset:2048
	ds_read_b128 v[158:161], v147 offset:3072
	ds_read_b128 v[162:165], v148
	ds_read_b128 v[166:169], v148 offset:1024
	ds_read_b128 v[170:173], v148 offset:2048
	ds_read_b128 v[174:177], v148 offset:3072
	s_add_u32 s52, s48, 0xfffc0080
	s_addc_u32 s53, s49, -1
	s_cmp_eq_u32 s74, 12
	s_cselect_b32 s55, s31, s53
	s_cselect_b32 s54, s70, s52
	s_cselect_b32 s53, s19, s73
	s_cselect_b32 s52, s71, s72
	v_lshl_add_u64 v[178:179], s[48:49], 0, v[132:133]
	s_add_i32 m0, s47, 0xc000
	ds_read_b128 v[184:187], v149
	ds_read_b128 v[188:191], v149 offset:1024
	ds_read_b128 v[192:195], v149 offset:2048
	ds_read_b128 v[196:199], v149 offset:3072
	ds_read_b128 v[200:203], v149 offset:4096
	ds_read_b128 v[204:207], v149 offset:5120
	ds_read_b128 v[208:211], v149 offset:6144
	ds_read_b128 v[212:215], v149 offset:7168
	global_load_lds_dwordx4 v[178:179], off
	v_lshl_add_u64 v[178:179], s[48:49], 0, v[134:135]
	s_add_i32 m0, s47, 0xe000
	s_nop 0
	global_load_lds_dwordx4 v[178:179], off
	s_waitcnt vmcnt(8)
	s_waitcnt lgkmcnt(0)
	s_barrier
	s_setprio 1
	s_waitcnt lgkmcnt(0)
	v_mfma_f32_16x16x32_bf16 v[124:127], v[140:143], v[184:187], 0
	v_mul_f32_e32 v222, 0xbfb8aa3b, v60
	v_exp_f32_e32 v224, v222
	v_mul_f32_e32 v225, 0xbfb8aa3b, v61
	v_exp_f32_e32 v225, v225
	v_add_u32_e32 v222, 0x80, v220
	v_add_f32_e32 v224, 1.0, v224
	v_rcp_f32_e32 v224, v224
	v_mad_i64_i32 v[222:223], vcc, v222, s68, v[216:217]
	v_mfma_f32_16x16x32_bf16 v[124:127], v[150:153], v[188:191], v[124:127]
	v_lshl_add_u64 v[222:223], v[222:223], 0, v[218:219]
	v_mul_f32_e32 v60, v60, v224
	v_mul_f32_e32 v56, v56, v60
	v_add_f32_e32 v60, 1.0, v225
	v_mul_f32_e32 v224, 0xbfb8aa3b, v62
	v_rcp_f32_e32 v60, v60
	v_exp_f32_e32 v224, v224
	v_mul_f32_e32 v225, 0xbfb8aa3b, v63
	v_mfma_f32_16x16x32_bf16 v[120:123], v[154:157], v[184:187], 0
	v_exp_f32_e32 v225, v225
	v_mul_f32_e32 v60, v61, v60
	v_add_f32_e32 v61, 1.0, v224
	v_rcp_f32_e32 v61, v61
	v_add_f32_e32 v224, 1.0, v225
	v_rcp_f32_e32 v224, v224
	v_mul_f32_e32 v57, v57, v60
	v_mul_f32_e32 v60, v62, v61
	v_mfma_f32_16x16x32_bf16 v[120:123], v[158:161], v[188:191], v[120:123]
	v_mul_f32_e32 v61, 0xbfb8aa3b, v52
	v_exp_f32_e32 v61, v61
	v_mul_f32_e32 v58, v58, v60
	v_mul_f32_e32 v60, v63, v224
	v_mul_f32_e32 v59, v59, v60
	v_cvt_pk_bf16_f32 v56, v56, v57
	v_cvt_pk_bf16_f32 v57, v58, v59
	v_add_f32_e32 v58, 1.0, v61
	v_mfma_f32_16x16x32_bf16 v[108:111], v[140:143], v[192:195], 0
	v_rcp_f32_e32 v58, v58
	v_mul_f32_e32 v59, 0xbfb8aa3b, v53
	v_exp_f32_e32 v59, v59
	global_store_dwordx2 v[222:223], v[56:57], off
	v_mul_f32_e32 v52, v52, v58
	v_mul_f32_e32 v48, v48, v52
	v_add_f32_e32 v52, 1.0, v59
	v_mul_f32_e32 v56, 0xbfb8aa3b, v54
	v_mfma_f32_16x16x32_bf16 v[108:111], v[150:153], v[196:199], v[108:111]
	v_rcp_f32_e32 v52, v52
	v_exp_f32_e32 v56, v56
	v_mul_f32_e32 v57, 0xbfb8aa3b, v55
	v_exp_f32_e32 v57, v57
	v_mul_f32_e32 v52, v53, v52
	v_add_f32_e32 v53, 1.0, v56
	v_rcp_f32_e32 v53, v53
	v_add_f32_e32 v56, 1.0, v57
	v_mfma_f32_16x16x32_bf16 v[104:107], v[154:157], v[192:195], 0
	v_rcp_f32_e32 v56, v56
	v_mul_f32_e32 v49, v49, v52
	v_mul_f32_e32 v52, v54, v53
	v_mul_f32_e32 v50, v50, v52
	v_mul_f32_e32 v52, v55, v56
	v_cvt_pk_bf16_f32 v48, v48, v49
	v_mul_f32_e32 v51, v51, v52
	v_cvt_pk_bf16_f32 v49, v50, v51
	v_mfma_f32_16x16x32_bf16 v[104:107], v[158:161], v[196:199], v[104:107]
	global_store_dwordx2 v[222:223], v[48:49], off offset:128
	v_mul_f32_e32 v48, 0xbfb8aa3b, v44
	v_exp_f32_e32 v50, v48
	v_mul_f32_e32 v51, 0xbfb8aa3b, v45
	v_exp_f32_e32 v51, v51
	v_add_u32_e32 v48, 0x90, v220
	v_add_f32_e32 v50, 1.0, v50
	v_rcp_f32_e32 v50, v50
	v_mfma_f32_16x16x32_bf16 v[92:95], v[140:143], v[200:203], 0
	v_mad_i64_i32 v[48:49], vcc, v48, s68, v[216:217]
	v_lshl_add_u64 v[48:49], v[48:49], 0, v[218:219]
	v_mul_f32_e32 v44, v44, v50
	v_mul_f32_e32 v40, v40, v44
	v_add_f32_e32 v44, 1.0, v51
	v_mul_f32_e32 v50, 0xbfb8aa3b, v46
	v_rcp_f32_e32 v44, v44
	v_exp_f32_e32 v50, v50
	v_mfma_f32_16x16x32_bf16 v[92:95], v[150:153], v[204:207], v[92:95]
	v_mul_f32_e32 v51, 0xbfb8aa3b, v47
	v_exp_f32_e32 v51, v51
	v_mul_f32_e32 v44, v45, v44
	v_add_f32_e32 v45, 1.0, v50
	v_rcp_f32_e32 v45, v45
	v_add_f32_e32 v50, 1.0, v51
	v_rcp_f32_e32 v50, v50
	v_mul_f32_e32 v41, v41, v44
	v_mfma_f32_16x16x32_bf16 v[88:91], v[154:157], v[200:203], 0
	v_mul_f32_e32 v44, v46, v45
	v_mul_f32_e32 v45, 0xbfb8aa3b, v36
	v_exp_f32_e32 v45, v45
	v_mul_f32_e32 v42, v42, v44
	v_mul_f32_e32 v44, v47, v50
	v_mul_f32_e32 v43, v43, v44
	v_cvt_pk_bf16_f32 v40, v40, v41
	v_cvt_pk_bf16_f32 v41, v42, v43
	v_mfma_f32_16x16x32_bf16 v[88:91], v[158:161], v[204:207], v[88:91]
	v_add_f32_e32 v42, 1.0, v45
	v_rcp_f32_e32 v42, v42
	v_mul_f32_e32 v43, 0xbfb8aa3b, v37
	v_exp_f32_e32 v43, v43
	global_store_dwordx2 v[48:49], v[40:41], off
	v_mul_f32_e32 v36, v36, v42
	v_mul_f32_e32 v32, v32, v36
	v_add_f32_e32 v36, 1.0, v43
	v_mfma_f32_16x16x32_bf16 v[76:79], v[140:143], v[208:211], 0
	v_mul_f32_e32 v40, 0xbfb8aa3b, v38
	v_rcp_f32_e32 v36, v36
	v_exp_f32_e32 v40, v40
	v_mul_f32_e32 v41, 0xbfb8aa3b, v39
	v_exp_f32_e32 v41, v41
	v_mul_f32_e32 v36, v37, v36
	v_add_f32_e32 v37, 1.0, v40
	v_rcp_f32_e32 v37, v37
	v_mfma_f32_16x16x32_bf16 v[76:79], v[150:153], v[212:215], v[76:79]
	v_add_f32_e32 v40, 1.0, v41
	v_rcp_f32_e32 v40, v40
	v_mul_f32_e32 v33, v33, v36
	v_mul_f32_e32 v36, v38, v37
	v_mul_f32_e32 v34, v34, v36
	v_mul_f32_e32 v36, v39, v40
	v_cvt_pk_bf16_f32 v32, v32, v33
	v_mul_f32_e32 v35, v35, v36
	v_mfma_f32_16x16x32_bf16 v[72:75], v[154:157], v[208:211], 0
	v_cvt_pk_bf16_f32 v33, v34, v35
	global_store_dwordx2 v[48:49], v[32:33], off offset:128
	v_mul_f32_e32 v32, 0xbfb8aa3b, v28
	v_exp_f32_e32 v34, v32
	v_mul_f32_e32 v35, 0xbfb8aa3b, v29
	v_exp_f32_e32 v35, v35
	v_add_u32_e32 v32, 0xa0, v220
	v_add_f32_e32 v34, 1.0, v34
	v_mfma_f32_16x16x32_bf16 v[72:75], v[158:161], v[212:215], v[72:75]
	v_rcp_f32_e32 v34, v34
	v_mad_i64_i32 v[32:33], vcc, v32, s68, v[216:217]
	v_lshl_add_u64 v[32:33], v[32:33], 0, v[218:219]
	v_mul_f32_e32 v28, v28, v34
	v_mul_f32_e32 v24, v24, v28
	v_add_f32_e32 v28, 1.0, v35
	v_mul_f32_e32 v34, 0xbfb8aa3b, v30
	v_rcp_f32_e32 v28, v28
	v_mfma_f32_16x16x32_bf16 v[116:119], v[162:165], v[184:187], 0
	v_exp_f32_e32 v34, v34
	v_mul_f32_e32 v35, 0xbfb8aa3b, v31
	v_exp_f32_e32 v35, v35
	v_mul_f32_e32 v28, v29, v28
	v_add_f32_e32 v29, 1.0, v34
	v_rcp_f32_e32 v29, v29
	v_add_f32_e32 v34, 1.0, v35
	v_rcp_f32_e32 v34, v34
	v_mfma_f32_16x16x32_bf16 v[116:119], v[166:169], v[188:191], v[116:119]
	v_mul_f32_e32 v25, v25, v28
	v_mul_f32_e32 v28, v30, v29
	v_mul_f32_e32 v29, 0xbfb8aa3b, v20
	v_exp_f32_e32 v29, v29
	v_mul_f32_e32 v26, v26, v28
	v_mul_f32_e32 v28, v31, v34
	v_mul_f32_e32 v27, v27, v28
	v_cvt_pk_bf16_f32 v24, v24, v25
	v_mfma_f32_16x16x32_bf16 v[112:115], v[170:173], v[184:187], 0
	v_cvt_pk_bf16_f32 v25, v26, v27
	v_add_f32_e32 v26, 1.0, v29
	v_rcp_f32_e32 v26, v26
	v_mul_f32_e32 v27, 0xbfb8aa3b, v21
	v_exp_f32_e32 v27, v27
	global_store_dwordx2 v[32:33], v[24:25], off
	v_mul_f32_e32 v20, v20, v26
	v_mul_f32_e32 v16, v16, v20
	v_mfma_f32_16x16x32_bf16 v[112:115], v[174:177], v[188:191], v[112:115]
	v_add_f32_e32 v20, 1.0, v27
	v_mul_f32_e32 v24, 0xbfb8aa3b, v22
	v_rcp_f32_e32 v20, v20
	v_exp_f32_e32 v24, v24
	v_mul_f32_e32 v25, 0xbfb8aa3b, v23
	v_exp_f32_e32 v25, v25
	v_mul_f32_e32 v20, v21, v20
	v_add_f32_e32 v21, 1.0, v24
	v_mfma_f32_16x16x32_bf16 v[100:103], v[162:165], v[192:195], 0
	v_rcp_f32_e32 v21, v21
	v_add_f32_e32 v24, 1.0, v25
	v_rcp_f32_e32 v24, v24
	v_mul_f32_e32 v17, v17, v20
	v_mul_f32_e32 v20, v22, v21
	v_mul_f32_e32 v18, v18, v20
	v_mul_f32_e32 v20, v23, v24
	v_cvt_pk_bf16_f32 v16, v16, v17
	v_mfma_f32_16x16x32_bf16 v[100:103], v[166:169], v[196:199], v[100:103]
	v_mul_f32_e32 v19, v19, v20
	v_cvt_pk_bf16_f32 v17, v18, v19
	global_store_dwordx2 v[32:33], v[16:17], off offset:128
	v_mul_f32_e32 v16, 0xbfb8aa3b, v12
	v_exp_f32_e32 v18, v16
	v_mul_f32_e32 v19, 0xbfb8aa3b, v13
	v_exp_f32_e32 v19, v19
	v_add_u32_e32 v16, 0xb0, v220
	v_mfma_f32_16x16x32_bf16 v[96:99], v[170:173], v[192:195], 0
	v_add_f32_e32 v18, 1.0, v18
	v_rcp_f32_e32 v18, v18
	v_mad_i64_i32 v[16:17], vcc, v16, s68, v[216:217]
	v_lshl_add_u64 v[16:17], v[16:17], 0, v[218:219]
	v_mul_f32_e32 v12, v12, v18
	v_mul_f32_e32 v8, v8, v12
	v_add_f32_e32 v12, 1.0, v19
	v_mul_f32_e32 v18, 0xbfb8aa3b, v14
	v_mfma_f32_16x16x32_bf16 v[96:99], v[174:177], v[196:199], v[96:99]
	v_rcp_f32_e32 v12, v12
	v_exp_f32_e32 v18, v18
	v_mul_f32_e32 v19, 0xbfb8aa3b, v15
	v_exp_f32_e32 v19, v19
	v_mul_f32_e32 v12, v13, v12
	v_add_f32_e32 v13, 1.0, v18
	v_rcp_f32_e32 v13, v13
	v_add_f32_e32 v18, 1.0, v19
	v_mfma_f32_16x16x32_bf16 v[84:87], v[162:165], v[200:203], 0
	v_rcp_f32_e32 v18, v18
	v_mul_f32_e32 v9, v9, v12
	v_mul_f32_e32 v12, v14, v13
	v_mul_f32_e32 v13, 0xbfb8aa3b, v4
	v_exp_f32_e32 v13, v13
	v_mul_f32_e32 v10, v10, v12
	v_mul_f32_e32 v12, v15, v18
	v_mul_f32_e32 v11, v11, v12
	v_mfma_f32_16x16x32_bf16 v[84:87], v[166:169], v[204:207], v[84:87]
	v_cvt_pk_bf16_f32 v8, v8, v9
	v_cvt_pk_bf16_f32 v9, v10, v11
	v_add_f32_e32 v10, 1.0, v13
	v_rcp_f32_e32 v10, v10
	v_mul_f32_e32 v11, 0xbfb8aa3b, v5
	v_exp_f32_e32 v11, v11
	global_store_dwordx2 v[16:17], v[8:9], off
	v_mul_f32_e32 v4, v4, v10
	v_mfma_f32_16x16x32_bf16 v[80:83], v[170:173], v[200:203], 0
	v_mul_f32_e32 v0, v0, v4
	v_add_f32_e32 v4, 1.0, v11
	v_mul_f32_e32 v8, 0xbfb8aa3b, v6
	v_rcp_f32_e32 v4, v4
	v_exp_f32_e32 v8, v8
	v_mul_f32_e32 v9, 0xbfb8aa3b, v7
	v_exp_f32_e32 v9, v9
	v_mul_f32_e32 v4, v5, v4
	v_mfma_f32_16x16x32_bf16 v[80:83], v[174:177], v[204:207], v[80:83]
	v_add_f32_e32 v5, 1.0, v8
	v_rcp_f32_e32 v5, v5
	v_add_f32_e32 v8, 1.0, v9
	v_rcp_f32_e32 v8, v8
	v_mul_f32_e32 v1, v1, v4
	v_mul_f32_e32 v4, v6, v5
	v_mul_f32_e32 v2, v2, v4
	v_mul_f32_e32 v4, v7, v8
	v_mfma_f32_16x16x32_bf16 v[68:71], v[162:165], v[208:211], 0
	v_mul_f32_e32 v3, v3, v4
	v_cvt_pk_bf16_f32 v0, v0, v1
	v_cvt_pk_bf16_f32 v1, v2, v3
	global_store_dwordx2 v[16:17], v[0:1], off offset:128
	v_mfma_f32_16x16x32_bf16 v[68:71], v[166:169], v[212:215], v[68:71]
	v_mfma_f32_16x16x32_bf16 v[64:67], v[170:173], v[208:211], 0
	v_mfma_f32_16x16x32_bf16 v[64:67], v[174:177], v[212:215], v[64:67]
	s_setprio 0
	s_barrier
	s_add_i32 s75, s66, s58
	v_lshl_add_u64 v[178:179], s[52:53], 0, v[130:131]
	s_mov_b32 m0, s75
	ds_read_b128 v[184:187], v149 offset:16384
	ds_read_b128 v[188:191], v149 offset:17408
	ds_read_b128 v[192:195], v149 offset:18432
	ds_read_b128 v[196:199], v149 offset:19456
	ds_read_b128 v[200:203], v149 offset:20480
	ds_read_b128 v[204:207], v149 offset:21504
	ds_read_b128 v[208:211], v149 offset:22528
	ds_read_b128 v[212:215], v149 offset:23552
	global_load_lds_dwordx4 v[178:179], off
	s_add_i32 m0, s75, 0x2000
	s_add_u32 s76, s52, 0x40000
	v_lshl_add_u64 v[216:217], s[52:53], 0, v[128:129]
	s_addc_u32 s77, s53, 0
	s_add_i32 s75, s67, s58
	global_load_lds_dwordx4 v[216:217], off
	v_lshl_add_u64 v[218:219], s[76:77], 0, v[130:131]
	s_mov_b32 m0, s75
	v_lshl_add_u64 v[220:221], s[54:55], 0, v[128:129]
	global_load_lds_dwordx4 v[218:219], off
	v_lshl_add_u64 v[218:219], s[76:77], 0, v[128:129]
	s_add_i32 m0, s75, 0x2000
	s_nop 0
	global_load_lds_dwordx4 v[218:219], off
	v_lshl_add_u64 v[218:219], s[54:55], 0, v[130:131]
	s_mov_b32 m0, s47
	s_nop 0
	global_load_lds_dwordx4 v[218:219], off
	s_mov_b32 m0, s60
	s_nop 0
	global_load_lds_dwordx4 v[220:221], off
	s_waitcnt vmcnt(8)
	s_waitcnt lgkmcnt(0)
	s_barrier
	s_setprio 1
	s_waitcnt lgkmcnt(0)
	v_mfma_f32_16x16x32_bf16 v[60:63], v[140:143], v[184:187], 0
	v_mfma_f32_16x16x32_bf16 v[60:63], v[150:153], v[188:191], v[60:63]
	v_mfma_f32_16x16x32_bf16 v[56:59], v[154:157], v[184:187], 0
	v_mfma_f32_16x16x32_bf16 v[56:59], v[158:161], v[188:191], v[56:59]
	v_mfma_f32_16x16x32_bf16 v[44:47], v[140:143], v[192:195], 0
	v_mfma_f32_16x16x32_bf16 v[44:47], v[150:153], v[196:199], v[44:47]
	v_mfma_f32_16x16x32_bf16 v[40:43], v[154:157], v[192:195], 0
	v_mfma_f32_16x16x32_bf16 v[40:43], v[158:161], v[196:199], v[40:43]
	v_mfma_f32_16x16x32_bf16 v[28:31], v[140:143], v[200:203], 0
	v_mfma_f32_16x16x32_bf16 v[28:31], v[150:153], v[204:207], v[28:31]
	v_mfma_f32_16x16x32_bf16 v[24:27], v[154:157], v[200:203], 0
	v_mfma_f32_16x16x32_bf16 v[24:27], v[158:161], v[204:207], v[24:27]
	v_mfma_f32_16x16x32_bf16 v[12:15], v[140:143], v[208:211], 0
	v_mfma_f32_16x16x32_bf16 v[12:15], v[150:153], v[212:215], v[12:15]
	v_mfma_f32_16x16x32_bf16 v[8:11], v[154:157], v[208:211], 0
	v_mfma_f32_16x16x32_bf16 v[8:11], v[158:161], v[212:215], v[8:11]
	v_mfma_f32_16x16x32_bf16 v[52:55], v[162:165], v[184:187], 0
	v_mfma_f32_16x16x32_bf16 v[52:55], v[166:169], v[188:191], v[52:55]
	v_mfma_f32_16x16x32_bf16 v[48:51], v[170:173], v[184:187], 0
	v_mfma_f32_16x16x32_bf16 v[48:51], v[174:177], v[188:191], v[48:51]
	v_mfma_f32_16x16x32_bf16 v[36:39], v[162:165], v[192:195], 0
	v_mfma_f32_16x16x32_bf16 v[36:39], v[166:169], v[196:199], v[36:39]
	v_mfma_f32_16x16x32_bf16 v[32:35], v[170:173], v[192:195], 0
	v_mfma_f32_16x16x32_bf16 v[32:35], v[174:177], v[196:199], v[32:35]
	v_mfma_f32_16x16x32_bf16 v[20:23], v[162:165], v[200:203], 0
	v_mfma_f32_16x16x32_bf16 v[20:23], v[166:169], v[204:207], v[20:23]
	v_mfma_f32_16x16x32_bf16 v[16:19], v[170:173], v[200:203], 0
	v_mfma_f32_16x16x32_bf16 v[16:19], v[174:177], v[204:207], v[16:19]
	v_mfma_f32_16x16x32_bf16 v[4:7], v[162:165], v[208:211], 0
	v_mfma_f32_16x16x32_bf16 v[4:7], v[166:169], v[212:215], v[4:7]
	v_mfma_f32_16x16x32_bf16 v[0:3], v[170:173], v[208:211], 0
	v_mfma_f32_16x16x32_bf16 v[0:3], v[174:177], v[212:215], v[0:3]
	s_setprio 0
	s_barrier
	s_branch .Lmid_gemm4

.LBB0_727:
	s_and_b64 vcc, exec, s[10:11]
	s_cbranch_vccnz .Lov_4
	v_mul_f32_e32 v151, 0xbfb8aa3b, v124
	v_exp_f32_e32 v151, v151
	v_mul_f32_e32 v154, 0xbfb8aa3b, v125
	v_exp_f32_e32 v154, v154
	v_lshl_or_b32 v142, s69, 7, v146
	v_add_f32_e32 v151, 1.0, v151
	v_rcp_f32_e32 v151, v151
	v_lshl_add_u32 v150, s46, 8, v144
	v_ashrrev_i32_e32 v143, 31, v142
	v_mov_b64_e32 v[140:141], s[22:23]
	v_mul_f32_e32 v124, v124, v151
	v_mul_f32_e32 v120, v120, v124
	v_add_f32_e32 v124, 1.0, v154
	v_mul_f32_e32 v151, 0xbfb8aa3b, v126
	v_rcp_f32_e32 v124, v124
	v_exp_f32_e32 v151, v151
	v_mul_f32_e32 v154, 0xbfb8aa3b, v127
	v_exp_f32_e32 v154, v154
	v_mul_f32_e32 v124, v125, v124
	v_add_f32_e32 v125, 1.0, v151
	v_rcp_f32_e32 v125, v125
	v_add_f32_e32 v151, 1.0, v154
	v_rcp_f32_e32 v151, v151
	v_mul_f32_e32 v121, v121, v124
	v_mul_f32_e32 v124, v126, v125
	v_mul_f32_e32 v125, 0xbfb8aa3b, v116
	v_exp_f32_e32 v125, v125
	v_mul_f32_e32 v122, v122, v124
	v_mul_f32_e32 v124, v127, v151
	v_mul_f32_e32 v123, v123, v124
	v_cvt_pk_bf16_f32 v120, v120, v121
	v_cvt_pk_bf16_f32 v121, v122, v123
	v_add_f32_e32 v122, 1.0, v125
	v_rcp_f32_e32 v122, v122
	v_mul_f32_e32 v123, 0xbfb8aa3b, v117
	v_exp_f32_e32 v123, v123
	v_mad_i64_i32 v[152:153], s[48:49], v150, s68, v[140:141]
	v_lshlrev_b64 v[142:143], 1, v[142:143]
	v_lshl_add_u64 v[152:153], v[152:153], 0, v[142:143]
	v_mul_f32_e32 v116, v116, v122
	global_store_dwordx2 v[152:153], v[120:121], off
	v_mul_f32_e32 v112, v112, v116
	v_add_f32_e32 v116, 1.0, v123
	v_mul_f32_e32 v120, 0xbfb8aa3b, v118
	v_rcp_f32_e32 v116, v116
	v_exp_f32_e32 v120, v120
	v_mul_f32_e32 v121, 0xbfb8aa3b, v119
	v_exp_f32_e32 v121, v121
	v_mul_f32_e32 v116, v117, v116
	v_add_f32_e32 v117, 1.0, v120
	v_rcp_f32_e32 v117, v117
	v_add_f32_e32 v120, 1.0, v121
	v_rcp_f32_e32 v120, v120
	v_mul_f32_e32 v113, v113, v116
	v_mul_f32_e32 v116, v118, v117
	v_mul_f32_e32 v114, v114, v116
	v_mul_f32_e32 v116, v119, v120
	v_cvt_pk_bf16_f32 v112, v112, v113
	v_mul_f32_e32 v115, v115, v116
	v_cvt_pk_bf16_f32 v113, v114, v115
	global_store_dwordx2 v[152:153], v[112:113], off offset:128
	v_mul_f32_e32 v112, 0xbfb8aa3b, v108
	v_exp_f32_e32 v114, v112
	v_mul_f32_e32 v115, 0xbfb8aa3b, v109
	v_exp_f32_e32 v115, v115
	v_or_b32_e32 v112, 16, v150
	v_add_f32_e32 v114, 1.0, v114
	v_rcp_f32_e32 v114, v114
	v_mad_i64_i32 v[112:113], s[48:49], v112, s68, v[140:141]
	v_lshl_add_u64 v[112:113], v[112:113], 0, v[142:143]
	v_mul_f32_e32 v108, v108, v114
	v_mul_f32_e32 v104, v104, v108
	v_add_f32_e32 v108, 1.0, v115
	v_mul_f32_e32 v114, 0xbfb8aa3b, v110
	v_rcp_f32_e32 v108, v108
	v_exp_f32_e32 v114, v114
	v_mul_f32_e32 v115, 0xbfb8aa3b, v111
	v_exp_f32_e32 v115, v115
	v_mul_f32_e32 v108, v109, v108
	v_add_f32_e32 v109, 1.0, v114
	v_rcp_f32_e32 v109, v109
	v_add_f32_e32 v114, 1.0, v115
	v_rcp_f32_e32 v114, v114
	v_mul_f32_e32 v105, v105, v108
	v_mul_f32_e32 v108, v110, v109
	v_mul_f32_e32 v109, 0xbfb8aa3b, v100
	v_exp_f32_e32 v109, v109
	v_mul_f32_e32 v106, v106, v108
	v_mul_f32_e32 v108, v111, v114
	v_mul_f32_e32 v107, v107, v108
	v_cvt_pk_bf16_f32 v104, v104, v105
	v_cvt_pk_bf16_f32 v105, v106, v107
	v_add_f32_e32 v106, 1.0, v109
	v_rcp_f32_e32 v106, v106
	v_mul_f32_e32 v107, 0xbfb8aa3b, v101
	v_exp_f32_e32 v107, v107
	global_store_dwordx2 v[112:113], v[104:105], off
	v_mul_f32_e32 v100, v100, v106
	v_mul_f32_e32 v96, v96, v100
	v_add_f32_e32 v100, 1.0, v107
	v_mul_f32_e32 v104, 0xbfb8aa3b, v102
	v_rcp_f32_e32 v100, v100
	v_exp_f32_e32 v104, v104
	v_mul_f32_e32 v105, 0xbfb8aa3b, v103
	v_exp_f32_e32 v105, v105
	v_mul_f32_e32 v100, v101, v100
	v_add_f32_e32 v101, 1.0, v104
	v_rcp_f32_e32 v101, v101
	v_add_f32_e32 v104, 1.0, v105
	v_rcp_f32_e32 v104, v104
	v_mul_f32_e32 v97, v97, v100
	v_mul_f32_e32 v100, v102, v101
	v_mul_f32_e32 v98, v98, v100
	v_mul_f32_e32 v100, v103, v104
	v_cvt_pk_bf16_f32 v96, v96, v97
	v_mul_f32_e32 v99, v99, v100
	v_cvt_pk_bf16_f32 v97, v98, v99
	global_store_dwordx2 v[112:113], v[96:97], off offset:128
	v_mul_f32_e32 v96, 0xbfb8aa3b, v92
	v_exp_f32_e32 v98, v96
	v_mul_f32_e32 v99, 0xbfb8aa3b, v93
	v_exp_f32_e32 v99, v99
	v_or_b32_e32 v96, 32, v150
	v_add_f32_e32 v98, 1.0, v98
	v_rcp_f32_e32 v98, v98
	v_mad_i64_i32 v[96:97], s[48:49], v96, s68, v[140:141]
	v_lshl_add_u64 v[96:97], v[96:97], 0, v[142:143]
	v_mul_f32_e32 v92, v92, v98
	v_mul_f32_e32 v88, v88, v92
	v_add_f32_e32 v92, 1.0, v99
	v_mul_f32_e32 v98, 0xbfb8aa3b, v94
	v_rcp_f32_e32 v92, v92
	v_exp_f32_e32 v98, v98
	v_mul_f32_e32 v99, 0xbfb8aa3b, v95
	v_exp_f32_e32 v99, v99
	v_mul_f32_e32 v92, v93, v92
	v_add_f32_e32 v93, 1.0, v98
	v_rcp_f32_e32 v93, v93
	v_add_f32_e32 v98, 1.0, v99
	v_rcp_f32_e32 v98, v98
	v_mul_f32_e32 v89, v89, v92
	v_mul_f32_e32 v92, v94, v93
	v_mul_f32_e32 v93, 0xbfb8aa3b, v84
	v_exp_f32_e32 v93, v93
	v_mul_f32_e32 v90, v90, v92
	v_mul_f32_e32 v92, v95, v98
	v_mul_f32_e32 v91, v91, v92
	v_cvt_pk_bf16_f32 v88, v88, v89
	v_cvt_pk_bf16_f32 v89, v90, v91
	v_add_f32_e32 v90, 1.0, v93
	v_rcp_f32_e32 v90, v90
	v_mul_f32_e32 v91, 0xbfb8aa3b, v85
	v_exp_f32_e32 v91, v91
	global_store_dwordx2 v[96:97], v[88:89], off
	v_mul_f32_e32 v84, v84, v90
	v_mul_f32_e32 v80, v80, v84
	v_add_f32_e32 v84, 1.0, v91
	v_mul_f32_e32 v88, 0xbfb8aa3b, v86
	v_rcp_f32_e32 v84, v84
	v_exp_f32_e32 v88, v88
	v_mul_f32_e32 v89, 0xbfb8aa3b, v87
	v_exp_f32_e32 v89, v89
	v_mul_f32_e32 v84, v85, v84
	v_add_f32_e32 v85, 1.0, v88
	v_rcp_f32_e32 v85, v85
	v_add_f32_e32 v88, 1.0, v89
	v_rcp_f32_e32 v88, v88
	v_mul_f32_e32 v81, v81, v84
	v_mul_f32_e32 v84, v86, v85
	v_mul_f32_e32 v82, v82, v84
	v_mul_f32_e32 v84, v87, v88
	v_cvt_pk_bf16_f32 v80, v80, v81
	v_mul_f32_e32 v83, v83, v84
	v_cvt_pk_bf16_f32 v81, v82, v83
	global_store_dwordx2 v[96:97], v[80:81], off offset:128
	v_mul_f32_e32 v80, 0xbfb8aa3b, v76
	v_exp_f32_e32 v82, v80
	v_mul_f32_e32 v83, 0xbfb8aa3b, v77
	v_exp_f32_e32 v83, v83
	v_or_b32_e32 v80, 48, v150
	v_add_f32_e32 v82, 1.0, v82
	v_rcp_f32_e32 v82, v82
	v_mad_i64_i32 v[80:81], s[48:49], v80, s68, v[140:141]
	v_lshl_add_u64 v[80:81], v[80:81], 0, v[142:143]
	v_mul_f32_e32 v76, v76, v82
	v_mul_f32_e32 v72, v72, v76
	v_add_f32_e32 v76, 1.0, v83
	v_mul_f32_e32 v82, 0xbfb8aa3b, v78
	v_rcp_f32_e32 v76, v76
	v_exp_f32_e32 v82, v82
	v_mul_f32_e32 v83, 0xbfb8aa3b, v79
	v_exp_f32_e32 v83, v83
	v_mul_f32_e32 v76, v77, v76
	v_add_f32_e32 v77, 1.0, v82
	v_rcp_f32_e32 v77, v77
	v_add_f32_e32 v82, 1.0, v83
	v_rcp_f32_e32 v82, v82
	v_mul_f32_e32 v73, v73, v76
	v_mul_f32_e32 v76, v78, v77
	v_mul_f32_e32 v77, 0xbfb8aa3b, v68
	v_exp_f32_e32 v77, v77
	v_mul_f32_e32 v74, v74, v76
	v_mul_f32_e32 v76, v79, v82
	v_mul_f32_e32 v75, v75, v76
	v_cvt_pk_bf16_f32 v72, v72, v73
	v_cvt_pk_bf16_f32 v73, v74, v75
	v_add_f32_e32 v74, 1.0, v77
	v_rcp_f32_e32 v74, v74
	v_mul_f32_e32 v75, 0xbfb8aa3b, v69
	v_exp_f32_e32 v75, v75
	global_store_dwordx2 v[80:81], v[72:73], off
	v_mul_f32_e32 v68, v68, v74
	v_mul_f32_e32 v64, v64, v68
	v_add_f32_e32 v68, 1.0, v75
	v_mul_f32_e32 v72, 0xbfb8aa3b, v70
	v_rcp_f32_e32 v68, v68
	v_exp_f32_e32 v72, v72
	v_mul_f32_e32 v73, 0xbfb8aa3b, v71
	v_exp_f32_e32 v73, v73
	v_mul_f32_e32 v68, v69, v68
	v_add_f32_e32 v69, 1.0, v72
	v_rcp_f32_e32 v69, v69
	v_add_f32_e32 v72, 1.0, v73
	v_rcp_f32_e32 v72, v72
	v_mul_f32_e32 v65, v65, v68
	v_mul_f32_e32 v68, v70, v69
	v_mul_f32_e32 v66, v66, v68
	v_mul_f32_e32 v68, v71, v72
	v_cvt_pk_bf16_f32 v64, v64, v65
	v_mul_f32_e32 v67, v67, v68
	v_cvt_pk_bf16_f32 v65, v66, v67
	global_store_dwordx2 v[80:81], v[64:65], off offset:128
	v_mul_f32_e32 v64, 0xbfb8aa3b, v60
	v_exp_f32_e32 v66, v64
	v_mul_f32_e32 v67, 0xbfb8aa3b, v61
	v_exp_f32_e32 v67, v67
	v_add_u32_e32 v64, 0x80, v150
	v_add_f32_e32 v66, 1.0, v66
	v_rcp_f32_e32 v66, v66
	v_mad_i64_i32 v[64:65], s[48:49], v64, s68, v[140:141]
	v_lshl_add_u64 v[64:65], v[64:65], 0, v[142:143]
	v_mul_f32_e32 v60, v60, v66
	v_mul_f32_e32 v56, v56, v60
	v_add_f32_e32 v60, 1.0, v67
	v_mul_f32_e32 v66, 0xbfb8aa3b, v62
	v_rcp_f32_e32 v60, v60
	v_exp_f32_e32 v66, v66
	v_mul_f32_e32 v67, 0xbfb8aa3b, v63
	v_exp_f32_e32 v67, v67
	v_mul_f32_e32 v60, v61, v60
	v_add_f32_e32 v61, 1.0, v66
	v_rcp_f32_e32 v61, v61
	v_add_f32_e32 v66, 1.0, v67
	v_rcp_f32_e32 v66, v66
	v_mul_f32_e32 v57, v57, v60
	v_mul_f32_e32 v60, v62, v61
	v_mul_f32_e32 v61, 0xbfb8aa3b, v52
	v_exp_f32_e32 v61, v61
	v_mul_f32_e32 v58, v58, v60
	v_mul_f32_e32 v60, v63, v66
	v_mul_f32_e32 v59, v59, v60
	v_cvt_pk_bf16_f32 v56, v56, v57
	v_cvt_pk_bf16_f32 v57, v58, v59
	v_add_f32_e32 v58, 1.0, v61
	v_rcp_f32_e32 v58, v58
	v_mul_f32_e32 v59, 0xbfb8aa3b, v53
	v_exp_f32_e32 v59, v59
	global_store_dwordx2 v[64:65], v[56:57], off
	v_mul_f32_e32 v52, v52, v58
	v_mul_f32_e32 v48, v48, v52
	v_add_f32_e32 v52, 1.0, v59
	v_mul_f32_e32 v56, 0xbfb8aa3b, v54
	v_rcp_f32_e32 v52, v52
	v_exp_f32_e32 v56, v56
	v_mul_f32_e32 v57, 0xbfb8aa3b, v55
	v_exp_f32_e32 v57, v57
	v_mul_f32_e32 v52, v53, v52
	v_add_f32_e32 v53, 1.0, v56
	v_rcp_f32_e32 v53, v53
	v_add_f32_e32 v56, 1.0, v57
	v_rcp_f32_e32 v56, v56
	v_mul_f32_e32 v49, v49, v52
	v_mul_f32_e32 v52, v54, v53
	v_mul_f32_e32 v50, v50, v52
	v_mul_f32_e32 v52, v55, v56
	v_cvt_pk_bf16_f32 v48, v48, v49
	v_mul_f32_e32 v51, v51, v52
	v_cvt_pk_bf16_f32 v49, v50, v51
	global_store_dwordx2 v[64:65], v[48:49], off offset:128
	v_mul_f32_e32 v48, 0xbfb8aa3b, v44
	v_exp_f32_e32 v50, v48
	v_mul_f32_e32 v51, 0xbfb8aa3b, v45
	v_exp_f32_e32 v51, v51
	v_add_u32_e32 v48, 0x90, v150
	v_add_f32_e32 v50, 1.0, v50
	v_rcp_f32_e32 v50, v50
	v_mad_i64_i32 v[48:49], s[48:49], v48, s68, v[140:141]
	v_lshl_add_u64 v[48:49], v[48:49], 0, v[142:143]
	v_mul_f32_e32 v44, v44, v50
	v_mul_f32_e32 v40, v40, v44
	v_add_f32_e32 v44, 1.0, v51
	v_mul_f32_e32 v50, 0xbfb8aa3b, v46
	v_rcp_f32_e32 v44, v44
	v_exp_f32_e32 v50, v50
	v_mul_f32_e32 v51, 0xbfb8aa3b, v47
	v_exp_f32_e32 v51, v51
	v_mul_f32_e32 v44, v45, v44
	v_add_f32_e32 v45, 1.0, v50
	v_rcp_f32_e32 v45, v45
	v_add_f32_e32 v50, 1.0, v51
	v_rcp_f32_e32 v50, v50
	v_mul_f32_e32 v41, v41, v44
	v_mul_f32_e32 v44, v46, v45
	v_mul_f32_e32 v45, 0xbfb8aa3b, v36
	v_exp_f32_e32 v45, v45
	v_mul_f32_e32 v42, v42, v44
	v_mul_f32_e32 v44, v47, v50
	v_mul_f32_e32 v43, v43, v44
	v_cvt_pk_bf16_f32 v40, v40, v41
	v_cvt_pk_bf16_f32 v41, v42, v43
	v_add_f32_e32 v42, 1.0, v45
	v_rcp_f32_e32 v42, v42
	v_mul_f32_e32 v43, 0xbfb8aa3b, v37
	v_exp_f32_e32 v43, v43
	global_store_dwordx2 v[48:49], v[40:41], off
	v_mul_f32_e32 v36, v36, v42
	v_mul_f32_e32 v32, v32, v36
	v_add_f32_e32 v36, 1.0, v43
	v_mul_f32_e32 v40, 0xbfb8aa3b, v38
	v_rcp_f32_e32 v36, v36
	v_exp_f32_e32 v40, v40
	v_mul_f32_e32 v41, 0xbfb8aa3b, v39
	v_exp_f32_e32 v41, v41
	v_mul_f32_e32 v36, v37, v36
	v_add_f32_e32 v37, 1.0, v40
	v_rcp_f32_e32 v37, v37
	v_add_f32_e32 v40, 1.0, v41
	v_rcp_f32_e32 v40, v40
	v_mul_f32_e32 v33, v33, v36
	v_mul_f32_e32 v36, v38, v37
	v_mul_f32_e32 v34, v34, v36
	v_mul_f32_e32 v36, v39, v40
	v_cvt_pk_bf16_f32 v32, v32, v33
	v_mul_f32_e32 v35, v35, v36
	v_cvt_pk_bf16_f32 v33, v34, v35
	global_store_dwordx2 v[48:49], v[32:33], off offset:128
	v_mul_f32_e32 v32, 0xbfb8aa3b, v28
	v_exp_f32_e32 v34, v32
	v_mul_f32_e32 v35, 0xbfb8aa3b, v29
	v_exp_f32_e32 v35, v35
	v_add_u32_e32 v32, 0xa0, v150
	v_add_f32_e32 v34, 1.0, v34
	v_rcp_f32_e32 v34, v34
	v_mad_i64_i32 v[32:33], s[48:49], v32, s68, v[140:141]
	v_lshl_add_u64 v[32:33], v[32:33], 0, v[142:143]
	v_mul_f32_e32 v28, v28, v34
	v_mul_f32_e32 v24, v24, v28
	v_add_f32_e32 v28, 1.0, v35
	v_mul_f32_e32 v34, 0xbfb8aa3b, v30
	v_rcp_f32_e32 v28, v28
	v_exp_f32_e32 v34, v34
	v_mul_f32_e32 v35, 0xbfb8aa3b, v31
	v_exp_f32_e32 v35, v35
	v_mul_f32_e32 v28, v29, v28
	v_add_f32_e32 v29, 1.0, v34
	v_rcp_f32_e32 v29, v29
	v_add_f32_e32 v34, 1.0, v35
	v_rcp_f32_e32 v34, v34
	v_mul_f32_e32 v25, v25, v28
	v_mul_f32_e32 v28, v30, v29
	v_mul_f32_e32 v29, 0xbfb8aa3b, v20
	v_exp_f32_e32 v29, v29
	v_mul_f32_e32 v26, v26, v28
	v_mul_f32_e32 v28, v31, v34
	v_mul_f32_e32 v27, v27, v28
	v_cvt_pk_bf16_f32 v24, v24, v25
	v_cvt_pk_bf16_f32 v25, v26, v27
	v_add_f32_e32 v26, 1.0, v29
	v_rcp_f32_e32 v26, v26
	v_mul_f32_e32 v27, 0xbfb8aa3b, v21
	v_exp_f32_e32 v27, v27
	global_store_dwordx2 v[32:33], v[24:25], off
	v_mul_f32_e32 v20, v20, v26
	v_mul_f32_e32 v16, v16, v20
	v_add_f32_e32 v20, 1.0, v27
	v_mul_f32_e32 v24, 0xbfb8aa3b, v22
	v_rcp_f32_e32 v20, v20
	v_exp_f32_e32 v24, v24
	v_mul_f32_e32 v25, 0xbfb8aa3b, v23
	v_exp_f32_e32 v25, v25
	v_mul_f32_e32 v20, v21, v20
	v_add_f32_e32 v21, 1.0, v24
	v_rcp_f32_e32 v21, v21
	v_add_f32_e32 v24, 1.0, v25
	v_rcp_f32_e32 v24, v24
	v_mul_f32_e32 v17, v17, v20
	v_mul_f32_e32 v20, v22, v21
	v_mul_f32_e32 v18, v18, v20
	v_mul_f32_e32 v20, v23, v24
	v_cvt_pk_bf16_f32 v16, v16, v17
	v_mul_f32_e32 v19, v19, v20
	v_cvt_pk_bf16_f32 v17, v18, v19
	global_store_dwordx2 v[32:33], v[16:17], off offset:128
	v_mul_f32_e32 v16, 0xbfb8aa3b, v12
	v_exp_f32_e32 v18, v16
	v_mul_f32_e32 v19, 0xbfb8aa3b, v13
	v_exp_f32_e32 v19, v19
	v_add_u32_e32 v16, 0xb0, v150
	v_add_f32_e32 v18, 1.0, v18
	v_rcp_f32_e32 v18, v18
	v_mad_i64_i32 v[16:17], s[48:49], v16, s68, v[140:141]
	v_lshl_add_u64 v[16:17], v[16:17], 0, v[142:143]
	v_mul_f32_e32 v12, v12, v18
	v_mul_f32_e32 v8, v8, v12
	v_add_f32_e32 v12, 1.0, v19
	v_mul_f32_e32 v18, 0xbfb8aa3b, v14
	v_rcp_f32_e32 v12, v12
	v_exp_f32_e32 v18, v18
	v_mul_f32_e32 v19, 0xbfb8aa3b, v15
	v_exp_f32_e32 v19, v19
	v_mul_f32_e32 v12, v13, v12
	v_add_f32_e32 v13, 1.0, v18
	v_rcp_f32_e32 v13, v13
	v_add_f32_e32 v18, 1.0, v19
	v_rcp_f32_e32 v18, v18
	v_mul_f32_e32 v9, v9, v12
	v_mul_f32_e32 v12, v14, v13
	v_mul_f32_e32 v13, 0xbfb8aa3b, v4
	v_exp_f32_e32 v13, v13
	v_mul_f32_e32 v10, v10, v12
	v_mul_f32_e32 v12, v15, v18
	v_mul_f32_e32 v11, v11, v12
	v_cvt_pk_bf16_f32 v8, v8, v9
	v_cvt_pk_bf16_f32 v9, v10, v11
	v_add_f32_e32 v10, 1.0, v13
	v_rcp_f32_e32 v10, v10
	v_mul_f32_e32 v11, 0xbfb8aa3b, v5
	v_exp_f32_e32 v11, v11
	global_store_dwordx2 v[16:17], v[8:9], off
	v_mul_f32_e32 v4, v4, v10
	v_mul_f32_e32 v0, v0, v4
	v_add_f32_e32 v4, 1.0, v11
	v_mul_f32_e32 v8, 0xbfb8aa3b, v6
	v_rcp_f32_e32 v4, v4
	v_exp_f32_e32 v8, v8
	v_mul_f32_e32 v9, 0xbfb8aa3b, v7
	v_exp_f32_e32 v9, v9
	v_mul_f32_e32 v4, v5, v4
	v_add_f32_e32 v5, 1.0, v8
	v_rcp_f32_e32 v5, v5
	v_add_f32_e32 v8, 1.0, v9
	v_rcp_f32_e32 v8, v8
	v_mul_f32_e32 v1, v1, v4
	v_mul_f32_e32 v4, v6, v5
	v_mul_f32_e32 v2, v2, v4
	v_mul_f32_e32 v4, v7, v8
	s_andn2_b64 vcc, exec, s[10:11]
	s_mov_b64 s[10:11], -1
	v_mul_f32_e32 v3, v3, v4
	v_cvt_pk_bf16_f32 v0, v0, v1
	v_cvt_pk_bf16_f32 v1, v2, v3
	global_store_dwordx2 v[16:17], v[0:1], off offset:128
	s_cbranch_vccnz .LBB0_720
	s_andn2_b64 vcc, exec, s[0:1]
	s_cbranch_vccnz .LBB0_719
	s_barrier
	s_branch .LBB0_719

.Lov_7:
	v_mul_f32_e32 v151, 0xbfb8aa3b, v124
	v_exp_f32_e32 v151, v151
	v_mul_f32_e32 v154, 0xbfb8aa3b, v125
	v_exp_f32_e32 v154, v154
	v_lshl_or_b32 v142, s71, 7, v146
	v_add_f32_e32 v151, 1.0, v151
	v_rcp_f32_e32 v151, v151
	v_lshl_add_u32 v150, s48, 8, v144
	v_ashrrev_i32_e32 v143, 31, v142
	v_mov_b64_e32 v[140:141], s[22:23]
	v_mul_f32_e32 v124, v124, v151
	v_mul_f32_e32 v120, v120, v124
	v_add_f32_e32 v124, 1.0, v154
	v_mul_f32_e32 v151, 0xbfb8aa3b, v126
	v_rcp_f32_e32 v124, v124
	v_exp_f32_e32 v151, v151
	v_mul_f32_e32 v154, 0xbfb8aa3b, v127
	v_exp_f32_e32 v154, v154
	v_mul_f32_e32 v124, v125, v124
	v_add_f32_e32 v125, 1.0, v151
	v_rcp_f32_e32 v125, v125
	v_add_f32_e32 v151, 1.0, v154
	v_rcp_f32_e32 v151, v151
	v_mul_f32_e32 v121, v121, v124
	v_mul_f32_e32 v124, v126, v125
	v_mul_f32_e32 v125, 0xbfb8aa3b, v116
	v_exp_f32_e32 v125, v125
	v_mul_f32_e32 v122, v122, v124
	v_mul_f32_e32 v124, v127, v151
	v_mul_f32_e32 v123, v123, v124
	v_cvt_pk_bf16_f32 v120, v120, v121
	v_cvt_pk_bf16_f32 v121, v122, v123
	v_add_f32_e32 v122, 1.0, v125
	v_rcp_f32_e32 v122, v122
	v_mul_f32_e32 v123, 0xbfb8aa3b, v117
	v_exp_f32_e32 v123, v123
	v_mad_i64_i32 v[152:153], s[52:53], v150, s70, v[140:141]
	v_lshlrev_b64 v[142:143], 1, v[142:143]
	v_lshl_add_u64 v[152:153], v[152:153], 0, v[142:143]
	v_mul_f32_e32 v116, v116, v122
	global_store_dwordx2 v[152:153], v[120:121], off
	v_mul_f32_e32 v112, v112, v116
	v_add_f32_e32 v116, 1.0, v123
	v_mul_f32_e32 v120, 0xbfb8aa3b, v118
	v_rcp_f32_e32 v116, v116
	v_exp_f32_e32 v120, v120
	v_mul_f32_e32 v121, 0xbfb8aa3b, v119
	v_exp_f32_e32 v121, v121
	v_mul_f32_e32 v116, v117, v116
	v_add_f32_e32 v117, 1.0, v120
	v_rcp_f32_e32 v117, v117
	v_add_f32_e32 v120, 1.0, v121
	v_rcp_f32_e32 v120, v120
	v_mul_f32_e32 v113, v113, v116
	v_mul_f32_e32 v116, v118, v117
	v_mul_f32_e32 v114, v114, v116
	v_mul_f32_e32 v116, v119, v120
	v_cvt_pk_bf16_f32 v112, v112, v113
	v_mul_f32_e32 v115, v115, v116
	v_cvt_pk_bf16_f32 v113, v114, v115
	global_store_dwordx2 v[152:153], v[112:113], off offset:128
	v_mul_f32_e32 v112, 0xbfb8aa3b, v108
	v_exp_f32_e32 v114, v112
	v_mul_f32_e32 v115, 0xbfb8aa3b, v109
	v_exp_f32_e32 v115, v115
	v_or_b32_e32 v112, 16, v150
	v_add_f32_e32 v114, 1.0, v114
	v_rcp_f32_e32 v114, v114
	v_mad_i64_i32 v[112:113], s[52:53], v112, s70, v[140:141]
	v_lshl_add_u64 v[112:113], v[112:113], 0, v[142:143]
	v_mul_f32_e32 v108, v108, v114
	v_mul_f32_e32 v104, v104, v108
	v_add_f32_e32 v108, 1.0, v115
	v_mul_f32_e32 v114, 0xbfb8aa3b, v110
	v_rcp_f32_e32 v108, v108
	v_exp_f32_e32 v114, v114
	v_mul_f32_e32 v115, 0xbfb8aa3b, v111
	v_exp_f32_e32 v115, v115
	v_mul_f32_e32 v108, v109, v108
	v_add_f32_e32 v109, 1.0, v114
	v_rcp_f32_e32 v109, v109
	v_add_f32_e32 v114, 1.0, v115
	v_rcp_f32_e32 v114, v114
	v_mul_f32_e32 v105, v105, v108
	v_mul_f32_e32 v108, v110, v109
	v_mul_f32_e32 v109, 0xbfb8aa3b, v100
	v_exp_f32_e32 v109, v109
	v_mul_f32_e32 v106, v106, v108
	v_mul_f32_e32 v108, v111, v114
	v_mul_f32_e32 v107, v107, v108
	v_cvt_pk_bf16_f32 v104, v104, v105
	v_cvt_pk_bf16_f32 v105, v106, v107
	v_add_f32_e32 v106, 1.0, v109
	v_rcp_f32_e32 v106, v106
	v_mul_f32_e32 v107, 0xbfb8aa3b, v101
	v_exp_f32_e32 v107, v107
	global_store_dwordx2 v[112:113], v[104:105], off
	v_mul_f32_e32 v100, v100, v106
	v_mul_f32_e32 v96, v96, v100
	v_add_f32_e32 v100, 1.0, v107
	v_mul_f32_e32 v104, 0xbfb8aa3b, v102
	v_rcp_f32_e32 v100, v100
	v_exp_f32_e32 v104, v104
	v_mul_f32_e32 v105, 0xbfb8aa3b, v103
	v_exp_f32_e32 v105, v105
	v_mul_f32_e32 v100, v101, v100
	v_add_f32_e32 v101, 1.0, v104
	v_rcp_f32_e32 v101, v101
	v_add_f32_e32 v104, 1.0, v105
	v_rcp_f32_e32 v104, v104
	v_mul_f32_e32 v97, v97, v100
	v_mul_f32_e32 v100, v102, v101
	v_mul_f32_e32 v98, v98, v100
	v_mul_f32_e32 v100, v103, v104
	v_cvt_pk_bf16_f32 v96, v96, v97
	v_mul_f32_e32 v99, v99, v100
	v_cvt_pk_bf16_f32 v97, v98, v99
	global_store_dwordx2 v[112:113], v[96:97], off offset:128
	v_mul_f32_e32 v96, 0xbfb8aa3b, v92
	v_exp_f32_e32 v98, v96
	v_mul_f32_e32 v99, 0xbfb8aa3b, v93
	v_exp_f32_e32 v99, v99
	v_or_b32_e32 v96, 32, v150
	v_add_f32_e32 v98, 1.0, v98
	v_rcp_f32_e32 v98, v98
	v_mad_i64_i32 v[96:97], s[52:53], v96, s70, v[140:141]
	v_lshl_add_u64 v[96:97], v[96:97], 0, v[142:143]
	v_mul_f32_e32 v92, v92, v98
	v_mul_f32_e32 v88, v88, v92
	v_add_f32_e32 v92, 1.0, v99
	v_mul_f32_e32 v98, 0xbfb8aa3b, v94
	v_rcp_f32_e32 v92, v92
	v_exp_f32_e32 v98, v98
	v_mul_f32_e32 v99, 0xbfb8aa3b, v95
	v_exp_f32_e32 v99, v99
	v_mul_f32_e32 v92, v93, v92
	v_add_f32_e32 v93, 1.0, v98
	v_rcp_f32_e32 v93, v93
	v_add_f32_e32 v98, 1.0, v99
	v_rcp_f32_e32 v98, v98
	v_mul_f32_e32 v89, v89, v92
	v_mul_f32_e32 v92, v94, v93
	v_mul_f32_e32 v93, 0xbfb8aa3b, v84
	v_exp_f32_e32 v93, v93
	v_mul_f32_e32 v90, v90, v92
	v_mul_f32_e32 v92, v95, v98
	v_mul_f32_e32 v91, v91, v92
	v_cvt_pk_bf16_f32 v88, v88, v89
	v_cvt_pk_bf16_f32 v89, v90, v91
	v_add_f32_e32 v90, 1.0, v93
	v_rcp_f32_e32 v90, v90
	v_mul_f32_e32 v91, 0xbfb8aa3b, v85
	v_exp_f32_e32 v91, v91
	global_store_dwordx2 v[96:97], v[88:89], off
	v_mul_f32_e32 v84, v84, v90
	v_mul_f32_e32 v80, v80, v84
	v_add_f32_e32 v84, 1.0, v91
	v_mul_f32_e32 v88, 0xbfb8aa3b, v86
	v_rcp_f32_e32 v84, v84
	v_exp_f32_e32 v88, v88
	v_mul_f32_e32 v89, 0xbfb8aa3b, v87
	v_exp_f32_e32 v89, v89
	v_mul_f32_e32 v84, v85, v84
	v_add_f32_e32 v85, 1.0, v88
	v_rcp_f32_e32 v85, v85
	v_add_f32_e32 v88, 1.0, v89
	v_rcp_f32_e32 v88, v88
	v_mul_f32_e32 v81, v81, v84
	v_mul_f32_e32 v84, v86, v85
	v_mul_f32_e32 v82, v82, v84
	v_mul_f32_e32 v84, v87, v88
	v_cvt_pk_bf16_f32 v80, v80, v81
	v_mul_f32_e32 v83, v83, v84
	v_cvt_pk_bf16_f32 v81, v82, v83
	global_store_dwordx2 v[96:97], v[80:81], off offset:128
	v_mul_f32_e32 v80, 0xbfb8aa3b, v76
	v_exp_f32_e32 v82, v80
	v_mul_f32_e32 v83, 0xbfb8aa3b, v77
	v_exp_f32_e32 v83, v83
	v_or_b32_e32 v80, 48, v150
	v_add_f32_e32 v82, 1.0, v82
	v_rcp_f32_e32 v82, v82
	v_mad_i64_i32 v[80:81], s[52:53], v80, s70, v[140:141]
	v_lshl_add_u64 v[80:81], v[80:81], 0, v[142:143]
	v_mul_f32_e32 v76, v76, v82
	v_mul_f32_e32 v72, v72, v76
	v_add_f32_e32 v76, 1.0, v83
	v_mul_f32_e32 v82, 0xbfb8aa3b, v78
	v_rcp_f32_e32 v76, v76
	v_exp_f32_e32 v82, v82
	v_mul_f32_e32 v83, 0xbfb8aa3b, v79
	v_exp_f32_e32 v83, v83
	v_mul_f32_e32 v76, v77, v76
	v_add_f32_e32 v77, 1.0, v82
	v_rcp_f32_e32 v77, v77
	v_add_f32_e32 v82, 1.0, v83
	v_rcp_f32_e32 v82, v82
	v_mul_f32_e32 v73, v73, v76
	v_mul_f32_e32 v76, v78, v77
	v_mul_f32_e32 v77, 0xbfb8aa3b, v68
	v_exp_f32_e32 v77, v77
	v_mul_f32_e32 v74, v74, v76
	v_mul_f32_e32 v76, v79, v82
	v_mul_f32_e32 v75, v75, v76
	v_cvt_pk_bf16_f32 v72, v72, v73
	v_cvt_pk_bf16_f32 v73, v74, v75
	v_add_f32_e32 v74, 1.0, v77
	v_rcp_f32_e32 v74, v74
	v_mul_f32_e32 v75, 0xbfb8aa3b, v69
	v_exp_f32_e32 v75, v75
	global_store_dwordx2 v[80:81], v[72:73], off
	v_mul_f32_e32 v68, v68, v74
	v_mul_f32_e32 v64, v64, v68
	v_add_f32_e32 v68, 1.0, v75
	v_mul_f32_e32 v72, 0xbfb8aa3b, v70
	v_rcp_f32_e32 v68, v68
	v_exp_f32_e32 v72, v72
	v_mul_f32_e32 v73, 0xbfb8aa3b, v71
	v_exp_f32_e32 v73, v73
	v_mul_f32_e32 v68, v69, v68
	v_add_f32_e32 v69, 1.0, v72
	v_rcp_f32_e32 v69, v69
	v_add_f32_e32 v72, 1.0, v73
	v_rcp_f32_e32 v72, v72
	v_mul_f32_e32 v65, v65, v68
	v_mul_f32_e32 v68, v70, v69
	v_mul_f32_e32 v66, v66, v68
	v_mul_f32_e32 v68, v71, v72
	v_cvt_pk_bf16_f32 v64, v64, v65
	v_mul_f32_e32 v67, v67, v68
	v_cvt_pk_bf16_f32 v65, v66, v67
	global_store_dwordx2 v[80:81], v[64:65], off offset:128
	v_mov_b32_e32 v216, v140
	v_mov_b32_e32 v217, v141
	v_mov_b32_e32 v218, v142
	v_mov_b32_e32 v219, v143
	v_mov_b32_e32 v220, v150
	s_andn2_b64 vcc, exec, s[0:1]
	s_cbranch_vccnz .Lov_nb_7
	s_barrier
.Lov_nb_7:
	s_mov_b32 s71, s18
	s_mov_b32 s48, s36
	s_mov_b64 s[54:55], s[46:47]
	s_mov_b64 s[52:53], s[44:45]
	s_add_i32 s65, s65, 1
	s_mul_i32 s10, s65, s21
	s_mul_hi_u32 s11, s65, s20
	s_add_i32 s11, s11, s10
	s_mul_i32 s10, s65, s20
	s_add_u32 s44, s10, s2
	s_addc_u32 s45, s11, s3
	v_cmp_gt_i64_e32 vcc, s[44:45], v[138:139]
	v_cmp_lt_i64_e64 s[10:11], s[44:45], v[136:137]
	s_cbranch_vccnz .LBB0_950_ov7
	s_lshr_b32 s18, s44, 3
	s_and_b32 s36, s44, 7
	s_lshl_b32 s36, s36, 1
	s_cmp_ge_u32 s18, 0xb0
	s_cbranch_scc0 .Ldec_7_ov7
	s_sub_u32 s18, s18, 0xb0
	s_add_u32 s36, s36, 1

.LBB0_950_ov7:
	s_ashr_i32 s37, s36, 31
	s_lshl_b64 s[44:45], s[36:37], 19
	s_add_u32 s44, s80, s44
	s_addc_u32 s45, s81, s45
	s_and_b64 s[46:47], s[10:11], exec
	s_cselect_b32 s37, s45, s53
	s_cselect_b32 s72, s44, s52
	s_ashr_i32 s19, s18, 31
	s_lshl_b64 s[46:47], s[18:19], 19
	s_add_u32 s46, s58, s46
	s_addc_u32 s47, s59, s47
	s_and_b64 s[56:57], s[10:11], exec
	s_cselect_b32 s19, s47, s55
	s_cselect_b32 s73, s46, s54
	s_add_u32 s52, s52, 0x40080
	s_addc_u32 s53, s53, 0
	s_add_u32 s74, s54, 0x100
	s_addc_u32 s75, s55, 0
	s_mov_b32 s76, -2
	ds_read_b128 v[140:143], v147
	ds_read_b128 v[150:153], v147 offset:1024
	ds_read_b128 v[154:157], v147 offset:2048
	ds_read_b128 v[158:161], v147 offset:3072
	ds_read_b128 v[162:165], v148
	ds_read_b128 v[166:169], v148 offset:1024
	ds_read_b128 v[170:173], v148 offset:2048
	ds_read_b128 v[174:177], v148 offset:3072
	s_add_u32 s54, s52, 0xfffc0080
	s_addc_u32 s55, s53, -1
	s_cmp_eq_u32 s76, 12
	s_cselect_b32 s57, s37, s55
	s_cselect_b32 s56, s72, s54
	s_cselect_b32 s55, s19, s75
	s_cselect_b32 s54, s73, s74
	v_lshl_add_u64 v[178:179], s[52:53], 0, v[132:133]
	s_add_i32 m0, s49, 0xc000
	ds_read_b128 v[184:187], v149
	ds_read_b128 v[188:191], v149 offset:1024
	ds_read_b128 v[192:195], v149 offset:2048
	ds_read_b128 v[196:199], v149 offset:3072
	ds_read_b128 v[200:203], v149 offset:4096
	ds_read_b128 v[204:207], v149 offset:5120
	ds_read_b128 v[208:211], v149 offset:6144
	ds_read_b128 v[212:215], v149 offset:7168
	global_load_lds_dwordx4 v[178:179], off
	v_lshl_add_u64 v[178:179], s[52:53], 0, v[134:135]
	s_add_i32 m0, s49, 0xe000
	s_nop 0
	global_load_lds_dwordx4 v[178:179], off
	s_waitcnt vmcnt(8)
	s_waitcnt lgkmcnt(0)
	s_barrier
	s_setprio 1
	s_waitcnt lgkmcnt(0)
	v_mfma_f32_16x16x32_bf16 v[124:127], v[140:143], v[184:187], 0
	v_mul_f32_e32 v222, 0xbfb8aa3b, v60
	v_exp_f32_e32 v224, v222
	v_mul_f32_e32 v225, 0xbfb8aa3b, v61
	v_exp_f32_e32 v225, v225
	v_add_u32_e32 v222, 0x80, v220
	v_add_f32_e32 v224, 1.0, v224
	v_rcp_f32_e32 v224, v224
	v_mad_i64_i32 v[222:223], vcc, v222, s70, v[216:217]
	v_mfma_f32_16x16x32_bf16 v[124:127], v[150:153], v[188:191], v[124:127]
	v_lshl_add_u64 v[222:223], v[222:223], 0, v[218:219]
	v_mul_f32_e32 v60, v60, v224
	v_mul_f32_e32 v56, v56, v60
	v_add_f32_e32 v60, 1.0, v225
	v_mul_f32_e32 v224, 0xbfb8aa3b, v62
	v_rcp_f32_e32 v60, v60
	v_exp_f32_e32 v224, v224
	v_mul_f32_e32 v225, 0xbfb8aa3b, v63
	v_mfma_f32_16x16x32_bf16 v[120:123], v[154:157], v[184:187], 0
	v_exp_f32_e32 v225, v225
	v_mul_f32_e32 v60, v61, v60
	v_add_f32_e32 v61, 1.0, v224
	v_rcp_f32_e32 v61, v61
	v_add_f32_e32 v224, 1.0, v225
	v_rcp_f32_e32 v224, v224
	v_mul_f32_e32 v57, v57, v60
	v_mul_f32_e32 v60, v62, v61
	v_mfma_f32_16x16x32_bf16 v[120:123], v[158:161], v[188:191], v[120:123]
	v_mul_f32_e32 v61, 0xbfb8aa3b, v52
	v_exp_f32_e32 v61, v61
	v_mul_f32_e32 v58, v58, v60
	v_mul_f32_e32 v60, v63, v224
	v_mul_f32_e32 v59, v59, v60
	v_cvt_pk_bf16_f32 v56, v56, v57
	v_cvt_pk_bf16_f32 v57, v58, v59
	v_add_f32_e32 v58, 1.0, v61
	v_mfma_f32_16x16x32_bf16 v[108:111], v[140:143], v[192:195], 0
	v_rcp_f32_e32 v58, v58
	v_mul_f32_e32 v59, 0xbfb8aa3b, v53
	v_exp_f32_e32 v59, v59
	global_store_dwordx2 v[222:223], v[56:57], off
	v_mul_f32_e32 v52, v52, v58
	v_mul_f32_e32 v48, v48, v52
	v_add_f32_e32 v52, 1.0, v59
	v_mul_f32_e32 v56, 0xbfb8aa3b, v54
	v_mfma_f32_16x16x32_bf16 v[108:111], v[150:153], v[196:199], v[108:111]
	v_rcp_f32_e32 v52, v52
	v_exp_f32_e32 v56, v56
	v_mul_f32_e32 v57, 0xbfb8aa3b, v55
	v_exp_f32_e32 v57, v57
	v_mul_f32_e32 v52, v53, v52
	v_add_f32_e32 v53, 1.0, v56
	v_rcp_f32_e32 v53, v53
	v_add_f32_e32 v56, 1.0, v57
	v_mfma_f32_16x16x32_bf16 v[104:107], v[154:157], v[192:195], 0
	v_rcp_f32_e32 v56, v56
	v_mul_f32_e32 v49, v49, v52
	v_mul_f32_e32 v52, v54, v53
	v_mul_f32_e32 v50, v50, v52
	v_mul_f32_e32 v52, v55, v56
	v_cvt_pk_bf16_f32 v48, v48, v49
	v_mul_f32_e32 v51, v51, v52
	v_cvt_pk_bf16_f32 v49, v50, v51
	v_mfma_f32_16x16x32_bf16 v[104:107], v[158:161], v[196:199], v[104:107]
	global_store_dwordx2 v[222:223], v[48:49], off offset:128
	v_mul_f32_e32 v48, 0xbfb8aa3b, v44
	v_exp_f32_e32 v50, v48
	v_mul_f32_e32 v51, 0xbfb8aa3b, v45
	v_exp_f32_e32 v51, v51
	v_add_u32_e32 v48, 0x90, v220
	v_add_f32_e32 v50, 1.0, v50
	v_rcp_f32_e32 v50, v50
	v_mfma_f32_16x16x32_bf16 v[92:95], v[140:143], v[200:203], 0
	v_mad_i64_i32 v[48:49], vcc, v48, s70, v[216:217]
	v_lshl_add_u64 v[48:49], v[48:49], 0, v[218:219]
	v_mul_f32_e32 v44, v44, v50
	v_mul_f32_e32 v40, v40, v44
	v_add_f32_e32 v44, 1.0, v51
	v_mul_f32_e32 v50, 0xbfb8aa3b, v46
	v_rcp_f32_e32 v44, v44
	v_exp_f32_e32 v50, v50
	v_mfma_f32_16x16x32_bf16 v[92:95], v[150:153], v[204:207], v[92:95]
	v_mul_f32_e32 v51, 0xbfb8aa3b, v47
	v_exp_f32_e32 v51, v51
	v_mul_f32_e32 v44, v45, v44
	v_add_f32_e32 v45, 1.0, v50
	v_rcp_f32_e32 v45, v45
	v_add_f32_e32 v50, 1.0, v51
	v_rcp_f32_e32 v50, v50
	v_mul_f32_e32 v41, v41, v44
	v_mfma_f32_16x16x32_bf16 v[88:91], v[154:157], v[200:203], 0
	v_mul_f32_e32 v44, v46, v45
	v_mul_f32_e32 v45, 0xbfb8aa3b, v36
	v_exp_f32_e32 v45, v45
	v_mul_f32_e32 v42, v42, v44
	v_mul_f32_e32 v44, v47, v50
	v_mul_f32_e32 v43, v43, v44
	v_cvt_pk_bf16_f32 v40, v40, v41
	v_cvt_pk_bf16_f32 v41, v42, v43
	v_mfma_f32_16x16x32_bf16 v[88:91], v[158:161], v[204:207], v[88:91]
	v_add_f32_e32 v42, 1.0, v45
	v_rcp_f32_e32 v42, v42
	v_mul_f32_e32 v43, 0xbfb8aa3b, v37
	v_exp_f32_e32 v43, v43
	global_store_dwordx2 v[48:49], v[40:41], off
	v_mul_f32_e32 v36, v36, v42
	v_mul_f32_e32 v32, v32, v36
	v_add_f32_e32 v36, 1.0, v43
	v_mfma_f32_16x16x32_bf16 v[76:79], v[140:143], v[208:211], 0
	v_mul_f32_e32 v40, 0xbfb8aa3b, v38
	v_rcp_f32_e32 v36, v36
	v_exp_f32_e32 v40, v40
	v_mul_f32_e32 v41, 0xbfb8aa3b, v39
	v_exp_f32_e32 v41, v41
	v_mul_f32_e32 v36, v37, v36
	v_add_f32_e32 v37, 1.0, v40
	v_rcp_f32_e32 v37, v37
	v_mfma_f32_16x16x32_bf16 v[76:79], v[150:153], v[212:215], v[76:79]
	v_add_f32_e32 v40, 1.0, v41
	v_rcp_f32_e32 v40, v40
	v_mul_f32_e32 v33, v33, v36
	v_mul_f32_e32 v36, v38, v37
	v_mul_f32_e32 v34, v34, v36
	v_mul_f32_e32 v36, v39, v40
	v_cvt_pk_bf16_f32 v32, v32, v33
	v_mul_f32_e32 v35, v35, v36
	v_mfma_f32_16x16x32_bf16 v[72:75], v[154:157], v[208:211], 0
	v_cvt_pk_bf16_f32 v33, v34, v35
	global_store_dwordx2 v[48:49], v[32:33], off offset:128
	v_mul_f32_e32 v32, 0xbfb8aa3b, v28
	v_exp_f32_e32 v34, v32
	v_mul_f32_e32 v35, 0xbfb8aa3b, v29
	v_exp_f32_e32 v35, v35
	v_add_u32_e32 v32, 0xa0, v220
	v_add_f32_e32 v34, 1.0, v34
	v_mfma_f32_16x16x32_bf16 v[72:75], v[158:161], v[212:215], v[72:75]
	v_rcp_f32_e32 v34, v34
	v_mad_i64_i32 v[32:33], vcc, v32, s70, v[216:217]
	v_lshl_add_u64 v[32:33], v[32:33], 0, v[218:219]
	v_mul_f32_e32 v28, v28, v34
	v_mul_f32_e32 v24, v24, v28
	v_add_f32_e32 v28, 1.0, v35
	v_mul_f32_e32 v34, 0xbfb8aa3b, v30
	v_rcp_f32_e32 v28, v28
	v_mfma_f32_16x16x32_bf16 v[116:119], v[162:165], v[184:187], 0
	v_exp_f32_e32 v34, v34
	v_mul_f32_e32 v35, 0xbfb8aa3b, v31
	v_exp_f32_e32 v35, v35
	v_mul_f32_e32 v28, v29, v28
	v_add_f32_e32 v29, 1.0, v34
	v_rcp_f32_e32 v29, v29
	v_add_f32_e32 v34, 1.0, v35
	v_rcp_f32_e32 v34, v34
	v_mfma_f32_16x16x32_bf16 v[116:119], v[166:169], v[188:191], v[116:119]
	v_mul_f32_e32 v25, v25, v28
	v_mul_f32_e32 v28, v30, v29
	v_mul_f32_e32 v29, 0xbfb8aa3b, v20
	v_exp_f32_e32 v29, v29
	v_mul_f32_e32 v26, v26, v28
	v_mul_f32_e32 v28, v31, v34
	v_mul_f32_e32 v27, v27, v28
	v_cvt_pk_bf16_f32 v24, v24, v25
	v_mfma_f32_16x16x32_bf16 v[112:115], v[170:173], v[184:187], 0
	v_cvt_pk_bf16_f32 v25, v26, v27
	v_add_f32_e32 v26, 1.0, v29
	v_rcp_f32_e32 v26, v26
	v_mul_f32_e32 v27, 0xbfb8aa3b, v21
	v_exp_f32_e32 v27, v27
	global_store_dwordx2 v[32:33], v[24:25], off
	v_mul_f32_e32 v20, v20, v26
	v_mul_f32_e32 v16, v16, v20
	v_mfma_f32_16x16x32_bf16 v[112:115], v[174:177], v[188:191], v[112:115]
	v_add_f32_e32 v20, 1.0, v27
	v_mul_f32_e32 v24, 0xbfb8aa3b, v22
	v_rcp_f32_e32 v20, v20
	v_exp_f32_e32 v24, v24
	v_mul_f32_e32 v25, 0xbfb8aa3b, v23
	v_exp_f32_e32 v25, v25
	v_mul_f32_e32 v20, v21, v20
	v_add_f32_e32 v21, 1.0, v24
	v_mfma_f32_16x16x32_bf16 v[100:103], v[162:165], v[192:195], 0
	v_rcp_f32_e32 v21, v21
	v_add_f32_e32 v24, 1.0, v25
	v_rcp_f32_e32 v24, v24
	v_mul_f32_e32 v17, v17, v20
	v_mul_f32_e32 v20, v22, v21
	v_mul_f32_e32 v18, v18, v20
	v_mul_f32_e32 v20, v23, v24
	v_cvt_pk_bf16_f32 v16, v16, v17
	v_mfma_f32_16x16x32_bf16 v[100:103], v[166:169], v[196:199], v[100:103]
	v_mul_f32_e32 v19, v19, v20
	v_cvt_pk_bf16_f32 v17, v18, v19
	global_store_dwordx2 v[32:33], v[16:17], off offset:128
	v_mul_f32_e32 v16, 0xbfb8aa3b, v12
	v_exp_f32_e32 v18, v16
	v_mul_f32_e32 v19, 0xbfb8aa3b, v13
	v_exp_f32_e32 v19, v19
	v_add_u32_e32 v16, 0xb0, v220
	v_mfma_f32_16x16x32_bf16 v[96:99], v[170:173], v[192:195], 0
	v_add_f32_e32 v18, 1.0, v18
	v_rcp_f32_e32 v18, v18
	v_mad_i64_i32 v[16:17], vcc, v16, s70, v[216:217]
	v_lshl_add_u64 v[16:17], v[16:17], 0, v[218:219]
	v_mul_f32_e32 v12, v12, v18
	v_mul_f32_e32 v8, v8, v12
	v_add_f32_e32 v12, 1.0, v19
	v_mul_f32_e32 v18, 0xbfb8aa3b, v14
	v_mfma_f32_16x16x32_bf16 v[96:99], v[174:177], v[196:199], v[96:99]
	v_rcp_f32_e32 v12, v12
	v_exp_f32_e32 v18, v18
	v_mul_f32_e32 v19, 0xbfb8aa3b, v15
	v_exp_f32_e32 v19, v19
	v_mul_f32_e32 v12, v13, v12
	v_add_f32_e32 v13, 1.0, v18
	v_rcp_f32_e32 v13, v13
	v_add_f32_e32 v18, 1.0, v19
	v_mfma_f32_16x16x32_bf16 v[84:87], v[162:165], v[200:203], 0
	v_rcp_f32_e32 v18, v18
	v_mul_f32_e32 v9, v9, v12
	v_mul_f32_e32 v12, v14, v13
	v_mul_f32_e32 v13, 0xbfb8aa3b, v4
	v_exp_f32_e32 v13, v13
	v_mul_f32_e32 v10, v10, v12
	v_mul_f32_e32 v12, v15, v18
	v_mul_f32_e32 v11, v11, v12
	v_mfma_f32_16x16x32_bf16 v[84:87], v[166:169], v[204:207], v[84:87]
	v_cvt_pk_bf16_f32 v8, v8, v9
	v_cvt_pk_bf16_f32 v9, v10, v11
	v_add_f32_e32 v10, 1.0, v13
	v_rcp_f32_e32 v10, v10
	v_mul_f32_e32 v11, 0xbfb8aa3b, v5
	v_exp_f32_e32 v11, v11
	global_store_dwordx2 v[16:17], v[8:9], off
	v_mul_f32_e32 v4, v4, v10
	v_mfma_f32_16x16x32_bf16 v[80:83], v[170:173], v[200:203], 0
	v_mul_f32_e32 v0, v0, v4
	v_add_f32_e32 v4, 1.0, v11
	v_mul_f32_e32 v8, 0xbfb8aa3b, v6
	v_rcp_f32_e32 v4, v4
	v_exp_f32_e32 v8, v8
	v_mul_f32_e32 v9, 0xbfb8aa3b, v7
	v_exp_f32_e32 v9, v9
	v_mul_f32_e32 v4, v5, v4
	v_mfma_f32_16x16x32_bf16 v[80:83], v[174:177], v[204:207], v[80:83]
	v_add_f32_e32 v5, 1.0, v8
	v_rcp_f32_e32 v5, v5
	v_add_f32_e32 v8, 1.0, v9
	v_rcp_f32_e32 v8, v8
	v_mul_f32_e32 v1, v1, v4
	v_mul_f32_e32 v4, v6, v5
	v_mul_f32_e32 v2, v2, v4
	v_mul_f32_e32 v4, v7, v8
	v_mfma_f32_16x16x32_bf16 v[68:71], v[162:165], v[208:211], 0
	v_mul_f32_e32 v3, v3, v4
	v_cvt_pk_bf16_f32 v0, v0, v1
	v_cvt_pk_bf16_f32 v1, v2, v3
	global_store_dwordx2 v[16:17], v[0:1], off offset:128
	v_mfma_f32_16x16x32_bf16 v[68:71], v[166:169], v[212:215], v[68:71]
	v_mfma_f32_16x16x32_bf16 v[64:67], v[170:173], v[208:211], 0
	v_mfma_f32_16x16x32_bf16 v[64:67], v[174:177], v[212:215], v[64:67]
	s_setprio 0
	s_barrier
	s_add_i32 s77, s68, s60
	v_lshl_add_u64 v[178:179], s[54:55], 0, v[130:131]
	s_mov_b32 m0, s77
	ds_read_b128 v[184:187], v149 offset:16384
	ds_read_b128 v[188:191], v149 offset:17408
	ds_read_b128 v[192:195], v149 offset:18432
	ds_read_b128 v[196:199], v149 offset:19456
	ds_read_b128 v[200:203], v149 offset:20480
	ds_read_b128 v[204:207], v149 offset:21504
	ds_read_b128 v[208:211], v149 offset:22528
	ds_read_b128 v[212:215], v149 offset:23552
	global_load_lds_dwordx4 v[178:179], off
	s_add_i32 m0, s77, 0x2000
	s_add_u32 s82, s54, 0x40000
	v_lshl_add_u64 v[216:217], s[54:55], 0, v[128:129]
	s_addc_u32 s83, s55, 0
	s_add_i32 s77, s69, s60
	global_load_lds_dwordx4 v[216:217], off
	v_lshl_add_u64 v[218:219], s[82:83], 0, v[130:131]
	s_mov_b32 m0, s77
	v_lshl_add_u64 v[220:221], s[56:57], 0, v[128:129]
	global_load_lds_dwordx4 v[218:219], off
	v_lshl_add_u64 v[218:219], s[82:83], 0, v[128:129]
	s_add_i32 m0, s77, 0x2000
	s_nop 0
	global_load_lds_dwordx4 v[218:219], off
	v_lshl_add_u64 v[218:219], s[56:57], 0, v[130:131]
	s_mov_b32 m0, s49
	s_nop 0
	global_load_lds_dwordx4 v[218:219], off
	s_mov_b32 m0, s62
	s_nop 0
	global_load_lds_dwordx4 v[220:221], off
	s_waitcnt vmcnt(8)
	s_waitcnt lgkmcnt(0)
	s_barrier
	s_setprio 1
	s_waitcnt lgkmcnt(0)
	v_mfma_f32_16x16x32_bf16 v[60:63], v[140:143], v[184:187], 0
	v_mfma_f32_16x16x32_bf16 v[60:63], v[150:153], v[188:191], v[60:63]
	v_mfma_f32_16x16x32_bf16 v[56:59], v[154:157], v[184:187], 0
	v_mfma_f32_16x16x32_bf16 v[56:59], v[158:161], v[188:191], v[56:59]
	v_mfma_f32_16x16x32_bf16 v[44:47], v[140:143], v[192:195], 0
	v_mfma_f32_16x16x32_bf16 v[44:47], v[150:153], v[196:199], v[44:47]
	v_mfma_f32_16x16x32_bf16 v[40:43], v[154:157], v[192:195], 0
	v_mfma_f32_16x16x32_bf16 v[40:43], v[158:161], v[196:199], v[40:43]
	v_mfma_f32_16x16x32_bf16 v[28:31], v[140:143], v[200:203], 0
	v_mfma_f32_16x16x32_bf16 v[28:31], v[150:153], v[204:207], v[28:31]
	v_mfma_f32_16x16x32_bf16 v[24:27], v[154:157], v[200:203], 0
	v_mfma_f32_16x16x32_bf16 v[24:27], v[158:161], v[204:207], v[24:27]
	v_mfma_f32_16x16x32_bf16 v[12:15], v[140:143], v[208:211], 0
	v_mfma_f32_16x16x32_bf16 v[12:15], v[150:153], v[212:215], v[12:15]
	v_mfma_f32_16x16x32_bf16 v[8:11], v[154:157], v[208:211], 0
	v_mfma_f32_16x16x32_bf16 v[8:11], v[158:161], v[212:215], v[8:11]
	v_mfma_f32_16x16x32_bf16 v[52:55], v[162:165], v[184:187], 0
	v_mfma_f32_16x16x32_bf16 v[52:55], v[166:169], v[188:191], v[52:55]
	v_mfma_f32_16x16x32_bf16 v[48:51], v[170:173], v[184:187], 0
	v_mfma_f32_16x16x32_bf16 v[48:51], v[174:177], v[188:191], v[48:51]
	v_mfma_f32_16x16x32_bf16 v[36:39], v[162:165], v[192:195], 0
	v_mfma_f32_16x16x32_bf16 v[36:39], v[166:169], v[196:199], v[36:39]
	v_mfma_f32_16x16x32_bf16 v[32:35], v[170:173], v[192:195], 0
	v_mfma_f32_16x16x32_bf16 v[32:35], v[174:177], v[196:199], v[32:35]
	v_mfma_f32_16x16x32_bf16 v[20:23], v[162:165], v[200:203], 0
	v_mfma_f32_16x16x32_bf16 v[20:23], v[166:169], v[204:207], v[20:23]
	v_mfma_f32_16x16x32_bf16 v[16:19], v[170:173], v[200:203], 0
	v_mfma_f32_16x16x32_bf16 v[16:19], v[174:177], v[204:207], v[16:19]
	v_mfma_f32_16x16x32_bf16 v[4:7], v[162:165], v[208:211], 0
	v_mfma_f32_16x16x32_bf16 v[4:7], v[166:169], v[212:215], v[4:7]
	v_mfma_f32_16x16x32_bf16 v[0:3], v[170:173], v[208:211], 0
	v_mfma_f32_16x16x32_bf16 v[0:3], v[174:177], v[212:215], v[0:3]
	s_setprio 0
	s_barrier
	s_branch .Lmid_gemm7

.LBB0_954:
	s_and_b64 vcc, exec, s[10:11]
	s_cbranch_vccnz .Lov_7
	v_mul_f32_e32 v151, 0xbfb8aa3b, v124
	v_exp_f32_e32 v151, v151
	v_mul_f32_e32 v154, 0xbfb8aa3b, v125
	v_exp_f32_e32 v154, v154
	v_lshl_or_b32 v142, s71, 7, v146
	v_add_f32_e32 v151, 1.0, v151
	v_rcp_f32_e32 v151, v151
	v_lshl_add_u32 v150, s48, 8, v144
	v_ashrrev_i32_e32 v143, 31, v142
	v_mov_b64_e32 v[140:141], s[22:23]
	v_mul_f32_e32 v124, v124, v151
	v_mul_f32_e32 v120, v120, v124
	v_add_f32_e32 v124, 1.0, v154
	v_mul_f32_e32 v151, 0xbfb8aa3b, v126
	v_rcp_f32_e32 v124, v124
	v_exp_f32_e32 v151, v151
	v_mul_f32_e32 v154, 0xbfb8aa3b, v127
	v_exp_f32_e32 v154, v154
	v_mul_f32_e32 v124, v125, v124
	v_add_f32_e32 v125, 1.0, v151
	v_rcp_f32_e32 v125, v125
	v_add_f32_e32 v151, 1.0, v154
	v_rcp_f32_e32 v151, v151
	v_mul_f32_e32 v121, v121, v124
	v_mul_f32_e32 v124, v126, v125
	v_mul_f32_e32 v125, 0xbfb8aa3b, v116
	v_exp_f32_e32 v125, v125
	v_mul_f32_e32 v122, v122, v124
	v_mul_f32_e32 v124, v127, v151
	v_mul_f32_e32 v123, v123, v124
	v_cvt_pk_bf16_f32 v120, v120, v121
	v_cvt_pk_bf16_f32 v121, v122, v123
	v_add_f32_e32 v122, 1.0, v125
	v_rcp_f32_e32 v122, v122
	v_mul_f32_e32 v123, 0xbfb8aa3b, v117
	v_exp_f32_e32 v123, v123
	v_mad_i64_i32 v[152:153], s[52:53], v150, s70, v[140:141]
	v_lshlrev_b64 v[142:143], 1, v[142:143]
	v_lshl_add_u64 v[152:153], v[152:153], 0, v[142:143]
	v_mul_f32_e32 v116, v116, v122
	global_store_dwordx2 v[152:153], v[120:121], off
	v_mul_f32_e32 v112, v112, v116
	v_add_f32_e32 v116, 1.0, v123
	v_mul_f32_e32 v120, 0xbfb8aa3b, v118
	v_rcp_f32_e32 v116, v116
	v_exp_f32_e32 v120, v120
	v_mul_f32_e32 v121, 0xbfb8aa3b, v119
	v_exp_f32_e32 v121, v121
	v_mul_f32_e32 v116, v117, v116
	v_add_f32_e32 v117, 1.0, v120
	v_rcp_f32_e32 v117, v117
	v_add_f32_e32 v120, 1.0, v121
	v_rcp_f32_e32 v120, v120
	v_mul_f32_e32 v113, v113, v116
	v_mul_f32_e32 v116, v118, v117
	v_mul_f32_e32 v114, v114, v116
	v_mul_f32_e32 v116, v119, v120
	v_cvt_pk_bf16_f32 v112, v112, v113
	v_mul_f32_e32 v115, v115, v116
	v_cvt_pk_bf16_f32 v113, v114, v115
	global_store_dwordx2 v[152:153], v[112:113], off offset:128
	v_mul_f32_e32 v112, 0xbfb8aa3b, v108
	v_exp_f32_e32 v114, v112
	v_mul_f32_e32 v115, 0xbfb8aa3b, v109
	v_exp_f32_e32 v115, v115
	v_or_b32_e32 v112, 16, v150
	v_add_f32_e32 v114, 1.0, v114
	v_rcp_f32_e32 v114, v114
	v_mad_i64_i32 v[112:113], s[52:53], v112, s70, v[140:141]
	v_lshl_add_u64 v[112:113], v[112:113], 0, v[142:143]
	v_mul_f32_e32 v108, v108, v114
	v_mul_f32_e32 v104, v104, v108
	v_add_f32_e32 v108, 1.0, v115
	v_mul_f32_e32 v114, 0xbfb8aa3b, v110
	v_rcp_f32_e32 v108, v108
	v_exp_f32_e32 v114, v114
	v_mul_f32_e32 v115, 0xbfb8aa3b, v111
	v_exp_f32_e32 v115, v115
	v_mul_f32_e32 v108, v109, v108
	v_add_f32_e32 v109, 1.0, v114
	v_rcp_f32_e32 v109, v109
	v_add_f32_e32 v114, 1.0, v115
	v_rcp_f32_e32 v114, v114
	v_mul_f32_e32 v105, v105, v108
	v_mul_f32_e32 v108, v110, v109
	v_mul_f32_e32 v109, 0xbfb8aa3b, v100
	v_exp_f32_e32 v109, v109
	v_mul_f32_e32 v106, v106, v108
	v_mul_f32_e32 v108, v111, v114
	v_mul_f32_e32 v107, v107, v108
	v_cvt_pk_bf16_f32 v104, v104, v105
	v_cvt_pk_bf16_f32 v105, v106, v107
	v_add_f32_e32 v106, 1.0, v109
	v_rcp_f32_e32 v106, v106
	v_mul_f32_e32 v107, 0xbfb8aa3b, v101
	v_exp_f32_e32 v107, v107
	global_store_dwordx2 v[112:113], v[104:105], off
	v_mul_f32_e32 v100, v100, v106
	v_mul_f32_e32 v96, v96, v100
	v_add_f32_e32 v100, 1.0, v107
	v_mul_f32_e32 v104, 0xbfb8aa3b, v102
	v_rcp_f32_e32 v100, v100
	v_exp_f32_e32 v104, v104
	v_mul_f32_e32 v105, 0xbfb8aa3b, v103
	v_exp_f32_e32 v105, v105
	v_mul_f32_e32 v100, v101, v100
	v_add_f32_e32 v101, 1.0, v104
	v_rcp_f32_e32 v101, v101
	v_add_f32_e32 v104, 1.0, v105
	v_rcp_f32_e32 v104, v104
	v_mul_f32_e32 v97, v97, v100
	v_mul_f32_e32 v100, v102, v101
	v_mul_f32_e32 v98, v98, v100
	v_mul_f32_e32 v100, v103, v104
	v_cvt_pk_bf16_f32 v96, v96, v97
	v_mul_f32_e32 v99, v99, v100
	v_cvt_pk_bf16_f32 v97, v98, v99
	global_store_dwordx2 v[112:113], v[96:97], off offset:128
	v_mul_f32_e32 v96, 0xbfb8aa3b, v92
	v_exp_f32_e32 v98, v96
	v_mul_f32_e32 v99, 0xbfb8aa3b, v93
	v_exp_f32_e32 v99, v99
	v_or_b32_e32 v96, 32, v150
	v_add_f32_e32 v98, 1.0, v98
	v_rcp_f32_e32 v98, v98
	v_mad_i64_i32 v[96:97], s[52:53], v96, s70, v[140:141]
	v_lshl_add_u64 v[96:97], v[96:97], 0, v[142:143]
	v_mul_f32_e32 v92, v92, v98
	v_mul_f32_e32 v88, v88, v92
	v_add_f32_e32 v92, 1.0, v99
	v_mul_f32_e32 v98, 0xbfb8aa3b, v94
	v_rcp_f32_e32 v92, v92
	v_exp_f32_e32 v98, v98
	v_mul_f32_e32 v99, 0xbfb8aa3b, v95
	v_exp_f32_e32 v99, v99
	v_mul_f32_e32 v92, v93, v92
	v_add_f32_e32 v93, 1.0, v98
	v_rcp_f32_e32 v93, v93
	v_add_f32_e32 v98, 1.0, v99
	v_rcp_f32_e32 v98, v98
	v_mul_f32_e32 v89, v89, v92
	v_mul_f32_e32 v92, v94, v93
	v_mul_f32_e32 v93, 0xbfb8aa3b, v84
	v_exp_f32_e32 v93, v93
	v_mul_f32_e32 v90, v90, v92
	v_mul_f32_e32 v92, v95, v98
	v_mul_f32_e32 v91, v91, v92
	v_cvt_pk_bf16_f32 v88, v88, v89
	v_cvt_pk_bf16_f32 v89, v90, v91
	v_add_f32_e32 v90, 1.0, v93
	v_rcp_f32_e32 v90, v90
	v_mul_f32_e32 v91, 0xbfb8aa3b, v85
	v_exp_f32_e32 v91, v91
	global_store_dwordx2 v[96:97], v[88:89], off
	v_mul_f32_e32 v84, v84, v90
	v_mul_f32_e32 v80, v80, v84
	v_add_f32_e32 v84, 1.0, v91
	v_mul_f32_e32 v88, 0xbfb8aa3b, v86
	v_rcp_f32_e32 v84, v84
	v_exp_f32_e32 v88, v88
	v_mul_f32_e32 v89, 0xbfb8aa3b, v87
	v_exp_f32_e32 v89, v89
	v_mul_f32_e32 v84, v85, v84
	v_add_f32_e32 v85, 1.0, v88
	v_rcp_f32_e32 v85, v85
	v_add_f32_e32 v88, 1.0, v89
	v_rcp_f32_e32 v88, v88
	v_mul_f32_e32 v81, v81, v84
	v_mul_f32_e32 v84, v86, v85
	v_mul_f32_e32 v82, v82, v84
	v_mul_f32_e32 v84, v87, v88
	v_cvt_pk_bf16_f32 v80, v80, v81
	v_mul_f32_e32 v83, v83, v84
	v_cvt_pk_bf16_f32 v81, v82, v83
	global_store_dwordx2 v[96:97], v[80:81], off offset:128
	v_mul_f32_e32 v80, 0xbfb8aa3b, v76
	v_exp_f32_e32 v82, v80
	v_mul_f32_e32 v83, 0xbfb8aa3b, v77
	v_exp_f32_e32 v83, v83
	v_or_b32_e32 v80, 48, v150
	v_add_f32_e32 v82, 1.0, v82
	v_rcp_f32_e32 v82, v82
	v_mad_i64_i32 v[80:81], s[52:53], v80, s70, v[140:141]
	v_lshl_add_u64 v[80:81], v[80:81], 0, v[142:143]
	v_mul_f32_e32 v76, v76, v82
	v_mul_f32_e32 v72, v72, v76
	v_add_f32_e32 v76, 1.0, v83
	v_mul_f32_e32 v82, 0xbfb8aa3b, v78
	v_rcp_f32_e32 v76, v76
	v_exp_f32_e32 v82, v82
	v_mul_f32_e32 v83, 0xbfb8aa3b, v79
	v_exp_f32_e32 v83, v83
	v_mul_f32_e32 v76, v77, v76
	v_add_f32_e32 v77, 1.0, v82
	v_rcp_f32_e32 v77, v77
	v_add_f32_e32 v82, 1.0, v83
	v_rcp_f32_e32 v82, v82
	v_mul_f32_e32 v73, v73, v76
	v_mul_f32_e32 v76, v78, v77
	v_mul_f32_e32 v77, 0xbfb8aa3b, v68
	v_exp_f32_e32 v77, v77
	v_mul_f32_e32 v74, v74, v76
	v_mul_f32_e32 v76, v79, v82
	v_mul_f32_e32 v75, v75, v76
	v_cvt_pk_bf16_f32 v72, v72, v73
	v_cvt_pk_bf16_f32 v73, v74, v75
	v_add_f32_e32 v74, 1.0, v77
	v_rcp_f32_e32 v74, v74
	v_mul_f32_e32 v75, 0xbfb8aa3b, v69
	v_exp_f32_e32 v75, v75
	global_store_dwordx2 v[80:81], v[72:73], off
	v_mul_f32_e32 v68, v68, v74
	v_mul_f32_e32 v64, v64, v68
	v_add_f32_e32 v68, 1.0, v75
	v_mul_f32_e32 v72, 0xbfb8aa3b, v70
	v_rcp_f32_e32 v68, v68
	v_exp_f32_e32 v72, v72
	v_mul_f32_e32 v73, 0xbfb8aa3b, v71
	v_exp_f32_e32 v73, v73
	v_mul_f32_e32 v68, v69, v68
	v_add_f32_e32 v69, 1.0, v72
	v_rcp_f32_e32 v69, v69
	v_add_f32_e32 v72, 1.0, v73
	v_rcp_f32_e32 v72, v72
	v_mul_f32_e32 v65, v65, v68
	v_mul_f32_e32 v68, v70, v69
	v_mul_f32_e32 v66, v66, v68
	v_mul_f32_e32 v68, v71, v72
	v_cvt_pk_bf16_f32 v64, v64, v65
	v_mul_f32_e32 v67, v67, v68
	v_cvt_pk_bf16_f32 v65, v66, v67
	global_store_dwordx2 v[80:81], v[64:65], off offset:128
	v_mul_f32_e32 v64, 0xbfb8aa3b, v60
	v_exp_f32_e32 v66, v64
	v_mul_f32_e32 v67, 0xbfb8aa3b, v61
	v_exp_f32_e32 v67, v67
	v_add_u32_e32 v64, 0x80, v150
	v_add_f32_e32 v66, 1.0, v66
	v_rcp_f32_e32 v66, v66
	v_mad_i64_i32 v[64:65], s[52:53], v64, s70, v[140:141]
	v_lshl_add_u64 v[64:65], v[64:65], 0, v[142:143]
	v_mul_f32_e32 v60, v60, v66
	v_mul_f32_e32 v56, v56, v60
	v_add_f32_e32 v60, 1.0, v67
	v_mul_f32_e32 v66, 0xbfb8aa3b, v62
	v_rcp_f32_e32 v60, v60
	v_exp_f32_e32 v66, v66
	v_mul_f32_e32 v67, 0xbfb8aa3b, v63
	v_exp_f32_e32 v67, v67
	v_mul_f32_e32 v60, v61, v60
	v_add_f32_e32 v61, 1.0, v66
	v_rcp_f32_e32 v61, v61
	v_add_f32_e32 v66, 1.0, v67
	v_rcp_f32_e32 v66, v66
	v_mul_f32_e32 v57, v57, v60
	v_mul_f32_e32 v60, v62, v61
	v_mul_f32_e32 v61, 0xbfb8aa3b, v52
	v_exp_f32_e32 v61, v61
	v_mul_f32_e32 v58, v58, v60
	v_mul_f32_e32 v60, v63, v66
	v_mul_f32_e32 v59, v59, v60
	v_cvt_pk_bf16_f32 v56, v56, v57
	v_cvt_pk_bf16_f32 v57, v58, v59
	v_add_f32_e32 v58, 1.0, v61
	v_rcp_f32_e32 v58, v58
	v_mul_f32_e32 v59, 0xbfb8aa3b, v53
	v_exp_f32_e32 v59, v59
	global_store_dwordx2 v[64:65], v[56:57], off
	v_mul_f32_e32 v52, v52, v58
	v_mul_f32_e32 v48, v48, v52
	v_add_f32_e32 v52, 1.0, v59
	v_mul_f32_e32 v56, 0xbfb8aa3b, v54
	v_rcp_f32_e32 v52, v52
	v_exp_f32_e32 v56, v56
	v_mul_f32_e32 v57, 0xbfb8aa3b, v55
	v_exp_f32_e32 v57, v57
	v_mul_f32_e32 v52, v53, v52
	v_add_f32_e32 v53, 1.0, v56
	v_rcp_f32_e32 v53, v53
	v_add_f32_e32 v56, 1.0, v57
	v_rcp_f32_e32 v56, v56
	v_mul_f32_e32 v49, v49, v52
	v_mul_f32_e32 v52, v54, v53
	v_mul_f32_e32 v50, v50, v52
	v_mul_f32_e32 v52, v55, v56
	v_cvt_pk_bf16_f32 v48, v48, v49
	v_mul_f32_e32 v51, v51, v52
	v_cvt_pk_bf16_f32 v49, v50, v51
	global_store_dwordx2 v[64:65], v[48:49], off offset:128
	v_mul_f32_e32 v48, 0xbfb8aa3b, v44
	v_exp_f32_e32 v50, v48
	v_mul_f32_e32 v51, 0xbfb8aa3b, v45
	v_exp_f32_e32 v51, v51
	v_add_u32_e32 v48, 0x90, v150
	v_add_f32_e32 v50, 1.0, v50
	v_rcp_f32_e32 v50, v50
	v_mad_i64_i32 v[48:49], s[52:53], v48, s70, v[140:141]
	v_lshl_add_u64 v[48:49], v[48:49], 0, v[142:143]
	v_mul_f32_e32 v44, v44, v50
	v_mul_f32_e32 v40, v40, v44
	v_add_f32_e32 v44, 1.0, v51
	v_mul_f32_e32 v50, 0xbfb8aa3b, v46
	v_rcp_f32_e32 v44, v44
	v_exp_f32_e32 v50, v50
	v_mul_f32_e32 v51, 0xbfb8aa3b, v47
	v_exp_f32_e32 v51, v51
	v_mul_f32_e32 v44, v45, v44
	v_add_f32_e32 v45, 1.0, v50
	v_rcp_f32_e32 v45, v45
	v_add_f32_e32 v50, 1.0, v51
	v_rcp_f32_e32 v50, v50
	v_mul_f32_e32 v41, v41, v44
	v_mul_f32_e32 v44, v46, v45
	v_mul_f32_e32 v45, 0xbfb8aa3b, v36
	v_exp_f32_e32 v45, v45
	v_mul_f32_e32 v42, v42, v44
	v_mul_f32_e32 v44, v47, v50
	v_mul_f32_e32 v43, v43, v44
	v_cvt_pk_bf16_f32 v40, v40, v41
	v_cvt_pk_bf16_f32 v41, v42, v43
	v_add_f32_e32 v42, 1.0, v45
	v_rcp_f32_e32 v42, v42
	v_mul_f32_e32 v43, 0xbfb8aa3b, v37
	v_exp_f32_e32 v43, v43
	global_store_dwordx2 v[48:49], v[40:41], off
	v_mul_f32_e32 v36, v36, v42
	v_mul_f32_e32 v32, v32, v36
	v_add_f32_e32 v36, 1.0, v43
	v_mul_f32_e32 v40, 0xbfb8aa3b, v38
	v_rcp_f32_e32 v36, v36
	v_exp_f32_e32 v40, v40
	v_mul_f32_e32 v41, 0xbfb8aa3b, v39
	v_exp_f32_e32 v41, v41
	v_mul_f32_e32 v36, v37, v36
	v_add_f32_e32 v37, 1.0, v40
	v_rcp_f32_e32 v37, v37
	v_add_f32_e32 v40, 1.0, v41
	v_rcp_f32_e32 v40, v40
	v_mul_f32_e32 v33, v33, v36
	v_mul_f32_e32 v36, v38, v37
	v_mul_f32_e32 v34, v34, v36
	v_mul_f32_e32 v36, v39, v40
	v_cvt_pk_bf16_f32 v32, v32, v33
	v_mul_f32_e32 v35, v35, v36
	v_cvt_pk_bf16_f32 v33, v34, v35
	global_store_dwordx2 v[48:49], v[32:33], off offset:128
	v_mul_f32_e32 v32, 0xbfb8aa3b, v28
	v_exp_f32_e32 v34, v32
	v_mul_f32_e32 v35, 0xbfb8aa3b, v29
	v_exp_f32_e32 v35, v35
	v_add_u32_e32 v32, 0xa0, v150
	v_add_f32_e32 v34, 1.0, v34
	v_rcp_f32_e32 v34, v34
	v_mad_i64_i32 v[32:33], s[52:53], v32, s70, v[140:141]
	v_lshl_add_u64 v[32:33], v[32:33], 0, v[142:143]
	v_mul_f32_e32 v28, v28, v34
	v_mul_f32_e32 v24, v24, v28
	v_add_f32_e32 v28, 1.0, v35
	v_mul_f32_e32 v34, 0xbfb8aa3b, v30
	v_rcp_f32_e32 v28, v28
	v_exp_f32_e32 v34, v34
	v_mul_f32_e32 v35, 0xbfb8aa3b, v31
	v_exp_f32_e32 v35, v35
	v_mul_f32_e32 v28, v29, v28
	v_add_f32_e32 v29, 1.0, v34
	v_rcp_f32_e32 v29, v29
	v_add_f32_e32 v34, 1.0, v35
	v_rcp_f32_e32 v34, v34
	v_mul_f32_e32 v25, v25, v28
	v_mul_f32_e32 v28, v30, v29
	v_mul_f32_e32 v29, 0xbfb8aa3b, v20
	v_exp_f32_e32 v29, v29
	v_mul_f32_e32 v26, v26, v28
	v_mul_f32_e32 v28, v31, v34
	v_mul_f32_e32 v27, v27, v28
	v_cvt_pk_bf16_f32 v24, v24, v25
	v_cvt_pk_bf16_f32 v25, v26, v27
	v_add_f32_e32 v26, 1.0, v29
	v_rcp_f32_e32 v26, v26
	v_mul_f32_e32 v27, 0xbfb8aa3b, v21
	v_exp_f32_e32 v27, v27
	global_store_dwordx2 v[32:33], v[24:25], off
	v_mul_f32_e32 v20, v20, v26
	v_mul_f32_e32 v16, v16, v20
	v_add_f32_e32 v20, 1.0, v27
	v_mul_f32_e32 v24, 0xbfb8aa3b, v22
	v_rcp_f32_e32 v20, v20
	v_exp_f32_e32 v24, v24
	v_mul_f32_e32 v25, 0xbfb8aa3b, v23
	v_exp_f32_e32 v25, v25
	v_mul_f32_e32 v20, v21, v20
	v_add_f32_e32 v21, 1.0, v24
	v_rcp_f32_e32 v21, v21
	v_add_f32_e32 v24, 1.0, v25
	v_rcp_f32_e32 v24, v24
	v_mul_f32_e32 v17, v17, v20
	v_mul_f32_e32 v20, v22, v21
	v_mul_f32_e32 v18, v18, v20
	v_mul_f32_e32 v20, v23, v24
	v_cvt_pk_bf16_f32 v16, v16, v17
	v_mul_f32_e32 v19, v19, v20
	v_cvt_pk_bf16_f32 v17, v18, v19
	global_store_dwordx2 v[32:33], v[16:17], off offset:128
	v_mul_f32_e32 v16, 0xbfb8aa3b, v12
	v_exp_f32_e32 v18, v16
	v_mul_f32_e32 v19, 0xbfb8aa3b, v13
	v_exp_f32_e32 v19, v19
	v_add_u32_e32 v16, 0xb0, v150
	v_add_f32_e32 v18, 1.0, v18
	v_rcp_f32_e32 v18, v18
	v_mad_i64_i32 v[16:17], s[52:53], v16, s70, v[140:141]
	v_lshl_add_u64 v[16:17], v[16:17], 0, v[142:143]
	v_mul_f32_e32 v12, v12, v18
	v_mul_f32_e32 v8, v8, v12
	v_add_f32_e32 v12, 1.0, v19
	v_mul_f32_e32 v18, 0xbfb8aa3b, v14
	v_rcp_f32_e32 v12, v12
	v_exp_f32_e32 v18, v18
	v_mul_f32_e32 v19, 0xbfb8aa3b, v15
	v_exp_f32_e32 v19, v19
	v_mul_f32_e32 v12, v13, v12
	v_add_f32_e32 v13, 1.0, v18
	v_rcp_f32_e32 v13, v13
	v_add_f32_e32 v18, 1.0, v19
	v_rcp_f32_e32 v18, v18
	v_mul_f32_e32 v9, v9, v12
	v_mul_f32_e32 v12, v14, v13
	v_mul_f32_e32 v13, 0xbfb8aa3b, v4
	v_exp_f32_e32 v13, v13
	v_mul_f32_e32 v10, v10, v12
	v_mul_f32_e32 v12, v15, v18
	v_mul_f32_e32 v11, v11, v12
	v_cvt_pk_bf16_f32 v8, v8, v9
	v_cvt_pk_bf16_f32 v9, v10, v11
	v_add_f32_e32 v10, 1.0, v13
	v_rcp_f32_e32 v10, v10
	v_mul_f32_e32 v11, 0xbfb8aa3b, v5
	v_exp_f32_e32 v11, v11
	global_store_dwordx2 v[16:17], v[8:9], off
	v_mul_f32_e32 v4, v4, v10
	v_mul_f32_e32 v0, v0, v4
	v_add_f32_e32 v4, 1.0, v11
	v_mul_f32_e32 v8, 0xbfb8aa3b, v6
	v_rcp_f32_e32 v4, v4
	v_exp_f32_e32 v8, v8
	v_mul_f32_e32 v9, 0xbfb8aa3b, v7
	v_exp_f32_e32 v9, v9
	v_mul_f32_e32 v4, v5, v4
	v_add_f32_e32 v5, 1.0, v8
	v_rcp_f32_e32 v5, v5
	v_add_f32_e32 v8, 1.0, v9
	v_rcp_f32_e32 v8, v8
	v_mul_f32_e32 v1, v1, v4
	v_mul_f32_e32 v4, v6, v5
	v_mul_f32_e32 v2, v2, v4
	v_mul_f32_e32 v4, v7, v8
	s_andn2_b64 vcc, exec, s[10:11]
	s_mov_b64 s[10:11], -1
	v_mul_f32_e32 v3, v3, v4
	v_cvt_pk_bf16_f32 v0, v0, v1
	v_cvt_pk_bf16_f32 v1, v2, v3
	global_store_dwordx2 v[16:17], v[0:1], off offset:128
	s_cbranch_vccnz .LBB0_947
	s_andn2_b64 vcc, exec, s[0:1]
	s_cbranch_vccnz .LBB0_946
	s_barrier
	s_branch .LBB0_946

.Lov_11:
	v_mul_f32_e32 v151, 0xbfb8aa3b, v124
	v_exp_f32_e32 v151, v151
	v_mul_f32_e32 v154, 0xbfb8aa3b, v125
	v_exp_f32_e32 v154, v154
	v_lshl_or_b32 v142, s65, 7, v146
	v_add_f32_e32 v151, 1.0, v151
	v_rcp_f32_e32 v151, v151
	v_lshl_add_u32 v150, s44, 8, v144
	v_ashrrev_i32_e32 v143, 31, v142
	v_mov_b64_e32 v[140:141], s[22:23]
	v_mul_f32_e32 v124, v124, v151
	v_mul_f32_e32 v120, v120, v124
	v_add_f32_e32 v124, 1.0, v154
	v_mul_f32_e32 v151, 0xbfb8aa3b, v126
	v_rcp_f32_e32 v124, v124
	v_exp_f32_e32 v151, v151
	v_mul_f32_e32 v154, 0xbfb8aa3b, v127
	v_exp_f32_e32 v154, v154
	v_mul_f32_e32 v124, v125, v124
	v_add_f32_e32 v125, 1.0, v151
	v_rcp_f32_e32 v125, v125
	v_add_f32_e32 v151, 1.0, v154
	v_rcp_f32_e32 v151, v151
	v_mul_f32_e32 v121, v121, v124
	v_mul_f32_e32 v124, v126, v125
	v_mul_f32_e32 v125, 0xbfb8aa3b, v116
	v_exp_f32_e32 v125, v125
	v_mul_f32_e32 v122, v122, v124
	v_mul_f32_e32 v124, v127, v151
	v_mul_f32_e32 v123, v123, v124
	v_cvt_pk_bf16_f32 v120, v120, v121
	v_cvt_pk_bf16_f32 v121, v122, v123
	v_add_f32_e32 v122, 1.0, v125
	v_rcp_f32_e32 v122, v122
	v_mul_f32_e32 v123, 0xbfb8aa3b, v117
	v_exp_f32_e32 v123, v123
	v_mad_i64_i32 v[152:153], s[46:47], v150, s64, v[140:141]
	v_lshlrev_b64 v[142:143], 1, v[142:143]
	v_lshl_add_u64 v[152:153], v[152:153], 0, v[142:143]
	v_mul_f32_e32 v116, v116, v122
	global_store_dwordx2 v[152:153], v[120:121], off
	v_mul_f32_e32 v112, v112, v116
	v_add_f32_e32 v116, 1.0, v123
	v_mul_f32_e32 v120, 0xbfb8aa3b, v118
	v_rcp_f32_e32 v116, v116
	v_exp_f32_e32 v120, v120
	v_mul_f32_e32 v121, 0xbfb8aa3b, v119
	v_exp_f32_e32 v121, v121
	v_mul_f32_e32 v116, v117, v116
	v_add_f32_e32 v117, 1.0, v120
	v_rcp_f32_e32 v117, v117
	v_add_f32_e32 v120, 1.0, v121
	v_rcp_f32_e32 v120, v120
	v_mul_f32_e32 v113, v113, v116
	v_mul_f32_e32 v116, v118, v117
	v_mul_f32_e32 v114, v114, v116
	v_mul_f32_e32 v116, v119, v120
	v_cvt_pk_bf16_f32 v112, v112, v113
	v_mul_f32_e32 v115, v115, v116
	v_cvt_pk_bf16_f32 v113, v114, v115
	global_store_dwordx2 v[152:153], v[112:113], off offset:128
	v_mul_f32_e32 v112, 0xbfb8aa3b, v108
	v_exp_f32_e32 v114, v112
	v_mul_f32_e32 v115, 0xbfb8aa3b, v109
	v_exp_f32_e32 v115, v115
	v_or_b32_e32 v112, 16, v150
	v_add_f32_e32 v114, 1.0, v114
	v_rcp_f32_e32 v114, v114
	v_mad_i64_i32 v[112:113], s[46:47], v112, s64, v[140:141]
	v_lshl_add_u64 v[112:113], v[112:113], 0, v[142:143]
	v_mul_f32_e32 v108, v108, v114
	v_mul_f32_e32 v104, v104, v108
	v_add_f32_e32 v108, 1.0, v115
	v_mul_f32_e32 v114, 0xbfb8aa3b, v110
	v_rcp_f32_e32 v108, v108
	v_exp_f32_e32 v114, v114
	v_mul_f32_e32 v115, 0xbfb8aa3b, v111
	v_exp_f32_e32 v115, v115
	v_mul_f32_e32 v108, v109, v108
	v_add_f32_e32 v109, 1.0, v114
	v_rcp_f32_e32 v109, v109
	v_add_f32_e32 v114, 1.0, v115
	v_rcp_f32_e32 v114, v114
	v_mul_f32_e32 v105, v105, v108
	v_mul_f32_e32 v108, v110, v109
	v_mul_f32_e32 v109, 0xbfb8aa3b, v100
	v_exp_f32_e32 v109, v109
	v_mul_f32_e32 v106, v106, v108
	v_mul_f32_e32 v108, v111, v114
	v_mul_f32_e32 v107, v107, v108
	v_cvt_pk_bf16_f32 v104, v104, v105
	v_cvt_pk_bf16_f32 v105, v106, v107
	v_add_f32_e32 v106, 1.0, v109
	v_rcp_f32_e32 v106, v106
	v_mul_f32_e32 v107, 0xbfb8aa3b, v101
	v_exp_f32_e32 v107, v107
	global_store_dwordx2 v[112:113], v[104:105], off
	v_mul_f32_e32 v100, v100, v106
	v_mul_f32_e32 v96, v96, v100
	v_add_f32_e32 v100, 1.0, v107
	v_mul_f32_e32 v104, 0xbfb8aa3b, v102
	v_rcp_f32_e32 v100, v100
	v_exp_f32_e32 v104, v104
	v_mul_f32_e32 v105, 0xbfb8aa3b, v103
	v_exp_f32_e32 v105, v105
	v_mul_f32_e32 v100, v101, v100
	v_add_f32_e32 v101, 1.0, v104
	v_rcp_f32_e32 v101, v101
	v_add_f32_e32 v104, 1.0, v105
	v_rcp_f32_e32 v104, v104
	v_mul_f32_e32 v97, v97, v100
	v_mul_f32_e32 v100, v102, v101
	v_mul_f32_e32 v98, v98, v100
	v_mul_f32_e32 v100, v103, v104
	v_cvt_pk_bf16_f32 v96, v96, v97
	v_mul_f32_e32 v99, v99, v100
	v_cvt_pk_bf16_f32 v97, v98, v99
	global_store_dwordx2 v[112:113], v[96:97], off offset:128
	v_mul_f32_e32 v96, 0xbfb8aa3b, v92
	v_exp_f32_e32 v98, v96
	v_mul_f32_e32 v99, 0xbfb8aa3b, v93
	v_exp_f32_e32 v99, v99
	v_or_b32_e32 v96, 32, v150
	v_add_f32_e32 v98, 1.0, v98
	v_rcp_f32_e32 v98, v98
	v_mad_i64_i32 v[96:97], s[46:47], v96, s64, v[140:141]
	v_lshl_add_u64 v[96:97], v[96:97], 0, v[142:143]
	v_mul_f32_e32 v92, v92, v98
	v_mul_f32_e32 v88, v88, v92
	v_add_f32_e32 v92, 1.0, v99
	v_mul_f32_e32 v98, 0xbfb8aa3b, v94
	v_rcp_f32_e32 v92, v92
	v_exp_f32_e32 v98, v98
	v_mul_f32_e32 v99, 0xbfb8aa3b, v95
	v_exp_f32_e32 v99, v99
	v_mul_f32_e32 v92, v93, v92
	v_add_f32_e32 v93, 1.0, v98
	v_rcp_f32_e32 v93, v93
	v_add_f32_e32 v98, 1.0, v99
	v_rcp_f32_e32 v98, v98
	v_mul_f32_e32 v89, v89, v92
	v_mul_f32_e32 v92, v94, v93
	v_mul_f32_e32 v93, 0xbfb8aa3b, v84
	v_exp_f32_e32 v93, v93
	v_mul_f32_e32 v90, v90, v92
	v_mul_f32_e32 v92, v95, v98
	v_mul_f32_e32 v91, v91, v92
	v_cvt_pk_bf16_f32 v88, v88, v89
	v_cvt_pk_bf16_f32 v89, v90, v91
	v_add_f32_e32 v90, 1.0, v93
	v_rcp_f32_e32 v90, v90
	v_mul_f32_e32 v91, 0xbfb8aa3b, v85
	v_exp_f32_e32 v91, v91
	global_store_dwordx2 v[96:97], v[88:89], off
	v_mul_f32_e32 v84, v84, v90
	v_mul_f32_e32 v80, v80, v84
	v_add_f32_e32 v84, 1.0, v91
	v_mul_f32_e32 v88, 0xbfb8aa3b, v86
	v_rcp_f32_e32 v84, v84
	v_exp_f32_e32 v88, v88
	v_mul_f32_e32 v89, 0xbfb8aa3b, v87
	v_exp_f32_e32 v89, v89
	v_mul_f32_e32 v84, v85, v84
	v_add_f32_e32 v85, 1.0, v88
	v_rcp_f32_e32 v85, v85
	v_add_f32_e32 v88, 1.0, v89
	v_rcp_f32_e32 v88, v88
	v_mul_f32_e32 v81, v81, v84
	v_mul_f32_e32 v84, v86, v85
	v_mul_f32_e32 v82, v82, v84
	v_mul_f32_e32 v84, v87, v88
	v_cvt_pk_bf16_f32 v80, v80, v81
	v_mul_f32_e32 v83, v83, v84
	v_cvt_pk_bf16_f32 v81, v82, v83
	global_store_dwordx2 v[96:97], v[80:81], off offset:128
	v_mul_f32_e32 v80, 0xbfb8aa3b, v76
	v_exp_f32_e32 v82, v80
	v_mul_f32_e32 v83, 0xbfb8aa3b, v77
	v_exp_f32_e32 v83, v83
	v_or_b32_e32 v80, 48, v150
	v_add_f32_e32 v82, 1.0, v82
	v_rcp_f32_e32 v82, v82
	v_mad_i64_i32 v[80:81], s[46:47], v80, s64, v[140:141]
	v_lshl_add_u64 v[80:81], v[80:81], 0, v[142:143]
	v_mul_f32_e32 v76, v76, v82
	v_mul_f32_e32 v72, v72, v76
	v_add_f32_e32 v76, 1.0, v83
	v_mul_f32_e32 v82, 0xbfb8aa3b, v78
	v_rcp_f32_e32 v76, v76
	v_exp_f32_e32 v82, v82
	v_mul_f32_e32 v83, 0xbfb8aa3b, v79
	v_exp_f32_e32 v83, v83
	v_mul_f32_e32 v76, v77, v76
	v_add_f32_e32 v77, 1.0, v82
	v_rcp_f32_e32 v77, v77
	v_add_f32_e32 v82, 1.0, v83
	v_rcp_f32_e32 v82, v82
	v_mul_f32_e32 v73, v73, v76
	v_mul_f32_e32 v76, v78, v77
	v_mul_f32_e32 v77, 0xbfb8aa3b, v68
	v_exp_f32_e32 v77, v77
	v_mul_f32_e32 v74, v74, v76
	v_mul_f32_e32 v76, v79, v82
	v_mul_f32_e32 v75, v75, v76
	v_cvt_pk_bf16_f32 v72, v72, v73
	v_cvt_pk_bf16_f32 v73, v74, v75
	v_add_f32_e32 v74, 1.0, v77
	v_rcp_f32_e32 v74, v74
	v_mul_f32_e32 v75, 0xbfb8aa3b, v69
	v_exp_f32_e32 v75, v75
	global_store_dwordx2 v[80:81], v[72:73], off
	v_mul_f32_e32 v68, v68, v74
	v_mul_f32_e32 v64, v64, v68
	v_add_f32_e32 v68, 1.0, v75
	v_mul_f32_e32 v72, 0xbfb8aa3b, v70
	v_rcp_f32_e32 v68, v68
	v_exp_f32_e32 v72, v72
	v_mul_f32_e32 v73, 0xbfb8aa3b, v71
	v_exp_f32_e32 v73, v73
	v_mul_f32_e32 v68, v69, v68
	v_add_f32_e32 v69, 1.0, v72
	v_rcp_f32_e32 v69, v69
	v_add_f32_e32 v72, 1.0, v73
	v_rcp_f32_e32 v72, v72
	v_mul_f32_e32 v65, v65, v68
	v_mul_f32_e32 v68, v70, v69
	v_mul_f32_e32 v66, v66, v68
	v_mul_f32_e32 v68, v71, v72
	v_cvt_pk_bf16_f32 v64, v64, v65
	v_mul_f32_e32 v67, v67, v68
	v_cvt_pk_bf16_f32 v65, v66, v67
	global_store_dwordx2 v[80:81], v[64:65], off offset:128
	v_mov_b32_e32 v216, v140
	v_mov_b32_e32 v217, v141
	v_mov_b32_e32 v218, v142
	v_mov_b32_e32 v219, v143
	v_mov_b32_e32 v220, v150
	s_andn2_b64 vcc, exec, s[0:1]
	s_cbranch_vccnz .Lov_nb_11
	s_barrier
.Lov_nb_11:
	s_mov_b32 s65, s16
	s_mov_b32 s44, s18
	s_mov_b64 s[48:49], s[36:37]
	s_mov_b64 s[46:47], s[30:31]
	s_add_i32 s59, s59, 1
	s_mul_i32 s8, s59, s21
	s_mul_hi_u32 s9, s59, s20
	s_add_i32 s9, s9, s8
	s_mul_i32 s8, s59, s20
	s_add_u32 s30, s8, s2
	s_addc_u32 s31, s9, s3
	v_cmp_gt_i64_e32 vcc, s[30:31], v[138:139]
	v_cmp_lt_i64_e64 s[8:9], s[30:31], v[136:137]
	s_cbranch_vccnz .LBB0_1433_ov11
	s_lshr_b32 s16, s30, 3
	s_and_b32 s18, s30, 7
	s_lshl_b32 s18, s18, 1
	s_cmp_ge_u32 s16, 0xb0
	s_cbranch_scc0 .Ldec_11_ov11
	s_sub_u32 s16, s16, 0xb0
	s_add_u32 s18, s18, 1

.LBB0_1433_ov11:
	s_ashr_i32 s19, s18, 31
	s_lshl_b64 s[30:31], s[18:19], 19
	s_add_u32 s30, s80, s30
	s_addc_u32 s31, s81, s31
	s_and_b64 s[36:37], s[8:9], exec
	s_cselect_b32 s19, s31, s47
	s_cselect_b32 s66, s30, s46
	s_ashr_i32 s17, s16, 31
	s_lshl_b64 s[36:37], s[16:17], 19
	s_add_u32 s36, s52, s36
	s_addc_u32 s37, s53, s37
	s_and_b64 s[50:51], s[8:9], exec
	s_cselect_b32 s17, s37, s49
	s_cselect_b32 s67, s36, s48
	s_add_u32 s46, s46, 0x40080
	s_addc_u32 s47, s47, 0
	s_add_u32 s68, s48, 0x100
	s_addc_u32 s69, s49, 0
	s_mov_b32 s70, -2
	ds_read_b128 v[140:143], v147
	ds_read_b128 v[150:153], v147 offset:1024
	ds_read_b128 v[154:157], v147 offset:2048
	ds_read_b128 v[158:161], v147 offset:3072
	ds_read_b128 v[162:165], v148
	ds_read_b128 v[166:169], v148 offset:1024
	ds_read_b128 v[170:173], v148 offset:2048
	ds_read_b128 v[174:177], v148 offset:3072
	s_add_u32 s48, s46, 0xfffc0080
	s_addc_u32 s49, s47, -1
	s_cmp_eq_u32 s70, 12
	s_cselect_b32 s51, s19, s49
	s_cselect_b32 s50, s66, s48
	s_cselect_b32 s49, s17, s69
	s_cselect_b32 s48, s67, s68
	v_lshl_add_u64 v[178:179], s[46:47], 0, v[132:133]
	s_add_i32 m0, s45, 0xc000
	ds_read_b128 v[184:187], v149
	ds_read_b128 v[188:191], v149 offset:1024
	ds_read_b128 v[192:195], v149 offset:2048
	ds_read_b128 v[196:199], v149 offset:3072
	ds_read_b128 v[200:203], v149 offset:4096
	ds_read_b128 v[204:207], v149 offset:5120
	ds_read_b128 v[208:211], v149 offset:6144
	ds_read_b128 v[212:215], v149 offset:7168
	global_load_lds_dwordx4 v[178:179], off
	v_lshl_add_u64 v[178:179], s[46:47], 0, v[134:135]
	s_add_i32 m0, s45, 0xe000
	s_nop 0
	global_load_lds_dwordx4 v[178:179], off
	s_waitcnt vmcnt(8)
	s_waitcnt lgkmcnt(0)
	s_barrier
	s_setprio 1
	s_waitcnt lgkmcnt(0)
	v_mfma_f32_16x16x32_bf16 v[124:127], v[140:143], v[184:187], 0
	v_mul_f32_e32 v222, 0xbfb8aa3b, v60
	v_exp_f32_e32 v224, v222
	v_mul_f32_e32 v225, 0xbfb8aa3b, v61
	v_exp_f32_e32 v225, v225
	v_add_u32_e32 v222, 0x80, v220
	v_add_f32_e32 v224, 1.0, v224
	v_rcp_f32_e32 v224, v224
	v_mad_i64_i32 v[222:223], vcc, v222, s64, v[216:217]
	v_mfma_f32_16x16x32_bf16 v[124:127], v[150:153], v[188:191], v[124:127]
	v_lshl_add_u64 v[222:223], v[222:223], 0, v[218:219]
	v_mul_f32_e32 v60, v60, v224
	v_mul_f32_e32 v56, v56, v60
	v_add_f32_e32 v60, 1.0, v225
	v_mul_f32_e32 v224, 0xbfb8aa3b, v62
	v_rcp_f32_e32 v60, v60
	v_exp_f32_e32 v224, v224
	v_mul_f32_e32 v225, 0xbfb8aa3b, v63
	v_mfma_f32_16x16x32_bf16 v[120:123], v[154:157], v[184:187], 0
	v_exp_f32_e32 v225, v225
	v_mul_f32_e32 v60, v61, v60
	v_add_f32_e32 v61, 1.0, v224
	v_rcp_f32_e32 v61, v61
	v_add_f32_e32 v224, 1.0, v225
	v_rcp_f32_e32 v224, v224
	v_mul_f32_e32 v57, v57, v60
	v_mul_f32_e32 v60, v62, v61
	v_mfma_f32_16x16x32_bf16 v[120:123], v[158:161], v[188:191], v[120:123]
	v_mul_f32_e32 v61, 0xbfb8aa3b, v52
	v_exp_f32_e32 v61, v61
	v_mul_f32_e32 v58, v58, v60
	v_mul_f32_e32 v60, v63, v224
	v_mul_f32_e32 v59, v59, v60
	v_cvt_pk_bf16_f32 v56, v56, v57
	v_cvt_pk_bf16_f32 v57, v58, v59
	v_add_f32_e32 v58, 1.0, v61
	v_mfma_f32_16x16x32_bf16 v[108:111], v[140:143], v[192:195], 0
	v_rcp_f32_e32 v58, v58
	v_mul_f32_e32 v59, 0xbfb8aa3b, v53
	v_exp_f32_e32 v59, v59
	global_store_dwordx2 v[222:223], v[56:57], off
	v_mul_f32_e32 v52, v52, v58
	v_mul_f32_e32 v48, v48, v52
	v_add_f32_e32 v52, 1.0, v59
	v_mul_f32_e32 v56, 0xbfb8aa3b, v54
	v_mfma_f32_16x16x32_bf16 v[108:111], v[150:153], v[196:199], v[108:111]
	v_rcp_f32_e32 v52, v52
	v_exp_f32_e32 v56, v56
	v_mul_f32_e32 v57, 0xbfb8aa3b, v55
	v_exp_f32_e32 v57, v57
	v_mul_f32_e32 v52, v53, v52
	v_add_f32_e32 v53, 1.0, v56
	v_rcp_f32_e32 v53, v53
	v_add_f32_e32 v56, 1.0, v57
	v_mfma_f32_16x16x32_bf16 v[104:107], v[154:157], v[192:195], 0
	v_rcp_f32_e32 v56, v56
	v_mul_f32_e32 v49, v49, v52
	v_mul_f32_e32 v52, v54, v53
	v_mul_f32_e32 v50, v50, v52
	v_mul_f32_e32 v52, v55, v56
	v_cvt_pk_bf16_f32 v48, v48, v49
	v_mul_f32_e32 v51, v51, v52
	v_cvt_pk_bf16_f32 v49, v50, v51
	v_mfma_f32_16x16x32_bf16 v[104:107], v[158:161], v[196:199], v[104:107]
	global_store_dwordx2 v[222:223], v[48:49], off offset:128
	v_mul_f32_e32 v48, 0xbfb8aa3b, v44
	v_exp_f32_e32 v50, v48
	v_mul_f32_e32 v51, 0xbfb8aa3b, v45
	v_exp_f32_e32 v51, v51
	v_add_u32_e32 v48, 0x90, v220
	v_add_f32_e32 v50, 1.0, v50
	v_rcp_f32_e32 v50, v50
	v_mfma_f32_16x16x32_bf16 v[92:95], v[140:143], v[200:203], 0
	v_mad_i64_i32 v[48:49], vcc, v48, s64, v[216:217]
	v_lshl_add_u64 v[48:49], v[48:49], 0, v[218:219]
	v_mul_f32_e32 v44, v44, v50
	v_mul_f32_e32 v40, v40, v44
	v_add_f32_e32 v44, 1.0, v51
	v_mul_f32_e32 v50, 0xbfb8aa3b, v46
	v_rcp_f32_e32 v44, v44
	v_exp_f32_e32 v50, v50
	v_mfma_f32_16x16x32_bf16 v[92:95], v[150:153], v[204:207], v[92:95]
	v_mul_f32_e32 v51, 0xbfb8aa3b, v47
	v_exp_f32_e32 v51, v51
	v_mul_f32_e32 v44, v45, v44
	v_add_f32_e32 v45, 1.0, v50
	v_rcp_f32_e32 v45, v45
	v_add_f32_e32 v50, 1.0, v51
	v_rcp_f32_e32 v50, v50
	v_mul_f32_e32 v41, v41, v44
	v_mfma_f32_16x16x32_bf16 v[88:91], v[154:157], v[200:203], 0
	v_mul_f32_e32 v44, v46, v45
	v_mul_f32_e32 v45, 0xbfb8aa3b, v36
	v_exp_f32_e32 v45, v45
	v_mul_f32_e32 v42, v42, v44
	v_mul_f32_e32 v44, v47, v50
	v_mul_f32_e32 v43, v43, v44
	v_cvt_pk_bf16_f32 v40, v40, v41
	v_cvt_pk_bf16_f32 v41, v42, v43
	v_mfma_f32_16x16x32_bf16 v[88:91], v[158:161], v[204:207], v[88:91]
	v_add_f32_e32 v42, 1.0, v45
	v_rcp_f32_e32 v42, v42
	v_mul_f32_e32 v43, 0xbfb8aa3b, v37
	v_exp_f32_e32 v43, v43
	global_store_dwordx2 v[48:49], v[40:41], off
	v_mul_f32_e32 v36, v36, v42
	v_mul_f32_e32 v32, v32, v36
	v_add_f32_e32 v36, 1.0, v43
	v_mfma_f32_16x16x32_bf16 v[76:79], v[140:143], v[208:211], 0
	v_mul_f32_e32 v40, 0xbfb8aa3b, v38
	v_rcp_f32_e32 v36, v36
	v_exp_f32_e32 v40, v40
	v_mul_f32_e32 v41, 0xbfb8aa3b, v39
	v_exp_f32_e32 v41, v41
	v_mul_f32_e32 v36, v37, v36
	v_add_f32_e32 v37, 1.0, v40
	v_rcp_f32_e32 v37, v37
	v_mfma_f32_16x16x32_bf16 v[76:79], v[150:153], v[212:215], v[76:79]
	v_add_f32_e32 v40, 1.0, v41
	v_rcp_f32_e32 v40, v40
	v_mul_f32_e32 v33, v33, v36
	v_mul_f32_e32 v36, v38, v37
	v_mul_f32_e32 v34, v34, v36
	v_mul_f32_e32 v36, v39, v40
	v_cvt_pk_bf16_f32 v32, v32, v33
	v_mul_f32_e32 v35, v35, v36
	v_mfma_f32_16x16x32_bf16 v[72:75], v[154:157], v[208:211], 0
	v_cvt_pk_bf16_f32 v33, v34, v35
	global_store_dwordx2 v[48:49], v[32:33], off offset:128
	v_mul_f32_e32 v32, 0xbfb8aa3b, v28
	v_exp_f32_e32 v34, v32
	v_mul_f32_e32 v35, 0xbfb8aa3b, v29
	v_exp_f32_e32 v35, v35
	v_add_u32_e32 v32, 0xa0, v220
	v_add_f32_e32 v34, 1.0, v34
	v_mfma_f32_16x16x32_bf16 v[72:75], v[158:161], v[212:215], v[72:75]
	v_rcp_f32_e32 v34, v34
	v_mad_i64_i32 v[32:33], vcc, v32, s64, v[216:217]
	v_lshl_add_u64 v[32:33], v[32:33], 0, v[218:219]
	v_mul_f32_e32 v28, v28, v34
	v_mul_f32_e32 v24, v24, v28
	v_add_f32_e32 v28, 1.0, v35
	v_mul_f32_e32 v34, 0xbfb8aa3b, v30
	v_rcp_f32_e32 v28, v28
	v_mfma_f32_16x16x32_bf16 v[116:119], v[162:165], v[184:187], 0
	v_exp_f32_e32 v34, v34
	v_mul_f32_e32 v35, 0xbfb8aa3b, v31
	v_exp_f32_e32 v35, v35
	v_mul_f32_e32 v28, v29, v28
	v_add_f32_e32 v29, 1.0, v34
	v_rcp_f32_e32 v29, v29
	v_add_f32_e32 v34, 1.0, v35
	v_rcp_f32_e32 v34, v34
	v_mfma_f32_16x16x32_bf16 v[116:119], v[166:169], v[188:191], v[116:119]
	v_mul_f32_e32 v25, v25, v28
	v_mul_f32_e32 v28, v30, v29
	v_mul_f32_e32 v29, 0xbfb8aa3b, v20
	v_exp_f32_e32 v29, v29
	v_mul_f32_e32 v26, v26, v28
	v_mul_f32_e32 v28, v31, v34
	v_mul_f32_e32 v27, v27, v28
	v_cvt_pk_bf16_f32 v24, v24, v25
	v_mfma_f32_16x16x32_bf16 v[112:115], v[170:173], v[184:187], 0
	v_cvt_pk_bf16_f32 v25, v26, v27
	v_add_f32_e32 v26, 1.0, v29
	v_rcp_f32_e32 v26, v26
	v_mul_f32_e32 v27, 0xbfb8aa3b, v21
	v_exp_f32_e32 v27, v27
	global_store_dwordx2 v[32:33], v[24:25], off
	v_mul_f32_e32 v20, v20, v26
	v_mul_f32_e32 v16, v16, v20
	v_mfma_f32_16x16x32_bf16 v[112:115], v[174:177], v[188:191], v[112:115]
	v_add_f32_e32 v20, 1.0, v27
	v_mul_f32_e32 v24, 0xbfb8aa3b, v22
	v_rcp_f32_e32 v20, v20
	v_exp_f32_e32 v24, v24
	v_mul_f32_e32 v25, 0xbfb8aa3b, v23
	v_exp_f32_e32 v25, v25
	v_mul_f32_e32 v20, v21, v20
	v_add_f32_e32 v21, 1.0, v24
	v_mfma_f32_16x16x32_bf16 v[100:103], v[162:165], v[192:195], 0
	v_rcp_f32_e32 v21, v21
	v_add_f32_e32 v24, 1.0, v25
	v_rcp_f32_e32 v24, v24
	v_mul_f32_e32 v17, v17, v20
	v_mul_f32_e32 v20, v22, v21
	v_mul_f32_e32 v18, v18, v20
	v_mul_f32_e32 v20, v23, v24
	v_cvt_pk_bf16_f32 v16, v16, v17
	v_mfma_f32_16x16x32_bf16 v[100:103], v[166:169], v[196:199], v[100:103]
	v_mul_f32_e32 v19, v19, v20
	v_cvt_pk_bf16_f32 v17, v18, v19
	global_store_dwordx2 v[32:33], v[16:17], off offset:128
	v_mul_f32_e32 v16, 0xbfb8aa3b, v12
	v_exp_f32_e32 v18, v16
	v_mul_f32_e32 v19, 0xbfb8aa3b, v13
	v_exp_f32_e32 v19, v19
	v_add_u32_e32 v16, 0xb0, v220
	v_mfma_f32_16x16x32_bf16 v[96:99], v[170:173], v[192:195], 0
	v_add_f32_e32 v18, 1.0, v18
	v_rcp_f32_e32 v18, v18
	v_mad_i64_i32 v[16:17], vcc, v16, s64, v[216:217]
	v_lshl_add_u64 v[16:17], v[16:17], 0, v[218:219]
	v_mul_f32_e32 v12, v12, v18
	v_mul_f32_e32 v8, v8, v12
	v_add_f32_e32 v12, 1.0, v19
	v_mul_f32_e32 v18, 0xbfb8aa3b, v14
	v_mfma_f32_16x16x32_bf16 v[96:99], v[174:177], v[196:199], v[96:99]
	v_rcp_f32_e32 v12, v12
	v_exp_f32_e32 v18, v18
	v_mul_f32_e32 v19, 0xbfb8aa3b, v15
	v_exp_f32_e32 v19, v19
	v_mul_f32_e32 v12, v13, v12
	v_add_f32_e32 v13, 1.0, v18
	v_rcp_f32_e32 v13, v13
	v_add_f32_e32 v18, 1.0, v19
	v_mfma_f32_16x16x32_bf16 v[84:87], v[162:165], v[200:203], 0
	v_rcp_f32_e32 v18, v18
	v_mul_f32_e32 v9, v9, v12
	v_mul_f32_e32 v12, v14, v13
	v_mul_f32_e32 v13, 0xbfb8aa3b, v4
	v_exp_f32_e32 v13, v13
	v_mul_f32_e32 v10, v10, v12
	v_mul_f32_e32 v12, v15, v18
	v_mul_f32_e32 v11, v11, v12
	v_mfma_f32_16x16x32_bf16 v[84:87], v[166:169], v[204:207], v[84:87]
	v_cvt_pk_bf16_f32 v8, v8, v9
	v_cvt_pk_bf16_f32 v9, v10, v11
	v_add_f32_e32 v10, 1.0, v13
	v_rcp_f32_e32 v10, v10
	v_mul_f32_e32 v11, 0xbfb8aa3b, v5
	v_exp_f32_e32 v11, v11
	global_store_dwordx2 v[16:17], v[8:9], off
	v_mul_f32_e32 v4, v4, v10
	v_mfma_f32_16x16x32_bf16 v[80:83], v[170:173], v[200:203], 0
	v_mul_f32_e32 v0, v0, v4
	v_add_f32_e32 v4, 1.0, v11
	v_mul_f32_e32 v8, 0xbfb8aa3b, v6
	v_rcp_f32_e32 v4, v4
	v_exp_f32_e32 v8, v8
	v_mul_f32_e32 v9, 0xbfb8aa3b, v7
	v_exp_f32_e32 v9, v9
	v_mul_f32_e32 v4, v5, v4
	v_mfma_f32_16x16x32_bf16 v[80:83], v[174:177], v[204:207], v[80:83]
	v_add_f32_e32 v5, 1.0, v8
	v_rcp_f32_e32 v5, v5
	v_add_f32_e32 v8, 1.0, v9
	v_rcp_f32_e32 v8, v8
	v_mul_f32_e32 v1, v1, v4
	v_mul_f32_e32 v4, v6, v5
	v_mul_f32_e32 v2, v2, v4
	v_mul_f32_e32 v4, v7, v8
	v_mfma_f32_16x16x32_bf16 v[68:71], v[162:165], v[208:211], 0
	v_mul_f32_e32 v3, v3, v4
	v_cvt_pk_bf16_f32 v0, v0, v1
	v_cvt_pk_bf16_f32 v1, v2, v3
	global_store_dwordx2 v[16:17], v[0:1], off offset:128
	v_mfma_f32_16x16x32_bf16 v[68:71], v[166:169], v[212:215], v[68:71]
	v_mfma_f32_16x16x32_bf16 v[64:67], v[170:173], v[208:211], 0
	v_mfma_f32_16x16x32_bf16 v[64:67], v[174:177], v[212:215], v[64:67]
	s_setprio 0
	s_barrier
	s_add_i32 s71, s62, s54
	v_lshl_add_u64 v[178:179], s[48:49], 0, v[130:131]
	s_mov_b32 m0, s71
	ds_read_b128 v[184:187], v149 offset:16384
	ds_read_b128 v[188:191], v149 offset:17408
	ds_read_b128 v[192:195], v149 offset:18432
	ds_read_b128 v[196:199], v149 offset:19456
	ds_read_b128 v[200:203], v149 offset:20480
	ds_read_b128 v[204:207], v149 offset:21504
	ds_read_b128 v[208:211], v149 offset:22528
	ds_read_b128 v[212:215], v149 offset:23552
	global_load_lds_dwordx4 v[178:179], off
	s_add_i32 m0, s71, 0x2000
	s_add_u32 s72, s48, 0x40000
	v_lshl_add_u64 v[216:217], s[48:49], 0, v[128:129]
	s_addc_u32 s73, s49, 0
	s_add_i32 s71, s63, s54
	global_load_lds_dwordx4 v[216:217], off
	v_lshl_add_u64 v[218:219], s[72:73], 0, v[130:131]
	s_mov_b32 m0, s71
	v_lshl_add_u64 v[220:221], s[50:51], 0, v[128:129]
	global_load_lds_dwordx4 v[218:219], off
	v_lshl_add_u64 v[218:219], s[72:73], 0, v[128:129]
	s_add_i32 m0, s71, 0x2000
	s_nop 0
	global_load_lds_dwordx4 v[218:219], off
	v_lshl_add_u64 v[218:219], s[50:51], 0, v[130:131]
	s_mov_b32 m0, s45
	s_nop 0
	global_load_lds_dwordx4 v[218:219], off
	s_mov_b32 m0, s56
	s_nop 0
	global_load_lds_dwordx4 v[220:221], off
	s_waitcnt vmcnt(8)
	s_waitcnt lgkmcnt(0)
	s_barrier
	s_setprio 1
	s_waitcnt lgkmcnt(0)
	v_mfma_f32_16x16x32_bf16 v[60:63], v[140:143], v[184:187], 0
	v_mfma_f32_16x16x32_bf16 v[60:63], v[150:153], v[188:191], v[60:63]
	v_mfma_f32_16x16x32_bf16 v[56:59], v[154:157], v[184:187], 0
	v_mfma_f32_16x16x32_bf16 v[56:59], v[158:161], v[188:191], v[56:59]
	v_mfma_f32_16x16x32_bf16 v[44:47], v[140:143], v[192:195], 0
	v_mfma_f32_16x16x32_bf16 v[44:47], v[150:153], v[196:199], v[44:47]
	v_mfma_f32_16x16x32_bf16 v[40:43], v[154:157], v[192:195], 0
	v_mfma_f32_16x16x32_bf16 v[40:43], v[158:161], v[196:199], v[40:43]
	v_mfma_f32_16x16x32_bf16 v[28:31], v[140:143], v[200:203], 0
	v_mfma_f32_16x16x32_bf16 v[28:31], v[150:153], v[204:207], v[28:31]
	v_mfma_f32_16x16x32_bf16 v[24:27], v[154:157], v[200:203], 0
	v_mfma_f32_16x16x32_bf16 v[24:27], v[158:161], v[204:207], v[24:27]
	v_mfma_f32_16x16x32_bf16 v[12:15], v[140:143], v[208:211], 0
	v_mfma_f32_16x16x32_bf16 v[12:15], v[150:153], v[212:215], v[12:15]
	v_mfma_f32_16x16x32_bf16 v[8:11], v[154:157], v[208:211], 0
	v_mfma_f32_16x16x32_bf16 v[8:11], v[158:161], v[212:215], v[8:11]
	v_mfma_f32_16x16x32_bf16 v[52:55], v[162:165], v[184:187], 0
	v_mfma_f32_16x16x32_bf16 v[52:55], v[166:169], v[188:191], v[52:55]
	v_mfma_f32_16x16x32_bf16 v[48:51], v[170:173], v[184:187], 0
	v_mfma_f32_16x16x32_bf16 v[48:51], v[174:177], v[188:191], v[48:51]
	v_mfma_f32_16x16x32_bf16 v[36:39], v[162:165], v[192:195], 0
	v_mfma_f32_16x16x32_bf16 v[36:39], v[166:169], v[196:199], v[36:39]
	v_mfma_f32_16x16x32_bf16 v[32:35], v[170:173], v[192:195], 0
	v_mfma_f32_16x16x32_bf16 v[32:35], v[174:177], v[196:199], v[32:35]
	v_mfma_f32_16x16x32_bf16 v[20:23], v[162:165], v[200:203], 0
	v_mfma_f32_16x16x32_bf16 v[20:23], v[166:169], v[204:207], v[20:23]
	v_mfma_f32_16x16x32_bf16 v[16:19], v[170:173], v[200:203], 0
	v_mfma_f32_16x16x32_bf16 v[16:19], v[174:177], v[204:207], v[16:19]
	v_mfma_f32_16x16x32_bf16 v[4:7], v[162:165], v[208:211], 0
	v_mfma_f32_16x16x32_bf16 v[4:7], v[166:169], v[212:215], v[4:7]
	v_mfma_f32_16x16x32_bf16 v[0:3], v[170:173], v[208:211], 0
	v_mfma_f32_16x16x32_bf16 v[0:3], v[174:177], v[212:215], v[0:3]
	s_setprio 0
	s_barrier
	s_branch .Lmid_gemm11

.LBB0_1437:
	s_and_b64 vcc, exec, s[8:9]
	s_cbranch_vccnz .Lov_11
	v_mul_f32_e32 v151, 0xbfb8aa3b, v124
	v_exp_f32_e32 v151, v151
	v_mul_f32_e32 v154, 0xbfb8aa3b, v125
	v_exp_f32_e32 v154, v154
	v_lshl_or_b32 v142, s65, 7, v146
	v_add_f32_e32 v151, 1.0, v151
	v_rcp_f32_e32 v151, v151
	v_lshl_add_u32 v150, s44, 8, v144
	v_ashrrev_i32_e32 v143, 31, v142
	v_mov_b64_e32 v[140:141], s[22:23]
	v_mul_f32_e32 v124, v124, v151
	v_mul_f32_e32 v120, v120, v124
	v_add_f32_e32 v124, 1.0, v154
	v_mul_f32_e32 v151, 0xbfb8aa3b, v126
	v_rcp_f32_e32 v124, v124
	v_exp_f32_e32 v151, v151
	v_mul_f32_e32 v154, 0xbfb8aa3b, v127
	v_exp_f32_e32 v154, v154
	v_mul_f32_e32 v124, v125, v124
	v_add_f32_e32 v125, 1.0, v151
	v_rcp_f32_e32 v125, v125
	v_add_f32_e32 v151, 1.0, v154
	v_rcp_f32_e32 v151, v151
	v_mul_f32_e32 v121, v121, v124
	v_mul_f32_e32 v124, v126, v125
	v_mul_f32_e32 v125, 0xbfb8aa3b, v116
	v_exp_f32_e32 v125, v125
	v_mul_f32_e32 v122, v122, v124
	v_mul_f32_e32 v124, v127, v151
	v_mul_f32_e32 v123, v123, v124
	v_cvt_pk_bf16_f32 v120, v120, v121
	v_cvt_pk_bf16_f32 v121, v122, v123
	v_add_f32_e32 v122, 1.0, v125
	v_rcp_f32_e32 v122, v122
	v_mul_f32_e32 v123, 0xbfb8aa3b, v117
	v_exp_f32_e32 v123, v123
	v_mad_i64_i32 v[152:153], s[46:47], v150, s64, v[140:141]
	v_lshlrev_b64 v[142:143], 1, v[142:143]
	v_lshl_add_u64 v[152:153], v[152:153], 0, v[142:143]
	v_mul_f32_e32 v116, v116, v122
	global_store_dwordx2 v[152:153], v[120:121], off
	v_mul_f32_e32 v112, v112, v116
	v_add_f32_e32 v116, 1.0, v123
	v_mul_f32_e32 v120, 0xbfb8aa3b, v118
	v_rcp_f32_e32 v116, v116
	v_exp_f32_e32 v120, v120
	v_mul_f32_e32 v121, 0xbfb8aa3b, v119
	v_exp_f32_e32 v121, v121
	v_mul_f32_e32 v116, v117, v116
	v_add_f32_e32 v117, 1.0, v120
	v_rcp_f32_e32 v117, v117
	v_add_f32_e32 v120, 1.0, v121
	v_rcp_f32_e32 v120, v120
	v_mul_f32_e32 v113, v113, v116
	v_mul_f32_e32 v116, v118, v117
	v_mul_f32_e32 v114, v114, v116
	v_mul_f32_e32 v116, v119, v120
	v_cvt_pk_bf16_f32 v112, v112, v113
	v_mul_f32_e32 v115, v115, v116
	v_cvt_pk_bf16_f32 v113, v114, v115
	global_store_dwordx2 v[152:153], v[112:113], off offset:128
	v_mul_f32_e32 v112, 0xbfb8aa3b, v108
	v_exp_f32_e32 v114, v112
	v_mul_f32_e32 v115, 0xbfb8aa3b, v109
	v_exp_f32_e32 v115, v115
	v_or_b32_e32 v112, 16, v150
	v_add_f32_e32 v114, 1.0, v114
	v_rcp_f32_e32 v114, v114
	v_mad_i64_i32 v[112:113], s[46:47], v112, s64, v[140:141]
	v_lshl_add_u64 v[112:113], v[112:113], 0, v[142:143]
	v_mul_f32_e32 v108, v108, v114
	v_mul_f32_e32 v104, v104, v108
	v_add_f32_e32 v108, 1.0, v115
	v_mul_f32_e32 v114, 0xbfb8aa3b, v110
	v_rcp_f32_e32 v108, v108
	v_exp_f32_e32 v114, v114
	v_mul_f32_e32 v115, 0xbfb8aa3b, v111
	v_exp_f32_e32 v115, v115
	v_mul_f32_e32 v108, v109, v108
	v_add_f32_e32 v109, 1.0, v114
	v_rcp_f32_e32 v109, v109
	v_add_f32_e32 v114, 1.0, v115
	v_rcp_f32_e32 v114, v114
	v_mul_f32_e32 v105, v105, v108
	v_mul_f32_e32 v108, v110, v109
	v_mul_f32_e32 v109, 0xbfb8aa3b, v100
	v_exp_f32_e32 v109, v109
	v_mul_f32_e32 v106, v106, v108
	v_mul_f32_e32 v108, v111, v114
	v_mul_f32_e32 v107, v107, v108
	v_cvt_pk_bf16_f32 v104, v104, v105
	v_cvt_pk_bf16_f32 v105, v106, v107
	v_add_f32_e32 v106, 1.0, v109
	v_rcp_f32_e32 v106, v106
	v_mul_f32_e32 v107, 0xbfb8aa3b, v101
	v_exp_f32_e32 v107, v107
	global_store_dwordx2 v[112:113], v[104:105], off
	v_mul_f32_e32 v100, v100, v106
	v_mul_f32_e32 v96, v96, v100
	v_add_f32_e32 v100, 1.0, v107
	v_mul_f32_e32 v104, 0xbfb8aa3b, v102
	v_rcp_f32_e32 v100, v100
	v_exp_f32_e32 v104, v104
	v_mul_f32_e32 v105, 0xbfb8aa3b, v103
	v_exp_f32_e32 v105, v105
	v_mul_f32_e32 v100, v101, v100
	v_add_f32_e32 v101, 1.0, v104
	v_rcp_f32_e32 v101, v101
	v_add_f32_e32 v104, 1.0, v105
	v_rcp_f32_e32 v104, v104
	v_mul_f32_e32 v97, v97, v100
	v_mul_f32_e32 v100, v102, v101
	v_mul_f32_e32 v98, v98, v100
	v_mul_f32_e32 v100, v103, v104
	v_cvt_pk_bf16_f32 v96, v96, v97
	v_mul_f32_e32 v99, v99, v100
	v_cvt_pk_bf16_f32 v97, v98, v99
	global_store_dwordx2 v[112:113], v[96:97], off offset:128
	v_mul_f32_e32 v96, 0xbfb8aa3b, v92
	v_exp_f32_e32 v98, v96
	v_mul_f32_e32 v99, 0xbfb8aa3b, v93
	v_exp_f32_e32 v99, v99
	v_or_b32_e32 v96, 32, v150
	v_add_f32_e32 v98, 1.0, v98
	v_rcp_f32_e32 v98, v98
	v_mad_i64_i32 v[96:97], s[46:47], v96, s64, v[140:141]
	v_lshl_add_u64 v[96:97], v[96:97], 0, v[142:143]
	v_mul_f32_e32 v92, v92, v98
	v_mul_f32_e32 v88, v88, v92
	v_add_f32_e32 v92, 1.0, v99
	v_mul_f32_e32 v98, 0xbfb8aa3b, v94
	v_rcp_f32_e32 v92, v92
	v_exp_f32_e32 v98, v98
	v_mul_f32_e32 v99, 0xbfb8aa3b, v95
	v_exp_f32_e32 v99, v99
	v_mul_f32_e32 v92, v93, v92
	v_add_f32_e32 v93, 1.0, v98
	v_rcp_f32_e32 v93, v93
	v_add_f32_e32 v98, 1.0, v99
	v_rcp_f32_e32 v98, v98
	v_mul_f32_e32 v89, v89, v92
	v_mul_f32_e32 v92, v94, v93
	v_mul_f32_e32 v93, 0xbfb8aa3b, v84
	v_exp_f32_e32 v93, v93
	v_mul_f32_e32 v90, v90, v92
	v_mul_f32_e32 v92, v95, v98
	v_mul_f32_e32 v91, v91, v92
	v_cvt_pk_bf16_f32 v88, v88, v89
	v_cvt_pk_bf16_f32 v89, v90, v91
	v_add_f32_e32 v90, 1.0, v93
	v_rcp_f32_e32 v90, v90
	v_mul_f32_e32 v91, 0xbfb8aa3b, v85
	v_exp_f32_e32 v91, v91
	global_store_dwordx2 v[96:97], v[88:89], off
	v_mul_f32_e32 v84, v84, v90
	v_mul_f32_e32 v80, v80, v84
	v_add_f32_e32 v84, 1.0, v91
	v_mul_f32_e32 v88, 0xbfb8aa3b, v86
	v_rcp_f32_e32 v84, v84
	v_exp_f32_e32 v88, v88
	v_mul_f32_e32 v89, 0xbfb8aa3b, v87
	v_exp_f32_e32 v89, v89
	v_mul_f32_e32 v84, v85, v84
	v_add_f32_e32 v85, 1.0, v88
	v_rcp_f32_e32 v85, v85
	v_add_f32_e32 v88, 1.0, v89
	v_rcp_f32_e32 v88, v88
	v_mul_f32_e32 v81, v81, v84
	v_mul_f32_e32 v84, v86, v85
	v_mul_f32_e32 v82, v82, v84
	v_mul_f32_e32 v84, v87, v88
	v_cvt_pk_bf16_f32 v80, v80, v81
	v_mul_f32_e32 v83, v83, v84
	v_cvt_pk_bf16_f32 v81, v82, v83
	global_store_dwordx2 v[96:97], v[80:81], off offset:128
	v_mul_f32_e32 v80, 0xbfb8aa3b, v76
	v_exp_f32_e32 v82, v80
	v_mul_f32_e32 v83, 0xbfb8aa3b, v77
	v_exp_f32_e32 v83, v83
	v_or_b32_e32 v80, 48, v150
	v_add_f32_e32 v82, 1.0, v82
	v_rcp_f32_e32 v82, v82
	v_mad_i64_i32 v[80:81], s[46:47], v80, s64, v[140:141]
	v_lshl_add_u64 v[80:81], v[80:81], 0, v[142:143]
	v_mul_f32_e32 v76, v76, v82
	v_mul_f32_e32 v72, v72, v76
	v_add_f32_e32 v76, 1.0, v83
	v_mul_f32_e32 v82, 0xbfb8aa3b, v78
	v_rcp_f32_e32 v76, v76
	v_exp_f32_e32 v82, v82
	v_mul_f32_e32 v83, 0xbfb8aa3b, v79
	v_exp_f32_e32 v83, v83
	v_mul_f32_e32 v76, v77, v76
	v_add_f32_e32 v77, 1.0, v82
	v_rcp_f32_e32 v77, v77
	v_add_f32_e32 v82, 1.0, v83
	v_rcp_f32_e32 v82, v82
	v_mul_f32_e32 v73, v73, v76
	v_mul_f32_e32 v76, v78, v77
	v_mul_f32_e32 v77, 0xbfb8aa3b, v68
	v_exp_f32_e32 v77, v77
	v_mul_f32_e32 v74, v74, v76
	v_mul_f32_e32 v76, v79, v82
	v_mul_f32_e32 v75, v75, v76
	v_cvt_pk_bf16_f32 v72, v72, v73
	v_cvt_pk_bf16_f32 v73, v74, v75
	v_add_f32_e32 v74, 1.0, v77
	v_rcp_f32_e32 v74, v74
	v_mul_f32_e32 v75, 0xbfb8aa3b, v69
	v_exp_f32_e32 v75, v75
	global_store_dwordx2 v[80:81], v[72:73], off
	v_mul_f32_e32 v68, v68, v74
	v_mul_f32_e32 v64, v64, v68
	v_add_f32_e32 v68, 1.0, v75
	v_mul_f32_e32 v72, 0xbfb8aa3b, v70
	v_rcp_f32_e32 v68, v68
	v_exp_f32_e32 v72, v72
	v_mul_f32_e32 v73, 0xbfb8aa3b, v71
	v_exp_f32_e32 v73, v73
	v_mul_f32_e32 v68, v69, v68
	v_add_f32_e32 v69, 1.0, v72
	v_rcp_f32_e32 v69, v69
	v_add_f32_e32 v72, 1.0, v73
	v_rcp_f32_e32 v72, v72
	v_mul_f32_e32 v65, v65, v68
	v_mul_f32_e32 v68, v70, v69
	v_mul_f32_e32 v66, v66, v68
	v_mul_f32_e32 v68, v71, v72
	v_cvt_pk_bf16_f32 v64, v64, v65
	v_mul_f32_e32 v67, v67, v68
	v_cvt_pk_bf16_f32 v65, v66, v67
	global_store_dwordx2 v[80:81], v[64:65], off offset:128
	v_mul_f32_e32 v64, 0xbfb8aa3b, v60
	v_exp_f32_e32 v66, v64
	v_mul_f32_e32 v67, 0xbfb8aa3b, v61
	v_exp_f32_e32 v67, v67
	v_add_u32_e32 v64, 0x80, v150
	v_add_f32_e32 v66, 1.0, v66
	v_rcp_f32_e32 v66, v66
	v_mad_i64_i32 v[64:65], s[46:47], v64, s64, v[140:141]
	v_lshl_add_u64 v[64:65], v[64:65], 0, v[142:143]
	v_mul_f32_e32 v60, v60, v66
	v_mul_f32_e32 v56, v56, v60
	v_add_f32_e32 v60, 1.0, v67
	v_mul_f32_e32 v66, 0xbfb8aa3b, v62
	v_rcp_f32_e32 v60, v60
	v_exp_f32_e32 v66, v66
	v_mul_f32_e32 v67, 0xbfb8aa3b, v63
	v_exp_f32_e32 v67, v67
	v_mul_f32_e32 v60, v61, v60
	v_add_f32_e32 v61, 1.0, v66
	v_rcp_f32_e32 v61, v61
	v_add_f32_e32 v66, 1.0, v67
	v_rcp_f32_e32 v66, v66
	v_mul_f32_e32 v57, v57, v60
	v_mul_f32_e32 v60, v62, v61
	v_mul_f32_e32 v61, 0xbfb8aa3b, v52
	v_exp_f32_e32 v61, v61
	v_mul_f32_e32 v58, v58, v60
	v_mul_f32_e32 v60, v63, v66
	v_mul_f32_e32 v59, v59, v60
	v_cvt_pk_bf16_f32 v56, v56, v57
	v_cvt_pk_bf16_f32 v57, v58, v59
	v_add_f32_e32 v58, 1.0, v61
	v_rcp_f32_e32 v58, v58
	v_mul_f32_e32 v59, 0xbfb8aa3b, v53
	v_exp_f32_e32 v59, v59
	global_store_dwordx2 v[64:65], v[56:57], off
	v_mul_f32_e32 v52, v52, v58
	v_mul_f32_e32 v48, v48, v52
	v_add_f32_e32 v52, 1.0, v59
	v_mul_f32_e32 v56, 0xbfb8aa3b, v54
	v_rcp_f32_e32 v52, v52
	v_exp_f32_e32 v56, v56
	v_mul_f32_e32 v57, 0xbfb8aa3b, v55
	v_exp_f32_e32 v57, v57
	v_mul_f32_e32 v52, v53, v52
	v_add_f32_e32 v53, 1.0, v56
	v_rcp_f32_e32 v53, v53
	v_add_f32_e32 v56, 1.0, v57
	v_rcp_f32_e32 v56, v56
	v_mul_f32_e32 v49, v49, v52
	v_mul_f32_e32 v52, v54, v53
	v_mul_f32_e32 v50, v50, v52
	v_mul_f32_e32 v52, v55, v56
	v_cvt_pk_bf16_f32 v48, v48, v49
	v_mul_f32_e32 v51, v51, v52
	v_cvt_pk_bf16_f32 v49, v50, v51
	global_store_dwordx2 v[64:65], v[48:49], off offset:128
	v_mul_f32_e32 v48, 0xbfb8aa3b, v44
	v_exp_f32_e32 v50, v48
	v_mul_f32_e32 v51, 0xbfb8aa3b, v45
	v_exp_f32_e32 v51, v51
	v_add_u32_e32 v48, 0x90, v150
	v_add_f32_e32 v50, 1.0, v50
	v_rcp_f32_e32 v50, v50
	v_mad_i64_i32 v[48:49], s[46:47], v48, s64, v[140:141]
	v_lshl_add_u64 v[48:49], v[48:49], 0, v[142:143]
	v_mul_f32_e32 v44, v44, v50
	v_mul_f32_e32 v40, v40, v44
	v_add_f32_e32 v44, 1.0, v51
	v_mul_f32_e32 v50, 0xbfb8aa3b, v46
	v_rcp_f32_e32 v44, v44
	v_exp_f32_e32 v50, v50
	v_mul_f32_e32 v51, 0xbfb8aa3b, v47
	v_exp_f32_e32 v51, v51
	v_mul_f32_e32 v44, v45, v44
	v_add_f32_e32 v45, 1.0, v50
	v_rcp_f32_e32 v45, v45
	v_add_f32_e32 v50, 1.0, v51
	v_rcp_f32_e32 v50, v50
	v_mul_f32_e32 v41, v41, v44
	v_mul_f32_e32 v44, v46, v45
	v_mul_f32_e32 v45, 0xbfb8aa3b, v36
	v_exp_f32_e32 v45, v45
	v_mul_f32_e32 v42, v42, v44
	v_mul_f32_e32 v44, v47, v50
	v_mul_f32_e32 v43, v43, v44
	v_cvt_pk_bf16_f32 v40, v40, v41
	v_cvt_pk_bf16_f32 v41, v42, v43
	v_add_f32_e32 v42, 1.0, v45
	v_rcp_f32_e32 v42, v42
	v_mul_f32_e32 v43, 0xbfb8aa3b, v37
	v_exp_f32_e32 v43, v43
	global_store_dwordx2 v[48:49], v[40:41], off
	v_mul_f32_e32 v36, v36, v42
	v_mul_f32_e32 v32, v32, v36
	v_add_f32_e32 v36, 1.0, v43
	v_mul_f32_e32 v40, 0xbfb8aa3b, v38
	v_rcp_f32_e32 v36, v36
	v_exp_f32_e32 v40, v40
	v_mul_f32_e32 v41, 0xbfb8aa3b, v39
	v_exp_f32_e32 v41, v41
	v_mul_f32_e32 v36, v37, v36
	v_add_f32_e32 v37, 1.0, v40
	v_rcp_f32_e32 v37, v37
	v_add_f32_e32 v40, 1.0, v41
	v_rcp_f32_e32 v40, v40
	v_mul_f32_e32 v33, v33, v36
	v_mul_f32_e32 v36, v38, v37
	v_mul_f32_e32 v34, v34, v36
	v_mul_f32_e32 v36, v39, v40
	v_cvt_pk_bf16_f32 v32, v32, v33
	v_mul_f32_e32 v35, v35, v36
	v_cvt_pk_bf16_f32 v33, v34, v35
	global_store_dwordx2 v[48:49], v[32:33], off offset:128
	v_mul_f32_e32 v32, 0xbfb8aa3b, v28
	v_exp_f32_e32 v34, v32
	v_mul_f32_e32 v35, 0xbfb8aa3b, v29
	v_exp_f32_e32 v35, v35
	v_add_u32_e32 v32, 0xa0, v150
	v_add_f32_e32 v34, 1.0, v34
	v_rcp_f32_e32 v34, v34
	v_mad_i64_i32 v[32:33], s[46:47], v32, s64, v[140:141]
	v_lshl_add_u64 v[32:33], v[32:33], 0, v[142:143]
	v_mul_f32_e32 v28, v28, v34
	v_mul_f32_e32 v24, v24, v28
	v_add_f32_e32 v28, 1.0, v35
	v_mul_f32_e32 v34, 0xbfb8aa3b, v30
	v_rcp_f32_e32 v28, v28
	v_exp_f32_e32 v34, v34
	v_mul_f32_e32 v35, 0xbfb8aa3b, v31
	v_exp_f32_e32 v35, v35
	v_mul_f32_e32 v28, v29, v28
	v_add_f32_e32 v29, 1.0, v34
	v_rcp_f32_e32 v29, v29
	v_add_f32_e32 v34, 1.0, v35
	v_rcp_f32_e32 v34, v34
	v_mul_f32_e32 v25, v25, v28
	v_mul_f32_e32 v28, v30, v29
	v_mul_f32_e32 v29, 0xbfb8aa3b, v20
	v_exp_f32_e32 v29, v29
	v_mul_f32_e32 v26, v26, v28
	v_mul_f32_e32 v28, v31, v34
	v_mul_f32_e32 v27, v27, v28
	v_cvt_pk_bf16_f32 v24, v24, v25
	v_cvt_pk_bf16_f32 v25, v26, v27
	v_add_f32_e32 v26, 1.0, v29
	v_rcp_f32_e32 v26, v26
	v_mul_f32_e32 v27, 0xbfb8aa3b, v21
	v_exp_f32_e32 v27, v27
	global_store_dwordx2 v[32:33], v[24:25], off
	v_mul_f32_e32 v20, v20, v26
	v_mul_f32_e32 v16, v16, v20
	v_add_f32_e32 v20, 1.0, v27
	v_mul_f32_e32 v24, 0xbfb8aa3b, v22
	v_rcp_f32_e32 v20, v20
	v_exp_f32_e32 v24, v24
	v_mul_f32_e32 v25, 0xbfb8aa3b, v23
	v_exp_f32_e32 v25, v25
	v_mul_f32_e32 v20, v21, v20
	v_add_f32_e32 v21, 1.0, v24
	v_rcp_f32_e32 v21, v21
	v_add_f32_e32 v24, 1.0, v25
	v_rcp_f32_e32 v24, v24
	v_mul_f32_e32 v17, v17, v20
	v_mul_f32_e32 v20, v22, v21
	v_mul_f32_e32 v18, v18, v20
	v_mul_f32_e32 v20, v23, v24
	v_cvt_pk_bf16_f32 v16, v16, v17
	v_mul_f32_e32 v19, v19, v20
	v_cvt_pk_bf16_f32 v17, v18, v19
	global_store_dwordx2 v[32:33], v[16:17], off offset:128
	v_mul_f32_e32 v16, 0xbfb8aa3b, v12
	v_exp_f32_e32 v18, v16
	v_mul_f32_e32 v19, 0xbfb8aa3b, v13
	v_exp_f32_e32 v19, v19
	v_add_u32_e32 v16, 0xb0, v150
	v_add_f32_e32 v18, 1.0, v18
	v_rcp_f32_e32 v18, v18
	v_mad_i64_i32 v[16:17], s[46:47], v16, s64, v[140:141]
	v_lshl_add_u64 v[16:17], v[16:17], 0, v[142:143]
	v_mul_f32_e32 v12, v12, v18
	v_mul_f32_e32 v8, v8, v12
	v_add_f32_e32 v12, 1.0, v19
	v_mul_f32_e32 v18, 0xbfb8aa3b, v14
	v_rcp_f32_e32 v12, v12
	v_exp_f32_e32 v18, v18
	v_mul_f32_e32 v19, 0xbfb8aa3b, v15
	v_exp_f32_e32 v19, v19
	v_mul_f32_e32 v12, v13, v12
	v_add_f32_e32 v13, 1.0, v18
	v_rcp_f32_e32 v13, v13
	v_add_f32_e32 v18, 1.0, v19
	v_rcp_f32_e32 v18, v18
	v_mul_f32_e32 v9, v9, v12
	v_mul_f32_e32 v12, v14, v13
	v_mul_f32_e32 v13, 0xbfb8aa3b, v4
	v_exp_f32_e32 v13, v13
	v_mul_f32_e32 v10, v10, v12
	v_mul_f32_e32 v12, v15, v18
	v_mul_f32_e32 v11, v11, v12
	v_cvt_pk_bf16_f32 v8, v8, v9
	v_cvt_pk_bf16_f32 v9, v10, v11
	v_add_f32_e32 v10, 1.0, v13
	v_rcp_f32_e32 v10, v10
	v_mul_f32_e32 v11, 0xbfb8aa3b, v5
	v_exp_f32_e32 v11, v11
	global_store_dwordx2 v[16:17], v[8:9], off
	v_mul_f32_e32 v4, v4, v10
	v_mul_f32_e32 v0, v0, v4
	v_add_f32_e32 v4, 1.0, v11
	v_mul_f32_e32 v8, 0xbfb8aa3b, v6
	v_rcp_f32_e32 v4, v4
	v_exp_f32_e32 v8, v8
	v_mul_f32_e32 v9, 0xbfb8aa3b, v7
	v_exp_f32_e32 v9, v9
	v_mul_f32_e32 v4, v5, v4
	v_add_f32_e32 v5, 1.0, v8
	v_rcp_f32_e32 v5, v5
	v_add_f32_e32 v8, 1.0, v9
	v_rcp_f32_e32 v8, v8
	v_mul_f32_e32 v1, v1, v4
	v_mul_f32_e32 v4, v6, v5
	v_mul_f32_e32 v2, v2, v4
	v_mul_f32_e32 v4, v7, v8
	s_andn2_b64 vcc, exec, s[8:9]
	s_mov_b64 s[8:9], -1
	v_mul_f32_e32 v3, v3, v4
	v_cvt_pk_bf16_f32 v0, v0, v1
	v_cvt_pk_bf16_f32 v1, v2, v3
	global_store_dwordx2 v[16:17], v[0:1], off offset:128
	s_cbranch_vccnz .LBB0_1430
	s_andn2_b64 vcc, exec, s[0:1]
	s_cbranch_vccnz .LBB0_1429
	s_barrier
	s_branch .LBB0_1429
